# E33: E27 + per-segment s_setprio toggling removed from all 256x256 GEMM K loops
# speedup vs baseline: 1.0055x; 1.0055x over previous
.LBB0_302:
	ds_read_b128 v[150:153], v146
	ds_read_b128 v[154:157], v146 offset:1024
	ds_read_b128 v[158:161], v146 offset:2048
	ds_read_b128 v[162:165], v146 offset:3072
	s_add_u32 s34, s30, 0xfffc0080
	s_addc_u32 s35, s31, -1
	s_cmp_eq_u32 s71, 12
	s_cselect_b32 s37, s23, s35
	s_cselect_b32 s36, s29, s34
	s_cselect_b32 s35, s21, s70
	s_cselect_b32 s34, s54, s55
	v_lshl_add_u64 v[198:199], s[30:31], 0, v[138:139]
	s_add_i32 m0, s5, 0xc000
	ds_read_b128 v[166:169], v147
	ds_read_b128 v[170:173], v147 offset:1024
	ds_read_b128 v[174:177], v147 offset:2048
	ds_read_b128 v[178:181], v147 offset:3072
	ds_read_b128 v[182:185], v147 offset:4096
	ds_read_b128 v[186:189], v147 offset:5120
	ds_read_b128 v[190:193], v147 offset:6144
	ds_read_b128 v[194:197], v147 offset:7168
	global_load_lds_dwordx4 v[198:199], off
	v_lshl_add_u64 v[198:199], s[30:31], 0, v[140:141]
	s_add_i32 m0, s5, 0xe000
	s_nop 0
	global_load_lds_dwordx4 v[198:199], off
	s_waitcnt lgkmcnt(8)
	s_barrier
	s_waitcnt lgkmcnt(0)
	s_waitcnt lgkmcnt(0)
	v_mfma_f32_16x16x32_bf16 v[126:129], v[150:153], v[166:169], v[126:129]
	v_mfma_f32_16x16x32_bf16 v[122:125], v[158:161], v[166:169], v[122:125]
	v_mfma_f32_16x16x32_bf16 v[110:113], v[150:153], v[174:177], v[110:113]
	v_mfma_f32_16x16x32_bf16 v[106:109], v[158:161], v[174:177], v[106:109]
	v_mfma_f32_16x16x32_bf16 v[94:97], v[150:153], v[182:185], v[94:97]
	v_mfma_f32_16x16x32_bf16 v[90:93], v[158:161], v[182:185], v[90:93]
	v_mfma_f32_16x16x32_bf16 v[78:81], v[150:153], v[190:193], v[78:81]
	v_mfma_f32_16x16x32_bf16 v[74:77], v[158:161], v[190:193], v[74:77]
	v_mfma_f32_16x16x32_bf16 v[126:129], v[154:157], v[170:173], v[126:129]
	v_mfma_f32_16x16x32_bf16 v[122:125], v[162:165], v[170:173], v[122:125]
	v_mfma_f32_16x16x32_bf16 v[110:113], v[154:157], v[178:181], v[110:113]
	v_mfma_f32_16x16x32_bf16 v[106:109], v[162:165], v[178:181], v[106:109]
	v_mfma_f32_16x16x32_bf16 v[94:97], v[154:157], v[186:189], v[94:97]
	v_mfma_f32_16x16x32_bf16 v[90:93], v[162:165], v[186:189], v[90:93]
	v_mfma_f32_16x16x32_bf16 v[78:81], v[154:157], v[194:197], v[78:81]
	v_mfma_f32_16x16x32_bf16 v[74:77], v[162:165], v[194:197], v[74:77]
	s_barrier
	s_add_i32 s72, s49, s40
	v_lshl_add_u64 v[214:215], s[34:35], 0, v[130:131]
	s_mov_b32 m0, s72
	ds_read_b128 v[198:201], v148
	ds_read_b128 v[202:205], v148 offset:1024
	ds_read_b128 v[206:209], v148 offset:2048
	ds_read_b128 v[210:213], v148 offset:3072
	global_load_lds_dwordx4 v[214:215], off
	v_lshl_add_u64 v[216:217], s[34:35], 0, v[132:133]
	s_add_i32 m0, s72, 0x2000
	s_nop 0
	global_load_lds_dwordx4 v[216:217], off
	s_barrier
	s_waitcnt lgkmcnt(0)
	s_waitcnt lgkmcnt(0)
	v_mfma_f32_16x16x32_bf16 v[118:121], v[198:201], v[166:169], v[118:121]
	v_mfma_f32_16x16x32_bf16 v[114:117], v[206:209], v[166:169], v[114:117]
	v_mfma_f32_16x16x32_bf16 v[102:105], v[198:201], v[174:177], v[102:105]
	v_mfma_f32_16x16x32_bf16 v[98:101], v[206:209], v[174:177], v[98:101]
	v_mfma_f32_16x16x32_bf16 v[86:89], v[198:201], v[182:185], v[86:89]
	v_mfma_f32_16x16x32_bf16 v[82:85], v[206:209], v[182:185], v[82:85]
	v_mfma_f32_16x16x32_bf16 v[70:73], v[198:201], v[190:193], v[70:73]
	v_mfma_f32_16x16x32_bf16 v[66:69], v[206:209], v[190:193], v[66:69]
	v_mfma_f32_16x16x32_bf16 v[118:121], v[202:205], v[170:173], v[118:121]
	v_mfma_f32_16x16x32_bf16 v[114:117], v[210:213], v[170:173], v[114:117]
	v_mfma_f32_16x16x32_bf16 v[102:105], v[202:205], v[178:181], v[102:105]
	v_mfma_f32_16x16x32_bf16 v[98:101], v[210:213], v[178:181], v[98:101]
	v_mfma_f32_16x16x32_bf16 v[86:89], v[202:205], v[186:189], v[86:89]
	v_mfma_f32_16x16x32_bf16 v[82:85], v[210:213], v[186:189], v[82:85]
	v_mfma_f32_16x16x32_bf16 v[70:73], v[202:205], v[194:197], v[70:73]
	v_mfma_f32_16x16x32_bf16 v[66:69], v[210:213], v[194:197], v[66:69]
	s_mov_b32 m0, s5
	v_lshl_add_u64 v[218:219], s[36:37], 0, v[130:131]
	s_barrier
	ds_read_b128 v[166:169], v147 offset:16384
	ds_read_b128 v[170:173], v147 offset:17408
	ds_read_b128 v[174:177], v147 offset:18432
	ds_read_b128 v[178:181], v147 offset:19456
	ds_read_b128 v[182:185], v147 offset:20480
	ds_read_b128 v[186:189], v147 offset:21504
	ds_read_b128 v[190:193], v147 offset:22528
	ds_read_b128 v[194:197], v147 offset:23552
	global_load_lds_dwordx4 v[218:219], off
	v_lshl_add_u64 v[220:221], s[36:37], 0, v[132:133]
	s_mov_b32 m0, s41
	s_nop 0
	global_load_lds_dwordx4 v[220:221], off
	s_barrier
	s_waitcnt lgkmcnt(0)
	s_waitcnt lgkmcnt(0)
	v_mfma_f32_16x16x32_bf16 v[62:65], v[150:153], v[166:169], v[62:65]
	v_mfma_f32_16x16x32_bf16 v[58:61], v[158:161], v[166:169], v[58:61]
	v_mfma_f32_16x16x32_bf16 v[46:49], v[150:153], v[174:177], v[46:49]
	v_mfma_f32_16x16x32_bf16 v[42:45], v[158:161], v[174:177], v[42:45]
	v_mfma_f32_16x16x32_bf16 v[30:33], v[150:153], v[182:185], v[30:33]
	v_mfma_f32_16x16x32_bf16 v[26:29], v[158:161], v[182:185], v[26:29]
	v_mfma_f32_16x16x32_bf16 v[14:17], v[150:153], v[190:193], v[14:17]
	v_mfma_f32_16x16x32_bf16 v[10:13], v[158:161], v[190:193], v[10:13]
	v_mfma_f32_16x16x32_bf16 v[62:65], v[154:157], v[170:173], v[62:65]
	v_mfma_f32_16x16x32_bf16 v[58:61], v[162:165], v[170:173], v[58:61]
	v_mfma_f32_16x16x32_bf16 v[46:49], v[154:157], v[178:181], v[46:49]
	v_mfma_f32_16x16x32_bf16 v[42:45], v[162:165], v[178:181], v[42:45]
	v_mfma_f32_16x16x32_bf16 v[30:33], v[154:157], v[186:189], v[30:33]
	v_mfma_f32_16x16x32_bf16 v[26:29], v[162:165], v[186:189], v[26:29]
	v_mfma_f32_16x16x32_bf16 v[14:17], v[154:157], v[194:197], v[14:17]
	v_mfma_f32_16x16x32_bf16 v[10:13], v[162:165], v[194:197], v[10:13]
	s_barrier
	s_add_u32 s72, s34, 0x40000
	s_addc_u32 s73, s35, 0
	s_add_i32 s74, s51, s40
	v_lshl_add_u64 v[150:151], s[72:73], 0, v[130:131]
	s_mov_b32 m0, s74
	s_nop 0
	global_load_lds_dwordx4 v[150:151], off
	v_lshl_add_u64 v[150:151], s[72:73], 0, v[132:133]
	s_add_i32 m0, s74, 0x2000
	s_nop 0
	global_load_lds_dwordx4 v[150:151], off
	s_waitcnt vmcnt(6)
	s_barrier
	v_mfma_f32_16x16x32_bf16 v[54:57], v[198:201], v[166:169], v[54:57]
	v_mfma_f32_16x16x32_bf16 v[50:53], v[206:209], v[166:169], v[50:53]
	v_mfma_f32_16x16x32_bf16 v[38:41], v[198:201], v[174:177], v[38:41]
	v_mfma_f32_16x16x32_bf16 v[34:37], v[206:209], v[174:177], v[34:37]
	v_mfma_f32_16x16x32_bf16 v[22:25], v[198:201], v[182:185], v[22:25]
	v_mfma_f32_16x16x32_bf16 v[18:21], v[206:209], v[182:185], v[18:21]
	v_mfma_f32_16x16x32_bf16 v[6:9], v[198:201], v[190:193], v[6:9]
	v_mfma_f32_16x16x32_bf16 v[2:5], v[206:209], v[190:193], v[2:5]
	v_mfma_f32_16x16x32_bf16 v[54:57], v[202:205], v[170:173], v[54:57]
	v_mfma_f32_16x16x32_bf16 v[50:53], v[210:213], v[170:173], v[50:53]
	v_mfma_f32_16x16x32_bf16 v[38:41], v[202:205], v[178:181], v[38:41]
	v_mfma_f32_16x16x32_bf16 v[34:37], v[210:213], v[178:181], v[34:37]
	v_mfma_f32_16x16x32_bf16 v[22:25], v[202:205], v[186:189], v[22:25]
	v_mfma_f32_16x16x32_bf16 v[18:21], v[210:213], v[186:189], v[18:21]
	v_mfma_f32_16x16x32_bf16 v[6:9], v[202:205], v[194:197], v[6:9]
	v_mfma_f32_16x16x32_bf16 v[2:5], v[210:213], v[194:197], v[2:5]
	s_add_i32 s72, 0, 0x18000
	v_add_u32_e32 v134, s72, v137
	s_barrier
	ds_read_b128 v[150:153], v134
	ds_read_b128 v[154:157], v134 offset:1024
	ds_read_b128 v[158:161], v134 offset:2048
	ds_read_b128 v[162:165], v134 offset:3072
	s_add_u32 s36, s36, 0x40000
	s_addc_u32 s37, s37, 0
	s_mov_b32 m0, s42
	v_lshl_add_u64 v[198:199], s[36:37], 0, v[130:131]
	ds_read_b128 v[166:169], v147 offset:32768
	ds_read_b128 v[170:173], v147 offset:33792
	ds_read_b128 v[174:177], v147 offset:34816
	ds_read_b128 v[178:181], v147 offset:35840
	ds_read_b128 v[182:185], v147 offset:36864
	ds_read_b128 v[186:189], v147 offset:37888
	ds_read_b128 v[190:193], v147 offset:38912
	ds_read_b128 v[194:197], v147 offset:39936
	global_load_lds_dwordx4 v[198:199], off
	v_lshl_add_u64 v[198:199], s[36:37], 0, v[132:133]
	s_mov_b32 m0, s43
	s_nop 0
	global_load_lds_dwordx4 v[198:199], off
	s_waitcnt lgkmcnt(8)
	s_barrier
	s_waitcnt lgkmcnt(0)
	s_waitcnt lgkmcnt(0)
	v_mfma_f32_16x16x32_bf16 v[126:129], v[150:153], v[166:169], v[126:129]
	v_mfma_f32_16x16x32_bf16 v[122:125], v[158:161], v[166:169], v[122:125]
	v_mfma_f32_16x16x32_bf16 v[110:113], v[150:153], v[174:177], v[110:113]
	v_mfma_f32_16x16x32_bf16 v[106:109], v[158:161], v[174:177], v[106:109]
	v_mfma_f32_16x16x32_bf16 v[94:97], v[150:153], v[182:185], v[94:97]
	v_mfma_f32_16x16x32_bf16 v[90:93], v[158:161], v[182:185], v[90:93]
	v_mfma_f32_16x16x32_bf16 v[78:81], v[150:153], v[190:193], v[78:81]
	v_mfma_f32_16x16x32_bf16 v[74:77], v[158:161], v[190:193], v[74:77]
	v_mfma_f32_16x16x32_bf16 v[126:129], v[154:157], v[170:173], v[126:129]
	v_mfma_f32_16x16x32_bf16 v[122:125], v[162:165], v[170:173], v[122:125]
	v_mfma_f32_16x16x32_bf16 v[110:113], v[154:157], v[178:181], v[110:113]
	v_mfma_f32_16x16x32_bf16 v[106:109], v[162:165], v[178:181], v[106:109]
	v_mfma_f32_16x16x32_bf16 v[94:97], v[154:157], v[186:189], v[94:97]
	v_mfma_f32_16x16x32_bf16 v[90:93], v[162:165], v[186:189], v[90:93]
	v_mfma_f32_16x16x32_bf16 v[78:81], v[154:157], v[194:197], v[78:81]
	v_mfma_f32_16x16x32_bf16 v[74:77], v[162:165], v[194:197], v[74:77]
	s_barrier
	s_add_i32 s36, 0, 0x1c000
	s_add_i32 s37, s72, s40
	v_add_u32_e32 v134, s36, v137
	v_lshl_add_u64 v[214:215], v[214:215], 0, s[2:3]
	s_mov_b32 m0, s37
	ds_read_b128 v[198:201], v134
	ds_read_b128 v[202:205], v134 offset:1024
	ds_read_b128 v[206:209], v134 offset:2048
	ds_read_b128 v[210:213], v134 offset:3072
	global_load_lds_dwordx4 v[214:215], off
	v_lshl_add_u64 v[214:215], v[216:217], 0, s[2:3]
	s_add_i32 m0, s37, 0x2000
	s_nop 0
	global_load_lds_dwordx4 v[214:215], off
	s_barrier
	s_waitcnt lgkmcnt(0)
	s_waitcnt lgkmcnt(0)
	v_mfma_f32_16x16x32_bf16 v[118:121], v[198:201], v[166:169], v[118:121]
	v_mfma_f32_16x16x32_bf16 v[114:117], v[206:209], v[166:169], v[114:117]
	v_mfma_f32_16x16x32_bf16 v[102:105], v[198:201], v[174:177], v[102:105]
	v_mfma_f32_16x16x32_bf16 v[98:101], v[206:209], v[174:177], v[98:101]
	v_mfma_f32_16x16x32_bf16 v[86:89], v[198:201], v[182:185], v[86:89]
	v_mfma_f32_16x16x32_bf16 v[82:85], v[206:209], v[182:185], v[82:85]
	v_mfma_f32_16x16x32_bf16 v[70:73], v[198:201], v[190:193], v[70:73]
	v_mfma_f32_16x16x32_bf16 v[66:69], v[206:209], v[190:193], v[66:69]
	v_mfma_f32_16x16x32_bf16 v[118:121], v[202:205], v[170:173], v[118:121]
	v_mfma_f32_16x16x32_bf16 v[114:117], v[210:213], v[170:173], v[114:117]
	v_mfma_f32_16x16x32_bf16 v[102:105], v[202:205], v[178:181], v[102:105]
	v_mfma_f32_16x16x32_bf16 v[98:101], v[210:213], v[178:181], v[98:101]
	v_mfma_f32_16x16x32_bf16 v[86:89], v[202:205], v[186:189], v[86:89]
	v_mfma_f32_16x16x32_bf16 v[82:85], v[210:213], v[186:189], v[82:85]
	v_mfma_f32_16x16x32_bf16 v[70:73], v[202:205], v[194:197], v[70:73]
	v_mfma_f32_16x16x32_bf16 v[66:69], v[210:213], v[194:197], v[66:69]
	s_mov_b32 m0, s45
	v_lshl_add_u64 v[214:215], v[218:219], 0, s[2:3]
	s_barrier
	ds_read_b128 v[166:169], v147 offset:49152
	ds_read_b128 v[170:173], v147 offset:50176
	ds_read_b128 v[174:177], v147 offset:51200
	ds_read_b128 v[178:181], v147 offset:52224
	ds_read_b128 v[182:185], v147 offset:53248
	ds_read_b128 v[186:189], v147 offset:54272
	ds_read_b128 v[190:193], v147 offset:55296
	ds_read_b128 v[194:197], v147 offset:56320
	global_load_lds_dwordx4 v[214:215], off
	v_lshl_add_u64 v[214:215], v[220:221], 0, s[2:3]
	s_mov_b32 m0, s46
	s_nop 0
	global_load_lds_dwordx4 v[214:215], off
	s_barrier
	s_waitcnt lgkmcnt(0)
	s_waitcnt lgkmcnt(0)
	v_mfma_f32_16x16x32_bf16 v[62:65], v[150:153], v[166:169], v[62:65]
	v_mfma_f32_16x16x32_bf16 v[58:61], v[158:161], v[166:169], v[58:61]
	v_mfma_f32_16x16x32_bf16 v[46:49], v[150:153], v[174:177], v[46:49]
	v_mfma_f32_16x16x32_bf16 v[42:45], v[158:161], v[174:177], v[42:45]
	v_mfma_f32_16x16x32_bf16 v[30:33], v[150:153], v[182:185], v[30:33]
	v_mfma_f32_16x16x32_bf16 v[26:29], v[158:161], v[182:185], v[26:29]
	v_mfma_f32_16x16x32_bf16 v[14:17], v[150:153], v[190:193], v[14:17]
	v_mfma_f32_16x16x32_bf16 v[10:13], v[158:161], v[190:193], v[10:13]
	v_mfma_f32_16x16x32_bf16 v[62:65], v[154:157], v[170:173], v[62:65]
	v_mfma_f32_16x16x32_bf16 v[58:61], v[162:165], v[170:173], v[58:61]
	v_mfma_f32_16x16x32_bf16 v[46:49], v[154:157], v[178:181], v[46:49]
	v_mfma_f32_16x16x32_bf16 v[42:45], v[162:165], v[178:181], v[42:45]
	v_mfma_f32_16x16x32_bf16 v[30:33], v[154:157], v[186:189], v[30:33]
	v_mfma_f32_16x16x32_bf16 v[26:29], v[162:165], v[186:189], v[26:29]
	v_mfma_f32_16x16x32_bf16 v[14:17], v[154:157], v[194:197], v[14:17]
	v_mfma_f32_16x16x32_bf16 v[10:13], v[162:165], v[194:197], v[10:13]
	s_barrier
	s_add_u32 s34, s34, 0x40080
	s_addc_u32 s35, s35, 0
	s_add_i32 s36, s36, s40
	v_lshl_add_u64 v[150:151], s[34:35], 0, v[130:131]
	s_mov_b32 m0, s36
	s_nop 0
	global_load_lds_dwordx4 v[150:151], off
	v_lshl_add_u64 v[150:151], s[34:35], 0, v[132:133]
	s_add_i32 m0, s36, 0x2000
	s_nop 0
	global_load_lds_dwordx4 v[150:151], off
	s_waitcnt vmcnt(6)
	s_barrier
	v_mfma_f32_16x16x32_bf16 v[54:57], v[198:201], v[166:169], v[54:57]
	v_mfma_f32_16x16x32_bf16 v[50:53], v[206:209], v[166:169], v[50:53]
	v_mfma_f32_16x16x32_bf16 v[38:41], v[198:201], v[174:177], v[38:41]
	v_mfma_f32_16x16x32_bf16 v[34:37], v[206:209], v[174:177], v[34:37]
	v_mfma_f32_16x16x32_bf16 v[22:25], v[198:201], v[182:185], v[22:25]
	v_mfma_f32_16x16x32_bf16 v[18:21], v[206:209], v[182:185], v[18:21]
	v_mfma_f32_16x16x32_bf16 v[6:9], v[198:201], v[190:193], v[6:9]
	v_mfma_f32_16x16x32_bf16 v[2:5], v[206:209], v[190:193], v[2:5]
	v_mfma_f32_16x16x32_bf16 v[54:57], v[202:205], v[170:173], v[54:57]
	v_mfma_f32_16x16x32_bf16 v[50:53], v[210:213], v[170:173], v[50:53]
	v_mfma_f32_16x16x32_bf16 v[38:41], v[202:205], v[178:181], v[38:41]
	v_mfma_f32_16x16x32_bf16 v[34:37], v[210:213], v[178:181], v[34:37]
	v_mfma_f32_16x16x32_bf16 v[22:25], v[202:205], v[186:189], v[22:25]
	v_mfma_f32_16x16x32_bf16 v[18:21], v[210:213], v[186:189], v[18:21]
	v_mfma_f32_16x16x32_bf16 v[6:9], v[202:205], v[194:197], v[6:9]
	v_mfma_f32_16x16x32_bf16 v[2:5], v[210:213], v[194:197], v[2:5]
	s_add_i32 s71, s71, 2
	s_add_u32 s30, s30, 0x100
	s_addc_u32 s31, s31, 0
	s_add_u32 s55, s55, 0x100
	s_addc_u32 s70, s70, 0
	s_cmp_gt_u32 s71, 13
	s_barrier
	s_cbranch_scc0 .LBB0_302
	s_lshl_b32 s21, s28, 8
	v_add_u32_e32 v149, s21, v1
	v_cmp_gt_i32_e32 vcc, s52, v149
	s_and_saveexec_b64 s[28:29], vcc
	s_cbranch_execz .LBB0_305
	s_load_dwordx16 s[56:71], s[78:79], 0x80
	s_lshl_b32 s23, s4, 8
	v_or_b32_e32 v134, s23, v136
	v_ashrrev_i32_e32 v157, 31, v134
	v_mov_b32_e32 v156, v134
	s_waitcnt lgkmcnt(0)
	v_lshl_add_u64 v[154:155], v[134:135], 2, s[66:67]
	s_load_dwordx16 s[56:71], s[78:79], 0x40
	v_lshl_add_u64 v[150:151], v[154:155], 0, s[6:7]
	v_cmp_gt_i32_e32 vcc, s53, v134
	s_load_dwordx2 s[30:31], s[78:79], 0x1d0
	v_or_b32_e32 v162, 16, v134
	s_waitcnt lgkmcnt(0)
	v_lshl_add_u64 v[158:159], v[156:157], 2, s[60:61]
	v_cndmask_b32_e32 v151, v151, v159, vcc
	v_cndmask_b32_e32 v150, v150, v158, vcc
	global_load_dwordx4 v[150:153], v[150:151], off
	v_mov_b64_e32 v[160:161], s[30:31]
	v_mad_i64_i32 v[160:161], s[30:31], v149, s50, v[160:161]
	v_cndmask_b32_e32 v157, 0, v157, vcc
	v_lshl_add_u64 v[164:165], v[154:155], 0, s[8:9]
	v_lshl_add_u64 v[158:159], v[158:159], 0, 64
	v_lshl_add_u64 v[156:157], v[156:157], 2, v[160:161]
	v_cmp_gt_i32_e32 vcc, s53, v162
	s_waitcnt vmcnt(0)
	v_pk_add_f32 v[128:129], v[128:129], v[152:153]
	v_pk_add_f32 v[126:127], v[126:127], v[150:151]
	v_cndmask_b32_e32 v159, v165, v159, vcc
	v_cndmask_b32_e32 v158, v164, v158, vcc
	global_store_dwordx4 v[156:157], v[126:129], off
	global_load_dwordx4 v[126:129], v[158:159], off
	v_or_b32_e32 v150, s23, v142
	s_ashr_i32 s23, s23, 31
	v_mov_b32_e32 v153, s23
	v_mov_b32_e32 v152, v134
	v_ashrrev_i32_e32 v134, 31, v162
	v_lshl_add_u64 v[152:153], v[152:153], 2, s[60:61]
	v_lshl_add_u64 v[156:157], v[154:155], 0, s[10:11]
	v_lshl_add_u64 v[158:159], v[152:153], 0, s[12:13]
	v_cndmask_b32_e32 v163, 0, v134, vcc
	v_cmp_gt_i32_e32 vcc, s53, v150
	v_lshl_add_u64 v[152:153], v[152:153], 0, s[16:17]
	s_waitcnt vmcnt(0)
	v_pk_add_f32 v[124:125], v[124:125], v[128:129]
	v_cndmask_b32_e32 v157, v157, v159, vcc
	v_cndmask_b32_e32 v156, v156, v158, vcc
	v_lshl_add_u64 v[158:159], v[162:163], 2, v[160:161]
	v_pk_add_f32 v[122:123], v[122:123], v[126:127]
	global_store_dwordx4 v[158:159], v[122:125], off
	global_load_dwordx4 v[122:125], v[156:157], off
	v_ashrrev_i32_e32 v127, 31, v150
	v_or_b32_e32 v126, 16, v150
	v_cndmask_b32_e32 v151, 0, v127, vcc
	v_lshl_add_u64 v[128:129], v[154:155], 0, s[14:15]
	v_cmp_gt_i32_e32 vcc, s53, v126
	v_lshl_add_u64 v[150:151], v[150:151], 2, v[160:161]
	s_waitcnt vmcnt(0)
	v_pk_add_f32 v[120:121], v[120:121], v[124:125]
	v_pk_add_f32 v[118:119], v[118:119], v[122:123]
	v_cndmask_b32_e32 v129, v129, v153, vcc
	v_cndmask_b32_e32 v128, v128, v152, vcc
	global_store_dwordx4 v[150:151], v[118:121], off
	global_load_dwordx4 v[118:121], v[128:129], off
	v_ashrrev_i32_e32 v122, 31, v126
	v_cndmask_b32_e32 v127, 0, v122, vcc
	s_waitcnt vmcnt(0)
	v_pk_add_f32 v[116:117], v[116:117], v[120:121]
	v_pk_add_f32 v[114:115], v[114:115], v[118:119]
	v_lshl_add_u64 v[118:119], v[126:127], 2, v[160:161]
	global_store_dwordx4 v[118:119], v[114:117], off

.LBB0_474:
	ds_read_b128 v[144:147], v167
	ds_read_b128 v[148:151], v167 offset:1024
	ds_read_b128 v[152:155], v167 offset:2048
	ds_read_b128 v[156:159], v167 offset:3072
	s_add_u32 s24, s22, 0xfffc0080
	s_addc_u32 s25, s23, -1
	s_cmp_eq_u32 s51, 12
	s_cselect_b32 s27, s7, s25
	s_cselect_b32 s26, s17, s24
	s_cselect_b32 s25, s9, s50
	s_cselect_b32 s24, s28, s29
	v_lshl_add_u64 v[160:161], s[22:23], 0, v[136:137]
	s_add_i32 m0, s1, 0xc000
	ds_read_b128 v[172:175], v168
	ds_read_b128 v[176:179], v168 offset:1024
	ds_read_b128 v[180:183], v168 offset:2048
	ds_read_b128 v[184:187], v168 offset:3072
	ds_read_b128 v[188:191], v168 offset:4096
	ds_read_b128 v[192:195], v168 offset:5120
	ds_read_b128 v[196:199], v168 offset:6144
	ds_read_b128 v[200:203], v168 offset:7168
	global_load_lds_dwordx4 v[160:161], off
	v_lshl_add_u64 v[160:161], s[22:23], 0, v[138:139]
	s_add_i32 m0, s1, 0xe000
	s_nop 0
	global_load_lds_dwordx4 v[160:161], off
	s_waitcnt lgkmcnt(8)
	s_barrier
	s_waitcnt lgkmcnt(0)
	s_waitcnt lgkmcnt(0)
	v_mfma_f32_16x16x32_bf16 v[126:129], v[144:147], v[172:175], v[126:129]
	v_mfma_f32_16x16x32_bf16 v[122:125], v[152:155], v[172:175], v[122:125]
	v_mfma_f32_16x16x32_bf16 v[110:113], v[144:147], v[180:183], v[110:113]
	v_mfma_f32_16x16x32_bf16 v[106:109], v[152:155], v[180:183], v[106:109]
	v_mfma_f32_16x16x32_bf16 v[94:97], v[144:147], v[188:191], v[94:97]
	v_mfma_f32_16x16x32_bf16 v[90:93], v[152:155], v[188:191], v[90:93]
	v_mfma_f32_16x16x32_bf16 v[78:81], v[144:147], v[196:199], v[78:81]
	v_mfma_f32_16x16x32_bf16 v[74:77], v[152:155], v[196:199], v[74:77]
	v_mfma_f32_16x16x32_bf16 v[126:129], v[148:151], v[176:179], v[126:129]
	v_mfma_f32_16x16x32_bf16 v[122:125], v[156:159], v[176:179], v[122:125]
	v_mfma_f32_16x16x32_bf16 v[110:113], v[148:151], v[184:187], v[110:113]
	v_mfma_f32_16x16x32_bf16 v[106:109], v[156:159], v[184:187], v[106:109]
	v_mfma_f32_16x16x32_bf16 v[94:97], v[148:151], v[192:195], v[94:97]
	v_mfma_f32_16x16x32_bf16 v[90:93], v[156:159], v[192:195], v[90:93]
	v_mfma_f32_16x16x32_bf16 v[78:81], v[148:151], v[200:203], v[78:81]
	v_mfma_f32_16x16x32_bf16 v[74:77], v[156:159], v[200:203], v[74:77]
	s_barrier
	s_add_i32 s52, s45, s34
	v_lshl_add_u64 v[160:161], s[24:25], 0, v[130:131]
	s_mov_b32 m0, s52
	ds_read_b128 v[204:207], v169
	ds_read_b128 v[208:211], v169 offset:1024
	ds_read_b128 v[212:215], v169 offset:2048
	ds_read_b128 v[216:219], v169 offset:3072
	global_load_lds_dwordx4 v[160:161], off
	v_lshl_add_u64 v[220:221], s[24:25], 0, v[132:133]
	s_add_i32 m0, s52, 0x2000
	s_nop 0
	global_load_lds_dwordx4 v[220:221], off
	s_barrier
	s_waitcnt lgkmcnt(0)
	s_waitcnt lgkmcnt(0)
	v_mfma_f32_16x16x32_bf16 v[118:121], v[204:207], v[172:175], v[118:121]
	v_mfma_f32_16x16x32_bf16 v[114:117], v[212:215], v[172:175], v[114:117]
	v_mfma_f32_16x16x32_bf16 v[102:105], v[204:207], v[180:183], v[102:105]
	v_mfma_f32_16x16x32_bf16 v[98:101], v[212:215], v[180:183], v[98:101]
	v_mfma_f32_16x16x32_bf16 v[86:89], v[204:207], v[188:191], v[86:89]
	v_mfma_f32_16x16x32_bf16 v[82:85], v[212:215], v[188:191], v[82:85]
	v_mfma_f32_16x16x32_bf16 v[70:73], v[204:207], v[196:199], v[70:73]
	v_mfma_f32_16x16x32_bf16 v[66:69], v[212:215], v[196:199], v[66:69]
	v_mfma_f32_16x16x32_bf16 v[118:121], v[208:211], v[176:179], v[118:121]
	v_mfma_f32_16x16x32_bf16 v[114:117], v[216:219], v[176:179], v[114:117]
	v_mfma_f32_16x16x32_bf16 v[102:105], v[208:211], v[184:187], v[102:105]
	v_mfma_f32_16x16x32_bf16 v[98:101], v[216:219], v[184:187], v[98:101]
	v_mfma_f32_16x16x32_bf16 v[86:89], v[208:211], v[192:195], v[86:89]
	v_mfma_f32_16x16x32_bf16 v[82:85], v[216:219], v[192:195], v[82:85]
	v_mfma_f32_16x16x32_bf16 v[70:73], v[208:211], v[200:203], v[70:73]
	v_mfma_f32_16x16x32_bf16 v[66:69], v[216:219], v[200:203], v[66:69]
	s_mov_b32 m0, s1
	v_lshl_add_u64 v[222:223], s[26:27], 0, v[130:131]
	s_barrier
	ds_read_b128 v[172:175], v168 offset:16384
	ds_read_b128 v[176:179], v168 offset:17408
	ds_read_b128 v[180:183], v168 offset:18432
	ds_read_b128 v[184:187], v168 offset:19456
	ds_read_b128 v[188:191], v168 offset:20480
	ds_read_b128 v[192:195], v168 offset:21504
	ds_read_b128 v[196:199], v168 offset:22528
	ds_read_b128 v[200:203], v168 offset:23552
	global_load_lds_dwordx4 v[222:223], off
	v_lshl_add_u64 v[224:225], s[26:27], 0, v[132:133]
	s_mov_b32 m0, s35
	s_nop 0
	global_load_lds_dwordx4 v[224:225], off
	s_barrier
	s_waitcnt lgkmcnt(0)
	s_waitcnt lgkmcnt(0)
	v_mfma_f32_16x16x32_bf16 v[62:65], v[144:147], v[172:175], v[62:65]
	v_mfma_f32_16x16x32_bf16 v[58:61], v[152:155], v[172:175], v[58:61]
	v_mfma_f32_16x16x32_bf16 v[46:49], v[144:147], v[180:183], v[46:49]
	v_mfma_f32_16x16x32_bf16 v[42:45], v[152:155], v[180:183], v[42:45]
	v_mfma_f32_16x16x32_bf16 v[30:33], v[144:147], v[188:191], v[30:33]
	v_mfma_f32_16x16x32_bf16 v[26:29], v[152:155], v[188:191], v[26:29]
	v_mfma_f32_16x16x32_bf16 v[14:17], v[144:147], v[196:199], v[14:17]
	v_mfma_f32_16x16x32_bf16 v[10:13], v[152:155], v[196:199], v[10:13]
	v_mfma_f32_16x16x32_bf16 v[62:65], v[148:151], v[176:179], v[62:65]
	v_mfma_f32_16x16x32_bf16 v[58:61], v[156:159], v[176:179], v[58:61]
	v_mfma_f32_16x16x32_bf16 v[46:49], v[148:151], v[184:187], v[46:49]
	v_mfma_f32_16x16x32_bf16 v[42:45], v[156:159], v[184:187], v[42:45]
	v_mfma_f32_16x16x32_bf16 v[30:33], v[148:151], v[192:195], v[30:33]
	v_mfma_f32_16x16x32_bf16 v[26:29], v[156:159], v[192:195], v[26:29]
	v_mfma_f32_16x16x32_bf16 v[14:17], v[148:151], v[200:203], v[14:17]
	v_mfma_f32_16x16x32_bf16 v[10:13], v[156:159], v[200:203], v[10:13]
	s_barrier
	s_add_u32 s52, s24, 0x40000
	s_addc_u32 s53, s25, 0
	s_add_i32 s54, s46, s34
	v_lshl_add_u64 v[144:145], s[52:53], 0, v[130:131]
	s_mov_b32 m0, s54
	s_nop 0
	global_load_lds_dwordx4 v[144:145], off
	v_lshl_add_u64 v[144:145], s[52:53], 0, v[132:133]
	s_add_i32 m0, s54, 0x2000
	s_nop 0
	global_load_lds_dwordx4 v[144:145], off
	s_waitcnt vmcnt(6)
	s_barrier
	v_mfma_f32_16x16x32_bf16 v[54:57], v[204:207], v[172:175], v[54:57]
	v_mfma_f32_16x16x32_bf16 v[50:53], v[212:215], v[172:175], v[50:53]
	v_mfma_f32_16x16x32_bf16 v[38:41], v[204:207], v[180:183], v[38:41]
	v_mfma_f32_16x16x32_bf16 v[34:37], v[212:215], v[180:183], v[34:37]
	v_mfma_f32_16x16x32_bf16 v[22:25], v[204:207], v[188:191], v[22:25]
	v_mfma_f32_16x16x32_bf16 v[18:21], v[212:215], v[188:191], v[18:21]
	v_mfma_f32_16x16x32_bf16 v[6:9], v[204:207], v[196:199], v[6:9]
	v_mfma_f32_16x16x32_bf16 v[2:5], v[212:215], v[196:199], v[2:5]
	v_mfma_f32_16x16x32_bf16 v[54:57], v[208:211], v[176:179], v[54:57]
	v_mfma_f32_16x16x32_bf16 v[50:53], v[216:219], v[176:179], v[50:53]
	v_mfma_f32_16x16x32_bf16 v[38:41], v[208:211], v[184:187], v[38:41]
	v_mfma_f32_16x16x32_bf16 v[34:37], v[216:219], v[184:187], v[34:37]
	v_mfma_f32_16x16x32_bf16 v[22:25], v[208:211], v[192:195], v[22:25]
	v_mfma_f32_16x16x32_bf16 v[18:21], v[216:219], v[192:195], v[18:21]
	v_mfma_f32_16x16x32_bf16 v[6:9], v[208:211], v[200:203], v[6:9]
	v_mfma_f32_16x16x32_bf16 v[2:5], v[216:219], v[200:203], v[2:5]
	s_add_i32 s52, 0, 0x18000
	v_add_u32_e32 v134, s52, v164
	s_barrier
	ds_read_b128 v[144:147], v134
	ds_read_b128 v[148:151], v134 offset:1024
	ds_read_b128 v[152:155], v134 offset:2048
	ds_read_b128 v[156:159], v134 offset:3072
	s_add_u32 s26, s26, 0x40000
	s_addc_u32 s27, s27, 0
	s_mov_b32 m0, s36
	v_lshl_add_u64 v[204:205], s[26:27], 0, v[130:131]
	ds_read_b128 v[172:175], v168 offset:32768
	ds_read_b128 v[176:179], v168 offset:33792
	ds_read_b128 v[180:183], v168 offset:34816
	ds_read_b128 v[184:187], v168 offset:35840
	ds_read_b128 v[188:191], v168 offset:36864
	ds_read_b128 v[192:195], v168 offset:37888
	ds_read_b128 v[196:199], v168 offset:38912
	ds_read_b128 v[200:203], v168 offset:39936
	global_load_lds_dwordx4 v[204:205], off
	v_lshl_add_u64 v[204:205], s[26:27], 0, v[132:133]
	s_mov_b32 m0, s37
	s_nop 0
	global_load_lds_dwordx4 v[204:205], off
	s_waitcnt lgkmcnt(8)
	s_barrier
	s_waitcnt lgkmcnt(0)
	s_waitcnt lgkmcnt(0)
	v_mfma_f32_16x16x32_bf16 v[126:129], v[144:147], v[172:175], v[126:129]
	v_mfma_f32_16x16x32_bf16 v[122:125], v[152:155], v[172:175], v[122:125]
	v_mfma_f32_16x16x32_bf16 v[110:113], v[144:147], v[180:183], v[110:113]
	v_mfma_f32_16x16x32_bf16 v[106:109], v[152:155], v[180:183], v[106:109]
	v_mfma_f32_16x16x32_bf16 v[94:97], v[144:147], v[188:191], v[94:97]
	v_mfma_f32_16x16x32_bf16 v[90:93], v[152:155], v[188:191], v[90:93]
	v_mfma_f32_16x16x32_bf16 v[78:81], v[144:147], v[196:199], v[78:81]
	v_mfma_f32_16x16x32_bf16 v[74:77], v[152:155], v[196:199], v[74:77]
	v_mfma_f32_16x16x32_bf16 v[126:129], v[148:151], v[176:179], v[126:129]
	v_mfma_f32_16x16x32_bf16 v[122:125], v[156:159], v[176:179], v[122:125]
	v_mfma_f32_16x16x32_bf16 v[110:113], v[148:151], v[184:187], v[110:113]
	v_mfma_f32_16x16x32_bf16 v[106:109], v[156:159], v[184:187], v[106:109]
	v_mfma_f32_16x16x32_bf16 v[94:97], v[148:151], v[192:195], v[94:97]
	v_mfma_f32_16x16x32_bf16 v[90:93], v[156:159], v[192:195], v[90:93]
	v_mfma_f32_16x16x32_bf16 v[78:81], v[148:151], v[200:203], v[78:81]
	v_mfma_f32_16x16x32_bf16 v[74:77], v[156:159], v[200:203], v[74:77]
	s_barrier
	s_add_i32 s26, 0, 0x1c000
	s_add_i32 s27, s52, s34
	v_add_u32_e32 v134, s26, v164
	v_lshl_add_u64 v[160:161], v[160:161], 0, s[2:3]
	s_mov_b32 m0, s27
	ds_read_b128 v[204:207], v134
	ds_read_b128 v[208:211], v134 offset:1024
	ds_read_b128 v[212:215], v134 offset:2048
	ds_read_b128 v[216:219], v134 offset:3072
	global_load_lds_dwordx4 v[160:161], off
	v_lshl_add_u64 v[160:161], v[220:221], 0, s[2:3]
	s_add_i32 m0, s27, 0x2000
	s_nop 0
	global_load_lds_dwordx4 v[160:161], off
	s_barrier
	s_waitcnt lgkmcnt(0)
	s_waitcnt lgkmcnt(0)
	v_mfma_f32_16x16x32_bf16 v[118:121], v[204:207], v[172:175], v[118:121]
	v_mfma_f32_16x16x32_bf16 v[114:117], v[212:215], v[172:175], v[114:117]
	v_mfma_f32_16x16x32_bf16 v[102:105], v[204:207], v[180:183], v[102:105]
	v_mfma_f32_16x16x32_bf16 v[98:101], v[212:215], v[180:183], v[98:101]
	v_mfma_f32_16x16x32_bf16 v[86:89], v[204:207], v[188:191], v[86:89]
	v_mfma_f32_16x16x32_bf16 v[82:85], v[212:215], v[188:191], v[82:85]
	v_mfma_f32_16x16x32_bf16 v[70:73], v[204:207], v[196:199], v[70:73]
	v_mfma_f32_16x16x32_bf16 v[66:69], v[212:215], v[196:199], v[66:69]
	v_mfma_f32_16x16x32_bf16 v[118:121], v[208:211], v[176:179], v[118:121]
	v_mfma_f32_16x16x32_bf16 v[114:117], v[216:219], v[176:179], v[114:117]
	v_mfma_f32_16x16x32_bf16 v[102:105], v[208:211], v[184:187], v[102:105]
	v_mfma_f32_16x16x32_bf16 v[98:101], v[216:219], v[184:187], v[98:101]
	v_mfma_f32_16x16x32_bf16 v[86:89], v[208:211], v[192:195], v[86:89]
	v_mfma_f32_16x16x32_bf16 v[82:85], v[216:219], v[192:195], v[82:85]
	v_mfma_f32_16x16x32_bf16 v[70:73], v[208:211], v[200:203], v[70:73]
	v_mfma_f32_16x16x32_bf16 v[66:69], v[216:219], v[200:203], v[66:69]
	s_mov_b32 m0, s41
	v_lshl_add_u64 v[160:161], v[222:223], 0, s[2:3]
	s_barrier
	ds_read_b128 v[172:175], v168 offset:49152
	ds_read_b128 v[176:179], v168 offset:50176
	ds_read_b128 v[180:183], v168 offset:51200
	ds_read_b128 v[184:187], v168 offset:52224
	ds_read_b128 v[188:191], v168 offset:53248
	ds_read_b128 v[192:195], v168 offset:54272
	ds_read_b128 v[196:199], v168 offset:55296
	ds_read_b128 v[200:203], v168 offset:56320
	global_load_lds_dwordx4 v[160:161], off
	v_lshl_add_u64 v[160:161], v[224:225], 0, s[2:3]
	s_mov_b32 m0, s42
	s_nop 0
	global_load_lds_dwordx4 v[160:161], off
	s_barrier
	s_waitcnt lgkmcnt(0)
	s_waitcnt lgkmcnt(0)
	v_mfma_f32_16x16x32_bf16 v[62:65], v[144:147], v[172:175], v[62:65]
	v_mfma_f32_16x16x32_bf16 v[58:61], v[152:155], v[172:175], v[58:61]
	v_mfma_f32_16x16x32_bf16 v[46:49], v[144:147], v[180:183], v[46:49]
	v_mfma_f32_16x16x32_bf16 v[42:45], v[152:155], v[180:183], v[42:45]
	v_mfma_f32_16x16x32_bf16 v[30:33], v[144:147], v[188:191], v[30:33]
	v_mfma_f32_16x16x32_bf16 v[26:29], v[152:155], v[188:191], v[26:29]
	v_mfma_f32_16x16x32_bf16 v[14:17], v[144:147], v[196:199], v[14:17]
	v_mfma_f32_16x16x32_bf16 v[10:13], v[152:155], v[196:199], v[10:13]
	v_mfma_f32_16x16x32_bf16 v[62:65], v[148:151], v[176:179], v[62:65]
	v_mfma_f32_16x16x32_bf16 v[58:61], v[156:159], v[176:179], v[58:61]
	v_mfma_f32_16x16x32_bf16 v[46:49], v[148:151], v[184:187], v[46:49]
	v_mfma_f32_16x16x32_bf16 v[42:45], v[156:159], v[184:187], v[42:45]
	v_mfma_f32_16x16x32_bf16 v[30:33], v[148:151], v[192:195], v[30:33]
	v_mfma_f32_16x16x32_bf16 v[26:29], v[156:159], v[192:195], v[26:29]
	v_mfma_f32_16x16x32_bf16 v[14:17], v[148:151], v[200:203], v[14:17]
	v_mfma_f32_16x16x32_bf16 v[10:13], v[156:159], v[200:203], v[10:13]
	s_barrier
	s_add_u32 s24, s24, 0x40080
	s_addc_u32 s25, s25, 0
	s_add_i32 s26, s26, s34
	v_lshl_add_u64 v[144:145], s[24:25], 0, v[130:131]
	s_mov_b32 m0, s26
	s_nop 0
	global_load_lds_dwordx4 v[144:145], off
	v_lshl_add_u64 v[144:145], s[24:25], 0, v[132:133]
	s_add_i32 m0, s26, 0x2000
	s_nop 0
	global_load_lds_dwordx4 v[144:145], off
	s_waitcnt vmcnt(6)
	s_barrier
	v_mfma_f32_16x16x32_bf16 v[54:57], v[204:207], v[172:175], v[54:57]
	v_mfma_f32_16x16x32_bf16 v[50:53], v[212:215], v[172:175], v[50:53]
	v_mfma_f32_16x16x32_bf16 v[38:41], v[204:207], v[180:183], v[38:41]
	v_mfma_f32_16x16x32_bf16 v[34:37], v[212:215], v[180:183], v[34:37]
	v_mfma_f32_16x16x32_bf16 v[22:25], v[204:207], v[188:191], v[22:25]
	v_mfma_f32_16x16x32_bf16 v[18:21], v[212:215], v[188:191], v[18:21]
	v_mfma_f32_16x16x32_bf16 v[6:9], v[204:207], v[196:199], v[6:9]
	v_mfma_f32_16x16x32_bf16 v[2:5], v[212:215], v[196:199], v[2:5]
	v_mfma_f32_16x16x32_bf16 v[54:57], v[208:211], v[176:179], v[54:57]
	v_mfma_f32_16x16x32_bf16 v[50:53], v[216:219], v[176:179], v[50:53]
	v_mfma_f32_16x16x32_bf16 v[38:41], v[208:211], v[184:187], v[38:41]
	v_mfma_f32_16x16x32_bf16 v[34:37], v[216:219], v[184:187], v[34:37]
	v_mfma_f32_16x16x32_bf16 v[22:25], v[208:211], v[192:195], v[22:25]
	v_mfma_f32_16x16x32_bf16 v[18:21], v[216:219], v[192:195], v[18:21]
	v_mfma_f32_16x16x32_bf16 v[6:9], v[208:211], v[200:203], v[6:9]
	v_mfma_f32_16x16x32_bf16 v[2:5], v[216:219], v[200:203], v[2:5]
	s_add_i32 s51, s51, 2
	s_add_u32 s22, s22, 0x100
	s_addc_u32 s23, s23, 0
	s_add_u32 s29, s29, 0x100
	s_addc_u32 s50, s50, 0
	s_cmp_gt_u32 s51, 13
	s_barrier
	s_cbranch_scc0 .LBB0_474
	s_mov_b64 s[22:23], exec
	s_load_dwordx8 s[52:59], s[78:79], 0x220
	s_load_dwordx4 s[24:27], s[78:79], 0x240
	v_and_b32_e32 v144, 15, v248
	v_bfe_u32 v147, v248, 8, 1
	v_bfe_u32 v145, v248, 6, 2
	v_bfe_u32 v134, v248, 4, 2
	v_lshlrev_b32_e32 v145, 5, v145
	v_lshl_or_b32 v145, v134, 2, v145
	v_lshl_add_u32 v147, v147, 6, v144
	s_lshl_b32 s9, s6, 8
	v_add_u32_e32 v146, s9, v147
	s_cmp_lt_u32 s0, 4
	s_cbranch_scc1 .Lmy_ri_q
	s_cmp_lt_u32 s0, 8
	s_cbranch_scc1 .Lmy_ri_k
	s_cmp_lt_u32 s0, 16
	s_cbranch_scc1 .Lmy_ri_v
	s_branch .Lmy_ri_g

.LBB0_1855:
	v_add_u32_e32 v149, s44, v147
	s_add_u32 s26, s0, s24
	ds_read_b128 v[150:153], v149
	ds_read_b128 v[154:157], v149 offset:1024
	ds_read_b128 v[158:161], v149 offset:2048
	ds_read_b128 v[162:165], v149 offset:3072
	s_addc_u32 s27, s1, s25
	s_add_u32 s26, s26, 0x100
	s_addc_u32 s27, s27, 0
	s_add_u32 s52, s47, s24
	s_addc_u32 s53, s48, s25
	s_cmpk_eq_i32 s24, 0xf00
	s_cselect_b32 s29, s19, s27
	s_cselect_b32 s28, s49, s26
	s_cselect_b32 s27, s15, s53
	s_cselect_b32 s26, s50, s52
	v_lshl_add_u64 v[202:203], v[142:143], 0, s[24:25]
	s_add_i32 m0, s36, 0xc000
	ds_read_b128 v[166:169], v148
	ds_read_b128 v[170:173], v148 offset:1024
	ds_read_b128 v[174:177], v148 offset:2048
	ds_read_b128 v[182:185], v148 offset:3072
	ds_read_b128 v[186:189], v148 offset:4096
	ds_read_b128 v[190:193], v148 offset:5120
	ds_read_b128 v[194:197], v148 offset:6144
	ds_read_b128 v[198:201], v148 offset:7168
	global_load_lds_dwordx4 v[202:203], off
	v_lshl_add_u64 v[202:203], v[144:145], 0, s[24:25]
	s_add_i32 m0, s36, 0xe000
	s_nop 0
	global_load_lds_dwordx4 v[202:203], off
	s_waitcnt lgkmcnt(8)
	s_barrier
	s_waitcnt lgkmcnt(0)
	s_waitcnt lgkmcnt(0)
	v_mfma_f32_16x16x32_bf16 v[126:129], v[150:153], v[166:169], v[126:129]
	v_mfma_f32_16x16x32_bf16 v[122:125], v[158:161], v[166:169], v[122:125]
	v_mfma_f32_16x16x32_bf16 v[110:113], v[150:153], v[174:177], v[110:113]
	v_mfma_f32_16x16x32_bf16 v[106:109], v[158:161], v[174:177], v[106:109]
	v_mfma_f32_16x16x32_bf16 v[94:97], v[150:153], v[186:189], v[94:97]
	v_mfma_f32_16x16x32_bf16 v[90:93], v[158:161], v[186:189], v[90:93]
	v_mfma_f32_16x16x32_bf16 v[78:81], v[150:153], v[194:197], v[78:81]
	v_mfma_f32_16x16x32_bf16 v[74:77], v[158:161], v[194:197], v[74:77]
	v_mfma_f32_16x16x32_bf16 v[126:129], v[154:157], v[170:173], v[126:129]
	v_mfma_f32_16x16x32_bf16 v[122:125], v[162:165], v[170:173], v[122:125]
	v_mfma_f32_16x16x32_bf16 v[110:113], v[154:157], v[182:185], v[110:113]
	v_mfma_f32_16x16x32_bf16 v[106:109], v[162:165], v[182:185], v[106:109]
	v_mfma_f32_16x16x32_bf16 v[94:97], v[154:157], v[190:193], v[94:97]
	v_mfma_f32_16x16x32_bf16 v[90:93], v[162:165], v[190:193], v[90:93]
	v_mfma_f32_16x16x32_bf16 v[78:81], v[154:157], v[198:201], v[78:81]
	v_mfma_f32_16x16x32_bf16 v[74:77], v[162:165], v[198:201], v[74:77]
	s_barrier
	s_add_i32 s52, s44, s35
	v_add_u32_e32 v149, s45, v147
	v_lshl_add_u64 v[218:219], s[26:27], 0, v[130:131]
	s_mov_b32 m0, s52
	ds_read_b128 v[202:205], v149
	ds_read_b128 v[206:209], v149 offset:1024
	ds_read_b128 v[210:213], v149 offset:2048
	ds_read_b128 v[214:217], v149 offset:3072
	global_load_lds_dwordx4 v[218:219], off
	v_lshl_add_u64 v[220:221], s[26:27], 0, v[132:133]
	s_add_i32 m0, s52, 0x2000
	s_nop 0
	global_load_lds_dwordx4 v[220:221], off
	s_barrier
	s_waitcnt lgkmcnt(0)
	s_waitcnt lgkmcnt(0)
	v_mfma_f32_16x16x32_bf16 v[118:121], v[202:205], v[166:169], v[118:121]
	v_mfma_f32_16x16x32_bf16 v[114:117], v[210:213], v[166:169], v[114:117]
	v_mfma_f32_16x16x32_bf16 v[102:105], v[202:205], v[174:177], v[102:105]
	v_mfma_f32_16x16x32_bf16 v[98:101], v[210:213], v[174:177], v[98:101]
	v_mfma_f32_16x16x32_bf16 v[86:89], v[202:205], v[186:189], v[86:89]
	v_mfma_f32_16x16x32_bf16 v[82:85], v[210:213], v[186:189], v[82:85]
	v_mfma_f32_16x16x32_bf16 v[70:73], v[202:205], v[194:197], v[70:73]
	v_mfma_f32_16x16x32_bf16 v[66:69], v[210:213], v[194:197], v[66:69]
	v_mfma_f32_16x16x32_bf16 v[118:121], v[206:209], v[170:173], v[118:121]
	v_mfma_f32_16x16x32_bf16 v[114:117], v[214:217], v[170:173], v[114:117]
	v_mfma_f32_16x16x32_bf16 v[102:105], v[206:209], v[182:185], v[102:105]
	v_mfma_f32_16x16x32_bf16 v[98:101], v[214:217], v[182:185], v[98:101]
	v_mfma_f32_16x16x32_bf16 v[86:89], v[206:209], v[190:193], v[86:89]
	v_mfma_f32_16x16x32_bf16 v[82:85], v[214:217], v[190:193], v[82:85]
	v_mfma_f32_16x16x32_bf16 v[70:73], v[206:209], v[198:201], v[70:73]
	v_mfma_f32_16x16x32_bf16 v[66:69], v[214:217], v[198:201], v[66:69]
	s_mov_b32 m0, s36
	v_lshl_add_u64 v[222:223], s[28:29], 0, v[130:131]
	s_barrier
	ds_read_b128 v[166:169], v148 offset:16384
	ds_read_b128 v[170:173], v148 offset:17408
	ds_read_b128 v[174:177], v148 offset:18432
	ds_read_b128 v[182:185], v148 offset:19456
	ds_read_b128 v[186:189], v148 offset:20480
	ds_read_b128 v[190:193], v148 offset:21504
	ds_read_b128 v[194:197], v148 offset:22528
	ds_read_b128 v[198:201], v148 offset:23552
	global_load_lds_dwordx4 v[222:223], off
	v_lshl_add_u64 v[224:225], s[28:29], 0, v[132:133]
	s_mov_b32 m0, s37
	s_nop 0
	global_load_lds_dwordx4 v[224:225], off
	s_barrier
	s_waitcnt lgkmcnt(0)
	s_waitcnt lgkmcnt(0)
	v_mfma_f32_16x16x32_bf16 v[62:65], v[150:153], v[166:169], v[62:65]
	v_mfma_f32_16x16x32_bf16 v[58:61], v[158:161], v[166:169], v[58:61]
	v_mfma_f32_16x16x32_bf16 v[46:49], v[150:153], v[174:177], v[46:49]
	v_mfma_f32_16x16x32_bf16 v[42:45], v[158:161], v[174:177], v[42:45]
	v_mfma_f32_16x16x32_bf16 v[30:33], v[150:153], v[186:189], v[30:33]
	v_mfma_f32_16x16x32_bf16 v[26:29], v[158:161], v[186:189], v[26:29]
	v_mfma_f32_16x16x32_bf16 v[14:17], v[150:153], v[194:197], v[14:17]
	v_mfma_f32_16x16x32_bf16 v[10:13], v[158:161], v[194:197], v[10:13]
	v_mfma_f32_16x16x32_bf16 v[62:65], v[154:157], v[170:173], v[62:65]
	v_mfma_f32_16x16x32_bf16 v[58:61], v[162:165], v[170:173], v[58:61]
	v_mfma_f32_16x16x32_bf16 v[46:49], v[154:157], v[182:185], v[46:49]
	v_mfma_f32_16x16x32_bf16 v[42:45], v[162:165], v[182:185], v[42:45]
	v_mfma_f32_16x16x32_bf16 v[30:33], v[154:157], v[190:193], v[30:33]
	v_mfma_f32_16x16x32_bf16 v[26:29], v[162:165], v[190:193], v[26:29]
	v_mfma_f32_16x16x32_bf16 v[14:17], v[154:157], v[198:201], v[14:17]
	v_mfma_f32_16x16x32_bf16 v[10:13], v[162:165], v[198:201], v[10:13]
	s_barrier
	s_add_u32 s52, s26, 0x80000
	s_addc_u32 s53, s27, 0
	s_add_i32 s54, s45, s35
	v_lshl_add_u64 v[150:151], s[52:53], 0, v[130:131]
	s_mov_b32 m0, s54
	s_nop 0
	global_load_lds_dwordx4 v[150:151], off
	v_lshl_add_u64 v[150:151], s[52:53], 0, v[132:133]
	s_add_i32 m0, s54, 0x2000
	s_nop 0
	global_load_lds_dwordx4 v[150:151], off
	s_waitcnt vmcnt(6)
	s_barrier
	v_mfma_f32_16x16x32_bf16 v[54:57], v[202:205], v[166:169], v[54:57]
	v_mfma_f32_16x16x32_bf16 v[50:53], v[210:213], v[166:169], v[50:53]
	v_mfma_f32_16x16x32_bf16 v[38:41], v[202:205], v[174:177], v[38:41]
	v_mfma_f32_16x16x32_bf16 v[34:37], v[210:213], v[174:177], v[34:37]
	v_mfma_f32_16x16x32_bf16 v[22:25], v[202:205], v[186:189], v[22:25]
	v_mfma_f32_16x16x32_bf16 v[18:21], v[210:213], v[186:189], v[18:21]
	v_mfma_f32_16x16x32_bf16 v[6:9], v[202:205], v[194:197], v[6:9]
	v_mfma_f32_16x16x32_bf16 v[2:5], v[210:213], v[194:197], v[2:5]
	v_mfma_f32_16x16x32_bf16 v[54:57], v[206:209], v[170:173], v[54:57]
	v_mfma_f32_16x16x32_bf16 v[50:53], v[214:217], v[170:173], v[50:53]
	v_mfma_f32_16x16x32_bf16 v[38:41], v[206:209], v[182:185], v[38:41]
	v_mfma_f32_16x16x32_bf16 v[34:37], v[214:217], v[182:185], v[34:37]
	v_mfma_f32_16x16x32_bf16 v[22:25], v[206:209], v[190:193], v[22:25]
	v_mfma_f32_16x16x32_bf16 v[18:21], v[214:217], v[190:193], v[18:21]
	v_mfma_f32_16x16x32_bf16 v[6:9], v[206:209], v[198:201], v[6:9]
	v_mfma_f32_16x16x32_bf16 v[2:5], v[214:217], v[198:201], v[2:5]
	s_add_i32 s52, 0, 0x18000
	v_add_u32_e32 v149, s52, v147
	s_barrier
	ds_read_b128 v[150:153], v149
	ds_read_b128 v[154:157], v149 offset:1024
	ds_read_b128 v[158:161], v149 offset:2048
	ds_read_b128 v[162:165], v149 offset:3072
	s_add_u32 s28, s28, 0x80000
	s_addc_u32 s29, s29, 0
	s_mov_b32 m0, s38
	v_lshl_add_u64 v[202:203], s[28:29], 0, v[130:131]
	ds_read_b128 v[166:169], v148 offset:32768
	ds_read_b128 v[170:173], v148 offset:33792
	ds_read_b128 v[174:177], v148 offset:34816
	ds_read_b128 v[182:185], v148 offset:35840
	ds_read_b128 v[186:189], v148 offset:36864
	ds_read_b128 v[190:193], v148 offset:37888
	ds_read_b128 v[194:197], v148 offset:38912
	ds_read_b128 v[198:201], v148 offset:39936
	global_load_lds_dwordx4 v[202:203], off
	v_lshl_add_u64 v[202:203], s[28:29], 0, v[132:133]
	s_mov_b32 m0, s39
	s_nop 0
	global_load_lds_dwordx4 v[202:203], off
	s_waitcnt lgkmcnt(8)
	s_barrier
	s_waitcnt lgkmcnt(0)
	s_waitcnt lgkmcnt(0)
	v_mfma_f32_16x16x32_bf16 v[126:129], v[150:153], v[166:169], v[126:129]
	v_mfma_f32_16x16x32_bf16 v[122:125], v[158:161], v[166:169], v[122:125]
	v_mfma_f32_16x16x32_bf16 v[110:113], v[150:153], v[174:177], v[110:113]
	v_mfma_f32_16x16x32_bf16 v[106:109], v[158:161], v[174:177], v[106:109]
	v_mfma_f32_16x16x32_bf16 v[94:97], v[150:153], v[186:189], v[94:97]
	v_mfma_f32_16x16x32_bf16 v[90:93], v[158:161], v[186:189], v[90:93]
	v_mfma_f32_16x16x32_bf16 v[78:81], v[150:153], v[194:197], v[78:81]
	v_mfma_f32_16x16x32_bf16 v[74:77], v[158:161], v[194:197], v[74:77]
	v_mfma_f32_16x16x32_bf16 v[126:129], v[154:157], v[170:173], v[126:129]
	v_mfma_f32_16x16x32_bf16 v[122:125], v[162:165], v[170:173], v[122:125]
	v_mfma_f32_16x16x32_bf16 v[110:113], v[154:157], v[182:185], v[110:113]
	v_mfma_f32_16x16x32_bf16 v[106:109], v[162:165], v[182:185], v[106:109]
	v_mfma_f32_16x16x32_bf16 v[94:97], v[154:157], v[190:193], v[94:97]
	v_mfma_f32_16x16x32_bf16 v[90:93], v[162:165], v[190:193], v[90:93]
	v_mfma_f32_16x16x32_bf16 v[78:81], v[154:157], v[198:201], v[78:81]
	v_mfma_f32_16x16x32_bf16 v[74:77], v[162:165], v[198:201], v[74:77]
	s_barrier
	s_add_i32 s28, 0, 0x1c000
	s_add_i32 s29, s52, s35
	v_add_u32_e32 v149, s28, v147
	v_lshl_add_u64 v[218:219], v[218:219], 0, s[2:3]
	s_mov_b32 m0, s29
	ds_read_b128 v[202:205], v149
	ds_read_b128 v[206:209], v149 offset:1024
	ds_read_b128 v[210:213], v149 offset:2048
	ds_read_b128 v[214:217], v149 offset:3072
	global_load_lds_dwordx4 v[218:219], off
	v_lshl_add_u64 v[218:219], v[220:221], 0, s[2:3]
	s_add_i32 m0, s29, 0x2000
	s_nop 0
	global_load_lds_dwordx4 v[218:219], off
	s_barrier
	s_waitcnt lgkmcnt(0)
	s_waitcnt lgkmcnt(0)
	v_mfma_f32_16x16x32_bf16 v[118:121], v[202:205], v[166:169], v[118:121]
	v_mfma_f32_16x16x32_bf16 v[114:117], v[210:213], v[166:169], v[114:117]
	v_mfma_f32_16x16x32_bf16 v[102:105], v[202:205], v[174:177], v[102:105]
	v_mfma_f32_16x16x32_bf16 v[98:101], v[210:213], v[174:177], v[98:101]
	v_mfma_f32_16x16x32_bf16 v[86:89], v[202:205], v[186:189], v[86:89]
	v_mfma_f32_16x16x32_bf16 v[82:85], v[210:213], v[186:189], v[82:85]
	v_mfma_f32_16x16x32_bf16 v[70:73], v[202:205], v[194:197], v[70:73]
	v_mfma_f32_16x16x32_bf16 v[66:69], v[210:213], v[194:197], v[66:69]
	v_mfma_f32_16x16x32_bf16 v[118:121], v[206:209], v[170:173], v[118:121]
	v_mfma_f32_16x16x32_bf16 v[114:117], v[214:217], v[170:173], v[114:117]
	v_mfma_f32_16x16x32_bf16 v[102:105], v[206:209], v[182:185], v[102:105]
	v_mfma_f32_16x16x32_bf16 v[98:101], v[214:217], v[182:185], v[98:101]
	v_mfma_f32_16x16x32_bf16 v[86:89], v[206:209], v[190:193], v[86:89]
	v_mfma_f32_16x16x32_bf16 v[82:85], v[214:217], v[190:193], v[82:85]
	v_mfma_f32_16x16x32_bf16 v[70:73], v[206:209], v[198:201], v[70:73]
	v_mfma_f32_16x16x32_bf16 v[66:69], v[214:217], v[198:201], v[66:69]
	s_mov_b32 m0, s42
	v_lshl_add_u64 v[218:219], v[222:223], 0, s[2:3]
	s_barrier
	ds_read_b128 v[166:169], v148 offset:49152
	ds_read_b128 v[170:173], v148 offset:50176
	ds_read_b128 v[174:177], v148 offset:51200
	ds_read_b128 v[182:185], v148 offset:52224
	ds_read_b128 v[186:189], v148 offset:53248
	ds_read_b128 v[190:193], v148 offset:54272
	ds_read_b128 v[194:197], v148 offset:55296
	ds_read_b128 v[198:201], v148 offset:56320
	global_load_lds_dwordx4 v[218:219], off
	v_lshl_add_u64 v[218:219], v[224:225], 0, s[2:3]
	s_mov_b32 m0, s43
	s_nop 0
	global_load_lds_dwordx4 v[218:219], off
	s_barrier
	s_waitcnt lgkmcnt(0)
	s_waitcnt lgkmcnt(0)
	v_mfma_f32_16x16x32_bf16 v[62:65], v[150:153], v[166:169], v[62:65]
	v_mfma_f32_16x16x32_bf16 v[58:61], v[158:161], v[166:169], v[58:61]
	v_mfma_f32_16x16x32_bf16 v[46:49], v[150:153], v[174:177], v[46:49]
	v_mfma_f32_16x16x32_bf16 v[42:45], v[158:161], v[174:177], v[42:45]
	v_mfma_f32_16x16x32_bf16 v[30:33], v[150:153], v[186:189], v[30:33]
	v_mfma_f32_16x16x32_bf16 v[26:29], v[158:161], v[186:189], v[26:29]
	v_mfma_f32_16x16x32_bf16 v[14:17], v[150:153], v[194:197], v[14:17]
	v_mfma_f32_16x16x32_bf16 v[10:13], v[158:161], v[194:197], v[10:13]
	v_mfma_f32_16x16x32_bf16 v[62:65], v[154:157], v[170:173], v[62:65]
	v_mfma_f32_16x16x32_bf16 v[58:61], v[162:165], v[170:173], v[58:61]
	v_mfma_f32_16x16x32_bf16 v[46:49], v[154:157], v[182:185], v[46:49]
	v_mfma_f32_16x16x32_bf16 v[42:45], v[162:165], v[182:185], v[42:45]
	v_mfma_f32_16x16x32_bf16 v[30:33], v[154:157], v[190:193], v[30:33]
	v_mfma_f32_16x16x32_bf16 v[26:29], v[162:165], v[190:193], v[26:29]
	v_mfma_f32_16x16x32_bf16 v[14:17], v[154:157], v[198:201], v[14:17]
	v_mfma_f32_16x16x32_bf16 v[10:13], v[162:165], v[198:201], v[10:13]
	s_barrier
	s_add_u32 s26, s26, 0x80080
	s_addc_u32 s27, s27, 0
	s_add_i32 s28, s28, s35
	v_lshl_add_u64 v[150:151], s[26:27], 0, v[130:131]
	s_mov_b32 m0, s28
	s_nop 0
	global_load_lds_dwordx4 v[150:151], off
	v_lshl_add_u64 v[150:151], s[26:27], 0, v[132:133]
	s_add_i32 m0, s28, 0x2000
	s_nop 0
	global_load_lds_dwordx4 v[150:151], off
	s_waitcnt vmcnt(6)
	s_barrier
	v_mfma_f32_16x16x32_bf16 v[54:57], v[202:205], v[166:169], v[54:57]
	v_mfma_f32_16x16x32_bf16 v[50:53], v[210:213], v[166:169], v[50:53]
	v_mfma_f32_16x16x32_bf16 v[38:41], v[202:205], v[174:177], v[38:41]
	v_mfma_f32_16x16x32_bf16 v[34:37], v[210:213], v[174:177], v[34:37]
	v_mfma_f32_16x16x32_bf16 v[22:25], v[202:205], v[186:189], v[22:25]
	v_mfma_f32_16x16x32_bf16 v[18:21], v[210:213], v[186:189], v[18:21]
	v_mfma_f32_16x16x32_bf16 v[6:9], v[202:205], v[194:197], v[6:9]
	v_mfma_f32_16x16x32_bf16 v[2:5], v[210:213], v[194:197], v[2:5]
	v_mfma_f32_16x16x32_bf16 v[54:57], v[206:209], v[170:173], v[54:57]
	v_mfma_f32_16x16x32_bf16 v[50:53], v[214:217], v[170:173], v[50:53]
	v_mfma_f32_16x16x32_bf16 v[38:41], v[206:209], v[182:185], v[38:41]
	v_mfma_f32_16x16x32_bf16 v[34:37], v[214:217], v[182:185], v[34:37]
	v_mfma_f32_16x16x32_bf16 v[22:25], v[206:209], v[190:193], v[22:25]
	v_mfma_f32_16x16x32_bf16 v[18:21], v[214:217], v[190:193], v[18:21]
	v_mfma_f32_16x16x32_bf16 v[6:9], v[206:209], v[198:201], v[6:9]
	v_mfma_f32_16x16x32_bf16 v[2:5], v[214:217], v[198:201], v[2:5]
	s_add_i32 s51, s51, 2
	s_add_u32 s24, s24, 0x100
	s_addc_u32 s25, s25, 0
	s_cmp_gt_u32 s51, 29
	s_barrier
	s_cbranch_scc0 .LBB0_1855
	s_add_u32 s24, s47, 0xffffff00
	s_addc_u32 s25, s48, -1
	s_andn2_b64 vcc, exec, s[6:7]
	s_cbranch_vccnz .LBB0_1846
	v_mov_b32_e32 v2, 0
	s_mov_b32 s12, s14
	s_mov_b32 s8, s18
	s_mov_b64 s[0:1], s[22:23]
	s_mov_b32 s41, s46
	v_mov_b32_e32 v3, v2
	v_mov_b32_e32 v4, v2
	v_mov_b32_e32 v5, v2
	v_mov_b32_e32 v6, v2
	v_mov_b32_e32 v7, v2
	v_mov_b32_e32 v8, v2
	v_mov_b32_e32 v9, v2
	v_mov_b32_e32 v18, v2
	v_mov_b32_e32 v19, v2
	v_mov_b32_e32 v20, v2
	v_mov_b32_e32 v21, v2
	v_mov_b32_e32 v22, v2
	v_mov_b32_e32 v23, v2
	v_mov_b32_e32 v24, v2
	v_mov_b32_e32 v25, v2
	v_mov_b32_e32 v34, v2
	v_mov_b32_e32 v35, v2
	v_mov_b32_e32 v36, v2
	v_mov_b32_e32 v37, v2
	v_mov_b32_e32 v38, v2
	v_mov_b32_e32 v39, v2
	v_mov_b32_e32 v40, v2
	v_mov_b32_e32 v41, v2
	v_mov_b32_e32 v50, v2
	v_mov_b32_e32 v51, v2
	v_mov_b32_e32 v52, v2
	v_mov_b32_e32 v53, v2
	v_mov_b32_e32 v54, v2
	v_mov_b32_e32 v55, v2
	v_mov_b32_e32 v56, v2
	v_mov_b32_e32 v57, v2
	v_mov_b32_e32 v10, v2
	v_mov_b32_e32 v11, v2
	v_mov_b32_e32 v12, v2
	v_mov_b32_e32 v13, v2
	v_mov_b32_e32 v14, v2
	v_mov_b32_e32 v15, v2
	v_mov_b32_e32 v16, v2
	v_mov_b32_e32 v17, v2
	v_mov_b32_e32 v26, v2
	v_mov_b32_e32 v27, v2
	v_mov_b32_e32 v28, v2
	v_mov_b32_e32 v29, v2
	v_mov_b32_e32 v30, v2
	v_mov_b32_e32 v31, v2
	v_mov_b32_e32 v32, v2
	v_mov_b32_e32 v33, v2
	v_mov_b32_e32 v42, v2
	v_mov_b32_e32 v43, v2
	v_mov_b32_e32 v44, v2
	v_mov_b32_e32 v45, v2
	v_mov_b32_e32 v46, v2
	v_mov_b32_e32 v47, v2
	v_mov_b32_e32 v48, v2
	v_mov_b32_e32 v49, v2
	v_mov_b32_e32 v58, v2
	v_mov_b32_e32 v59, v2
	v_mov_b32_e32 v60, v2
	v_mov_b32_e32 v61, v2
	v_mov_b32_e32 v62, v2
	v_mov_b32_e32 v63, v2
	v_mov_b32_e32 v64, v2
	v_mov_b32_e32 v65, v2
	v_mov_b32_e32 v66, v2
	v_mov_b32_e32 v67, v2
	v_mov_b32_e32 v68, v2
	v_mov_b32_e32 v69, v2
	v_mov_b32_e32 v70, v2
	v_mov_b32_e32 v71, v2
	v_mov_b32_e32 v72, v2
	v_mov_b32_e32 v73, v2
	v_mov_b32_e32 v82, v2
	v_mov_b32_e32 v83, v2
	v_mov_b32_e32 v84, v2
	v_mov_b32_e32 v85, v2
	v_mov_b32_e32 v86, v2
	v_mov_b32_e32 v87, v2
	v_mov_b32_e32 v88, v2
	v_mov_b32_e32 v89, v2
	v_mov_b32_e32 v98, v2
	v_mov_b32_e32 v99, v2
	v_mov_b32_e32 v100, v2
	v_mov_b32_e32 v101, v2
	v_mov_b32_e32 v102, v2
	v_mov_b32_e32 v103, v2
	v_mov_b32_e32 v104, v2
	v_mov_b32_e32 v105, v2
	v_mov_b32_e32 v114, v2
	v_mov_b32_e32 v115, v2
	v_mov_b32_e32 v116, v2
	v_mov_b32_e32 v117, v2
	v_mov_b32_e32 v118, v2
	v_mov_b32_e32 v119, v2
	v_mov_b32_e32 v120, v2
	v_mov_b32_e32 v121, v2
	v_mov_b32_e32 v74, v2
	v_mov_b32_e32 v75, v2
	v_mov_b32_e32 v76, v2
	v_mov_b32_e32 v77, v2
	v_mov_b32_e32 v78, v2
	v_mov_b32_e32 v79, v2
	v_mov_b32_e32 v80, v2
	v_mov_b32_e32 v81, v2
	v_mov_b32_e32 v90, v2
	v_mov_b32_e32 v91, v2
	v_mov_b32_e32 v92, v2
	v_mov_b32_e32 v93, v2
	v_mov_b32_e32 v94, v2
	v_mov_b32_e32 v95, v2
	v_mov_b32_e32 v96, v2
	v_mov_b32_e32 v97, v2
	v_mov_b32_e32 v106, v2
	v_mov_b32_e32 v107, v2
	v_mov_b32_e32 v108, v2
	v_mov_b32_e32 v109, v2
	v_mov_b32_e32 v110, v2
	v_mov_b32_e32 v111, v2
	v_mov_b32_e32 v112, v2
	v_mov_b32_e32 v113, v2
	v_mov_b32_e32 v122, v2
	v_mov_b32_e32 v123, v2
	v_mov_b32_e32 v124, v2
	v_mov_b32_e32 v125, v2
	v_mov_b32_e32 v126, v2
	v_mov_b32_e32 v127, v2
	v_mov_b32_e32 v128, v2
	v_mov_b32_e32 v129, v2
	s_andn2_b64 vcc, exec, s[4:5]
	s_cbranch_vccnz .LBB0_1847

.LBB0_2030:
	ds_read_b128 v[130:133], v228
	ds_read_b128 v[134:137], v228 offset:1024
	ds_read_b128 v[138:141], v228 offset:2048
	ds_read_b128 v[142:145], v228 offset:3072
	s_add_u32 s18, s16, 0xfffc0080
	s_addc_u32 s19, s17, -1
	s_cmp_eq_u32 s26, 12
	s_cselect_b32 s21, s13, s19
	s_cselect_b32 s20, s15, s18
	s_cselect_b32 s19, s22, s25
	s_cselect_b32 s18, s23, s24
	v_lshl_add_u64 v[204:205], s[16:17], 0, v[196:197]
	s_add_i32 m0, s85, 0xc000
	ds_read_b128 v[146:149], v229
	ds_read_b128 v[150:153], v229 offset:1024
	ds_read_b128 v[154:157], v229 offset:2048
	ds_read_b128 v[158:161], v229 offset:3072
	ds_read_b128 v[162:165], v229 offset:4096
	ds_read_b128 v[166:169], v229 offset:5120
	ds_read_b128 v[170:173], v229 offset:6144
	ds_read_b128 v[174:177], v229 offset:7168
	global_load_lds_dwordx4 v[204:205], off
	v_lshl_add_u64 v[204:205], s[16:17], 0, v[198:199]
	s_add_i32 m0, s85, 0xe000
	s_nop 0
	global_load_lds_dwordx4 v[204:205], off
	s_waitcnt lgkmcnt(8)
	s_barrier
	s_waitcnt lgkmcnt(0)
	s_waitcnt lgkmcnt(0)
	v_mfma_f32_16x16x32_bf16 v[126:129], v[130:133], v[146:149], v[126:129]
	v_mfma_f32_16x16x32_bf16 v[62:65], v[138:141], v[146:149], v[62:65]
	v_mfma_f32_16x16x32_bf16 v[118:121], v[130:133], v[154:157], v[118:121]
	v_mfma_f32_16x16x32_bf16 v[54:57], v[138:141], v[154:157], v[54:57]
	v_mfma_f32_16x16x32_bf16 v[110:113], v[130:133], v[162:165], v[110:113]
	v_mfma_f32_16x16x32_bf16 v[46:49], v[138:141], v[162:165], v[46:49]
	v_mfma_f32_16x16x32_bf16 v[102:105], v[130:133], v[170:173], v[102:105]
	v_mfma_f32_16x16x32_bf16 v[38:41], v[138:141], v[170:173], v[38:41]
	v_mfma_f32_16x16x32_bf16 v[126:129], v[134:137], v[150:153], v[126:129]
	v_mfma_f32_16x16x32_bf16 v[62:65], v[142:145], v[150:153], v[62:65]
	v_mfma_f32_16x16x32_bf16 v[118:121], v[134:137], v[158:161], v[118:121]
	v_mfma_f32_16x16x32_bf16 v[54:57], v[142:145], v[158:161], v[54:57]
	v_mfma_f32_16x16x32_bf16 v[110:113], v[134:137], v[166:169], v[110:113]
	v_mfma_f32_16x16x32_bf16 v[46:49], v[142:145], v[166:169], v[46:49]
	v_mfma_f32_16x16x32_bf16 v[102:105], v[134:137], v[174:177], v[102:105]
	v_mfma_f32_16x16x32_bf16 v[38:41], v[142:145], v[174:177], v[38:41]
	s_barrier
	s_add_i32 s27, s64, s84
	v_lshl_add_u64 v[220:221], s[18:19], 0, v[184:185]
	s_mov_b32 m0, s27
	ds_read_b128 v[204:207], v230
	ds_read_b128 v[208:211], v230 offset:1024
	ds_read_b128 v[212:215], v230 offset:2048
	ds_read_b128 v[216:219], v230 offset:3072
	global_load_lds_dwordx4 v[220:221], off
	v_lshl_add_u64 v[222:223], s[18:19], 0, v[188:189]
	s_add_i32 m0, s27, 0x2000
	s_nop 0
	global_load_lds_dwordx4 v[222:223], off
	s_barrier
	s_waitcnt lgkmcnt(0)
	s_waitcnt lgkmcnt(0)
	v_mfma_f32_16x16x32_bf16 v[122:125], v[204:207], v[146:149], v[122:125]
	v_mfma_f32_16x16x32_bf16 v[58:61], v[212:215], v[146:149], v[58:61]
	v_mfma_f32_16x16x32_bf16 v[114:117], v[204:207], v[154:157], v[114:117]
	v_mfma_f32_16x16x32_bf16 v[50:53], v[212:215], v[154:157], v[50:53]
	v_mfma_f32_16x16x32_bf16 v[106:109], v[204:207], v[162:165], v[106:109]
	v_mfma_f32_16x16x32_bf16 v[42:45], v[212:215], v[162:165], v[42:45]
	v_mfma_f32_16x16x32_bf16 v[98:101], v[204:207], v[170:173], v[98:101]
	v_mfma_f32_16x16x32_bf16 v[34:37], v[212:215], v[170:173], v[34:37]
	v_mfma_f32_16x16x32_bf16 v[122:125], v[208:211], v[150:153], v[122:125]
	v_mfma_f32_16x16x32_bf16 v[58:61], v[216:219], v[150:153], v[58:61]
	v_mfma_f32_16x16x32_bf16 v[114:117], v[208:211], v[158:161], v[114:117]
	v_mfma_f32_16x16x32_bf16 v[50:53], v[216:219], v[158:161], v[50:53]
	v_mfma_f32_16x16x32_bf16 v[106:109], v[208:211], v[166:169], v[106:109]
	v_mfma_f32_16x16x32_bf16 v[42:45], v[216:219], v[166:169], v[42:45]
	v_mfma_f32_16x16x32_bf16 v[98:101], v[208:211], v[174:177], v[98:101]
	v_mfma_f32_16x16x32_bf16 v[34:37], v[216:219], v[174:177], v[34:37]
	s_mov_b32 m0, s85
	v_lshl_add_u64 v[224:225], s[20:21], 0, v[182:183]
	s_barrier
	ds_read_b128 v[146:149], v229 offset:16384
	ds_read_b128 v[150:153], v229 offset:17408
	ds_read_b128 v[154:157], v229 offset:18432
	ds_read_b128 v[158:161], v229 offset:19456
	ds_read_b128 v[162:165], v229 offset:20480
	ds_read_b128 v[166:169], v229 offset:21504
	ds_read_b128 v[170:173], v229 offset:22528
	ds_read_b128 v[174:177], v229 offset:23552
	global_load_lds_dwordx4 v[224:225], off
	v_lshl_add_u64 v[232:233], s[20:21], 0, v[186:187]
	s_mov_b32 m0, s86
	s_nop 0
	global_load_lds_dwordx4 v[232:233], off
	s_barrier
	s_waitcnt lgkmcnt(0)
	s_waitcnt lgkmcnt(0)
	v_mfma_f32_16x16x32_bf16 v[94:97], v[130:133], v[146:149], v[94:97]
	v_mfma_f32_16x16x32_bf16 v[30:33], v[138:141], v[146:149], v[30:33]
	v_mfma_f32_16x16x32_bf16 v[86:89], v[130:133], v[154:157], v[86:89]
	v_mfma_f32_16x16x32_bf16 v[22:25], v[138:141], v[154:157], v[22:25]
	v_mfma_f32_16x16x32_bf16 v[78:81], v[130:133], v[162:165], v[78:81]
	v_mfma_f32_16x16x32_bf16 v[14:17], v[138:141], v[162:165], v[14:17]
	v_mfma_f32_16x16x32_bf16 v[70:73], v[130:133], v[170:173], v[70:73]
	v_mfma_f32_16x16x32_bf16 v[6:9], v[138:141], v[170:173], v[6:9]
	v_mfma_f32_16x16x32_bf16 v[94:97], v[134:137], v[150:153], v[94:97]
	v_mfma_f32_16x16x32_bf16 v[30:33], v[142:145], v[150:153], v[30:33]
	v_mfma_f32_16x16x32_bf16 v[86:89], v[134:137], v[158:161], v[86:89]
	v_mfma_f32_16x16x32_bf16 v[22:25], v[142:145], v[158:161], v[22:25]
	v_mfma_f32_16x16x32_bf16 v[78:81], v[134:137], v[166:169], v[78:81]
	v_mfma_f32_16x16x32_bf16 v[14:17], v[142:145], v[166:169], v[14:17]
	v_mfma_f32_16x16x32_bf16 v[70:73], v[134:137], v[174:177], v[70:73]
	v_mfma_f32_16x16x32_bf16 v[6:9], v[142:145], v[174:177], v[6:9]
	s_barrier
	s_add_u32 s28, s18, 0x40000
	s_addc_u32 s29, s19, 0
	s_add_i32 s27, s65, s84
	v_lshl_add_u64 v[130:131], s[28:29], 0, v[184:185]
	s_mov_b32 m0, s27
	s_nop 0
	global_load_lds_dwordx4 v[130:131], off
	v_lshl_add_u64 v[130:131], s[28:29], 0, v[188:189]
	s_add_i32 m0, s27, 0x2000
	s_nop 0
	global_load_lds_dwordx4 v[130:131], off
	s_waitcnt vmcnt(6)
	s_barrier
	v_mfma_f32_16x16x32_bf16 v[90:93], v[204:207], v[146:149], v[90:93]
	v_mfma_f32_16x16x32_bf16 v[26:29], v[212:215], v[146:149], v[26:29]
	v_mfma_f32_16x16x32_bf16 v[82:85], v[204:207], v[154:157], v[82:85]
	v_mfma_f32_16x16x32_bf16 v[18:21], v[212:215], v[154:157], v[18:21]
	v_mfma_f32_16x16x32_bf16 v[74:77], v[204:207], v[162:165], v[74:77]
	v_mfma_f32_16x16x32_bf16 v[10:13], v[212:215], v[162:165], v[10:13]
	v_mfma_f32_16x16x32_bf16 v[66:69], v[204:207], v[170:173], v[66:69]
	v_mfma_f32_16x16x32_bf16 v[2:5], v[212:215], v[170:173], v[2:5]
	v_mfma_f32_16x16x32_bf16 v[90:93], v[208:211], v[150:153], v[90:93]
	v_mfma_f32_16x16x32_bf16 v[26:29], v[216:219], v[150:153], v[26:29]
	v_mfma_f32_16x16x32_bf16 v[82:85], v[208:211], v[158:161], v[82:85]
	v_mfma_f32_16x16x32_bf16 v[18:21], v[216:219], v[158:161], v[18:21]
	v_mfma_f32_16x16x32_bf16 v[74:77], v[208:211], v[166:169], v[74:77]
	v_mfma_f32_16x16x32_bf16 v[10:13], v[216:219], v[166:169], v[10:13]
	v_mfma_f32_16x16x32_bf16 v[66:69], v[208:211], v[174:177], v[66:69]
	v_mfma_f32_16x16x32_bf16 v[2:5], v[216:219], v[174:177], v[2:5]
	s_add_i32 s27, 0, 0x18000
	v_add_u32_e32 v142, s27, v1
	s_barrier
	ds_read_b128 v[130:133], v142
	ds_read_b128 v[134:137], v142 offset:1024
	ds_read_b128 v[138:141], v142 offset:2048
	ds_read_b128 v[142:145], v142 offset:3072
	s_add_u32 s20, s20, 0x40000
	s_addc_u32 s21, s21, 0
	s_mov_b32 m0, s87
	v_lshl_add_u64 v[204:205], s[20:21], 0, v[182:183]
	ds_read_b128 v[146:149], v229 offset:32768
	ds_read_b128 v[150:153], v229 offset:33792
	ds_read_b128 v[154:157], v229 offset:34816
	ds_read_b128 v[158:161], v229 offset:35840
	ds_read_b128 v[162:165], v229 offset:36864
	ds_read_b128 v[166:169], v229 offset:37888
	ds_read_b128 v[170:173], v229 offset:38912
	ds_read_b128 v[174:177], v229 offset:39936
	global_load_lds_dwordx4 v[204:205], off
	v_lshl_add_u64 v[204:205], s[20:21], 0, v[186:187]
	s_mov_b32 m0, s94
	s_nop 0
	global_load_lds_dwordx4 v[204:205], off
	s_waitcnt lgkmcnt(8)
	s_barrier
	s_waitcnt lgkmcnt(0)
	s_waitcnt lgkmcnt(0)
	v_mfma_f32_16x16x32_bf16 v[126:129], v[130:133], v[146:149], v[126:129]
	v_mfma_f32_16x16x32_bf16 v[62:65], v[138:141], v[146:149], v[62:65]
	v_mfma_f32_16x16x32_bf16 v[118:121], v[130:133], v[154:157], v[118:121]
	v_mfma_f32_16x16x32_bf16 v[54:57], v[138:141], v[154:157], v[54:57]
	v_mfma_f32_16x16x32_bf16 v[110:113], v[130:133], v[162:165], v[110:113]
	v_mfma_f32_16x16x32_bf16 v[46:49], v[138:141], v[162:165], v[46:49]
	v_mfma_f32_16x16x32_bf16 v[102:105], v[130:133], v[170:173], v[102:105]
	v_mfma_f32_16x16x32_bf16 v[38:41], v[138:141], v[170:173], v[38:41]
	v_mfma_f32_16x16x32_bf16 v[126:129], v[134:137], v[150:153], v[126:129]
	v_mfma_f32_16x16x32_bf16 v[62:65], v[142:145], v[150:153], v[62:65]
	v_mfma_f32_16x16x32_bf16 v[118:121], v[134:137], v[158:161], v[118:121]
	v_mfma_f32_16x16x32_bf16 v[54:57], v[142:145], v[158:161], v[54:57]
	v_mfma_f32_16x16x32_bf16 v[110:113], v[134:137], v[166:169], v[110:113]
	v_mfma_f32_16x16x32_bf16 v[46:49], v[142:145], v[166:169], v[46:49]
	v_mfma_f32_16x16x32_bf16 v[102:105], v[134:137], v[174:177], v[102:105]
	v_mfma_f32_16x16x32_bf16 v[38:41], v[142:145], v[174:177], v[38:41]
	s_barrier
	s_add_i32 s20, 0, 0x1c000
	s_add_i32 s21, s27, s84
	v_add_u32_e32 v190, s20, v1
	v_lshl_add_u64 v[220:221], v[220:221], 0, s[2:3]
	s_mov_b32 m0, s21
	ds_read_b128 v[204:207], v190
	ds_read_b128 v[208:211], v190 offset:1024
	ds_read_b128 v[212:215], v190 offset:2048
	ds_read_b128 v[216:219], v190 offset:3072
	global_load_lds_dwordx4 v[220:221], off
	v_lshl_add_u64 v[220:221], v[222:223], 0, s[2:3]
	s_add_i32 m0, s21, 0x2000
	s_nop 0
	global_load_lds_dwordx4 v[220:221], off
	s_barrier
	s_waitcnt lgkmcnt(0)
	s_waitcnt lgkmcnt(0)
	v_mfma_f32_16x16x32_bf16 v[122:125], v[204:207], v[146:149], v[122:125]
	v_mfma_f32_16x16x32_bf16 v[58:61], v[212:215], v[146:149], v[58:61]
	v_mfma_f32_16x16x32_bf16 v[114:117], v[204:207], v[154:157], v[114:117]
	v_mfma_f32_16x16x32_bf16 v[50:53], v[212:215], v[154:157], v[50:53]
	v_mfma_f32_16x16x32_bf16 v[106:109], v[204:207], v[162:165], v[106:109]
	v_mfma_f32_16x16x32_bf16 v[42:45], v[212:215], v[162:165], v[42:45]
	v_mfma_f32_16x16x32_bf16 v[98:101], v[204:207], v[170:173], v[98:101]
	v_mfma_f32_16x16x32_bf16 v[34:37], v[212:215], v[170:173], v[34:37]
	v_mfma_f32_16x16x32_bf16 v[122:125], v[208:211], v[150:153], v[122:125]
	v_mfma_f32_16x16x32_bf16 v[58:61], v[216:219], v[150:153], v[58:61]
	v_mfma_f32_16x16x32_bf16 v[114:117], v[208:211], v[158:161], v[114:117]
	v_mfma_f32_16x16x32_bf16 v[50:53], v[216:219], v[158:161], v[50:53]
	v_mfma_f32_16x16x32_bf16 v[106:109], v[208:211], v[166:169], v[106:109]
	v_mfma_f32_16x16x32_bf16 v[42:45], v[216:219], v[166:169], v[42:45]
	v_mfma_f32_16x16x32_bf16 v[98:101], v[208:211], v[174:177], v[98:101]
	v_mfma_f32_16x16x32_bf16 v[34:37], v[216:219], v[174:177], v[34:37]
	s_mov_b32 m0, s97
	v_lshl_add_u64 v[220:221], v[224:225], 0, s[2:3]
	s_barrier
	ds_read_b128 v[146:149], v229 offset:49152
	ds_read_b128 v[150:153], v229 offset:50176
	ds_read_b128 v[154:157], v229 offset:51200
	ds_read_b128 v[158:161], v229 offset:52224
	ds_read_b128 v[162:165], v229 offset:53248
	ds_read_b128 v[166:169], v229 offset:54272
	ds_read_b128 v[170:173], v229 offset:55296
	ds_read_b128 v[174:177], v229 offset:56320
	global_load_lds_dwordx4 v[220:221], off
	v_lshl_add_u64 v[220:221], v[232:233], 0, s[2:3]
	s_mov_b32 m0, s96
	s_nop 0
	global_load_lds_dwordx4 v[220:221], off
	s_barrier
	s_waitcnt lgkmcnt(0)
	s_waitcnt lgkmcnt(0)
	v_mfma_f32_16x16x32_bf16 v[94:97], v[130:133], v[146:149], v[94:97]
	v_mfma_f32_16x16x32_bf16 v[30:33], v[138:141], v[146:149], v[30:33]
	v_mfma_f32_16x16x32_bf16 v[86:89], v[130:133], v[154:157], v[86:89]
	v_mfma_f32_16x16x32_bf16 v[22:25], v[138:141], v[154:157], v[22:25]
	v_mfma_f32_16x16x32_bf16 v[78:81], v[130:133], v[162:165], v[78:81]
	v_mfma_f32_16x16x32_bf16 v[14:17], v[138:141], v[162:165], v[14:17]
	v_mfma_f32_16x16x32_bf16 v[70:73], v[130:133], v[170:173], v[70:73]
	v_mfma_f32_16x16x32_bf16 v[6:9], v[138:141], v[170:173], v[6:9]
	v_mfma_f32_16x16x32_bf16 v[94:97], v[134:137], v[150:153], v[94:97]
	v_mfma_f32_16x16x32_bf16 v[30:33], v[142:145], v[150:153], v[30:33]
	v_mfma_f32_16x16x32_bf16 v[86:89], v[134:137], v[158:161], v[86:89]
	v_mfma_f32_16x16x32_bf16 v[22:25], v[142:145], v[158:161], v[22:25]
	v_mfma_f32_16x16x32_bf16 v[78:81], v[134:137], v[166:169], v[78:81]
	v_mfma_f32_16x16x32_bf16 v[14:17], v[142:145], v[166:169], v[14:17]
	v_mfma_f32_16x16x32_bf16 v[70:73], v[134:137], v[174:177], v[70:73]
	v_mfma_f32_16x16x32_bf16 v[6:9], v[142:145], v[174:177], v[6:9]
	s_barrier
	s_add_u32 s18, s18, 0x40080
	s_addc_u32 s19, s19, 0
	s_add_i32 s20, s20, s84
	v_lshl_add_u64 v[130:131], s[18:19], 0, v[184:185]
	s_mov_b32 m0, s20
	s_nop 0
	global_load_lds_dwordx4 v[130:131], off
	v_lshl_add_u64 v[130:131], s[18:19], 0, v[188:189]
	s_add_i32 m0, s20, 0x2000
	s_nop 0
	global_load_lds_dwordx4 v[130:131], off
	s_waitcnt vmcnt(6)
	s_barrier
	v_mfma_f32_16x16x32_bf16 v[90:93], v[204:207], v[146:149], v[90:93]
	v_mfma_f32_16x16x32_bf16 v[26:29], v[212:215], v[146:149], v[26:29]
	v_mfma_f32_16x16x32_bf16 v[82:85], v[204:207], v[154:157], v[82:85]
	v_mfma_f32_16x16x32_bf16 v[18:21], v[212:215], v[154:157], v[18:21]
	v_mfma_f32_16x16x32_bf16 v[74:77], v[204:207], v[162:165], v[74:77]
	v_mfma_f32_16x16x32_bf16 v[10:13], v[212:215], v[162:165], v[10:13]
	v_mfma_f32_16x16x32_bf16 v[66:69], v[204:207], v[170:173], v[66:69]
	v_mfma_f32_16x16x32_bf16 v[2:5], v[212:215], v[170:173], v[2:5]
	v_mfma_f32_16x16x32_bf16 v[90:93], v[208:211], v[150:153], v[90:93]
	v_mfma_f32_16x16x32_bf16 v[26:29], v[216:219], v[150:153], v[26:29]
	v_mfma_f32_16x16x32_bf16 v[82:85], v[208:211], v[158:161], v[82:85]
	v_mfma_f32_16x16x32_bf16 v[18:21], v[216:219], v[158:161], v[18:21]
	v_mfma_f32_16x16x32_bf16 v[74:77], v[208:211], v[166:169], v[74:77]
	v_mfma_f32_16x16x32_bf16 v[10:13], v[216:219], v[166:169], v[10:13]
	v_mfma_f32_16x16x32_bf16 v[66:69], v[208:211], v[174:177], v[66:69]
	v_mfma_f32_16x16x32_bf16 v[2:5], v[216:219], v[174:177], v[2:5]
	s_add_i32 s26, s26, 2
	s_add_u32 s16, s16, 0x100
	s_addc_u32 s17, s17, 0
	s_add_u32 s24, s24, 0x100
	s_addc_u32 s25, s25, 0
	s_cmp_gt_u32 s26, 13
	s_barrier
	s_cbranch_scc0 .LBB0_2030
	s_mov_b64 s[16:17], -1
	s_cmp_lt_i32 s12, 64
	v_lshl_or_b32 v204, s14, 7, v181
	s_cbranch_scc0 .Lmy_ffnA_sample
	s_load_dwordx2 s[36:37], s[78:79], 0x268
	s_load_dwordx2 s[38:39], s[78:79], 0x2a0
	s_load_dwordx4 s[40:43], s[78:79], 0x70
	s_load_dwordx2 s[44:45], s[78:79], 0x120
	v_and_b32_e32 v204, 15, v248
	v_bfe_u32 v205, v248, 8, 1
	v_bfe_u32 v206, v248, 6, 2
	v_bfe_u32 v207, v248, 4, 2
	v_lshlrev_b32_e32 v206, 5, v206
	v_lshl_or_b32 v206, v207, 3, v206
	s_lshl_b32 s13, s14, 7
	v_add_u32_e32 v206, s13, v206
	s_lshl_b32 s13, s12, 8
	v_lshl_add_u32 v207, v205, 6, v204
	v_add_u32_e32 v207, s13, v207
	v_mul_u32_u24_e32 v231, 0x1600, v207
	v_lshl_add_u32 v231, v206, 1, v231
	v_lshlrev_b32_e32 v232, 2, v206
	s_lshl_b32 s13, s12, 4
	v_lshl_add_u32 v233, v205, 2, s13
	v_add_u32_e32 v208, -12, v204
	v_cmp_gt_u32_e32 vcc, 2, v204
	s_nop 1
	v_cndmask_b32_e32 v208, v208, v204, vcc
	v_add_u32_e32 v233, v233, v208
	v_mul_u32_u24_e32 v233, 0x2c00, v233
	v_lshl_add_u32 v233, v206, 1, v233
	s_lshr_b32 s13, s12, 3
	s_lshl_b32 s13, s13, 1
	s_add_i32 s13, s13, -14
	v_add_u32_e32 v234, s13, v204
	v_mul_u32_u24_e32 v234, 0x5800, v234
	v_lshl_add_u32 v234, v206, 2, v234
	v_readfirstlane_b32 s4, v248
	s_lshr_b32 s4, s4, 8
	s_and_b32 s5, s12, 7
	s_cmp_eq_u32 s5, 7
	s_cselect_b32 s5, 1, 0
	s_and_b32 s5, s5, s4
	s_waitcnt lgkmcnt(0)
	global_load_dwordx4 v[130:133], v232, s[40:41]
	v_add_u32_e32 v213, 0x5800, v232
	global_load_dwordx4 v[134:137], v213, s[40:41]
	v_add_u32_e32 v214, 0xb000, v232
	global_load_dwordx4 v[138:141], v214, s[40:41]
	global_load_dwordx4 v[142:145], v232, s[42:43]
	v_add_u32_e32 v215, 0x2c00, v232
	global_load_dwordx4 v[146:149], v215, s[40:41]
	v_add_u32_e32 v216, 0x8400, v232
	global_load_dwordx4 v[150:153], v216, s[40:41]
	v_add_u32_e32 v217, 0xdc00, v232
	global_load_dwordx4 v[154:157], v217, s[40:41]
	v_add_u32_e32 v218, 0x2c00, v232
	global_load_dwordx4 v[158:161], v218, s[42:43]
	s_mov_b32 exec_lo, 0x30003
	s_mov_b32 exec_hi, 0x30003
	v_cvt_pk_bf16_f32 v162, v126, v127
	v_cvt_pk_bf16_f32 v163, v128, v129
	global_store_dwordx2 v233, v[162:163], s[38:39]
	v_cvt_pk_bf16_f32 v164, v122, v123
	v_cvt_pk_bf16_f32 v165, v124, v125
	v_add_u32_e32 v220, 0x1600, v233
	global_store_dwordx2 v220, v[164:165], s[38:39]
	v_cvt_pk_bf16_f32 v166, v94, v95
	v_cvt_pk_bf16_f32 v167, v96, v97
	v_add_u32_e32 v221, 0x16000, v233
	global_store_dwordx2 v221, v[166:167], s[38:39]
	v_cvt_pk_bf16_f32 v168, v90, v91
	v_cvt_pk_bf16_f32 v169, v92, v93
	v_add_u32_e32 v222, 0x17600, v233
	global_store_dwordx2 v222, v[168:169], s[38:39]
	v_cvt_pk_bf16_f32 v170, v62, v63
	v_cvt_pk_bf16_f32 v171, v64, v65
	v_add_u32_e32 v223, 0x8, v233
	global_store_dwordx2 v223, v[170:171], s[38:39]
	v_cvt_pk_bf16_f32 v172, v58, v59
	v_cvt_pk_bf16_f32 v173, v60, v61
	v_add_u32_e32 v224, 0x1608, v233
	global_store_dwordx2 v224, v[172:173], s[38:39]
	v_cvt_pk_bf16_f32 v174, v30, v31
	v_cvt_pk_bf16_f32 v175, v32, v33
	v_add_u32_e32 v225, 0x16008, v233
	global_store_dwordx2 v225, v[174:175], s[38:39]
	v_cvt_pk_bf16_f32 v176, v26, v27
	v_cvt_pk_bf16_f32 v177, v28, v29
	v_add_u32_e32 v226, 0x17608, v233
	global_store_dwordx2 v226, v[176:177], s[38:39]
	s_mov_b32 exec_lo, 0xc000c000
	s_mov_b32 exec_hi, 0xc000c000
	v_cvt_pk_bf16_f32 v162, v102, v103
	v_cvt_pk_bf16_f32 v163, v104, v105
	global_store_dwordx2 v233, v[162:163], s[38:39]
	v_cvt_pk_bf16_f32 v164, v98, v99
	v_cvt_pk_bf16_f32 v165, v100, v101
	v_add_u32_e32 v220, 0x1600, v233
	global_store_dwordx2 v220, v[164:165], s[38:39]
	v_cvt_pk_bf16_f32 v166, v70, v71
	v_cvt_pk_bf16_f32 v167, v72, v73
	v_add_u32_e32 v221, 0x16000, v233
	global_store_dwordx2 v221, v[166:167], s[38:39]
	v_cvt_pk_bf16_f32 v168, v66, v67
	v_cvt_pk_bf16_f32 v169, v68, v69
	v_add_u32_e32 v222, 0x17600, v233
	global_store_dwordx2 v222, v[168:169], s[38:39]
	v_cvt_pk_bf16_f32 v170, v38, v39
	v_cvt_pk_bf16_f32 v171, v40, v41
	v_add_u32_e32 v223, 0x8, v233
	global_store_dwordx2 v223, v[170:171], s[38:39]
	v_cvt_pk_bf16_f32 v172, v34, v35
	v_cvt_pk_bf16_f32 v173, v36, v37
	v_add_u32_e32 v224, 0x1608, v233
	global_store_dwordx2 v224, v[172:173], s[38:39]
	v_cvt_pk_bf16_f32 v174, v6, v7
	v_cvt_pk_bf16_f32 v175, v8, v9
	v_add_u32_e32 v225, 0x16008, v233
	global_store_dwordx2 v225, v[174:175], s[38:39]
	v_cvt_pk_bf16_f32 v176, v2, v3
	v_cvt_pk_bf16_f32 v177, v4, v5
	v_add_u32_e32 v226, 0x17608, v233
	global_store_dwordx2 v226, v[176:177], s[38:39]
	s_cmp_lg_u32 s5, 0
	s_cbranch_scc0 .Lmy_ffnA_ncp
	global_store_dwordx4 v234, v[70:73], s[44:45]
	v_add_u32_e32 v220, 0x2c00, v234
	global_store_dwordx4 v220, v[66:69], s[44:45]
	v_add_u32_e32 v221, 0x10, v234
	global_store_dwordx4 v221, v[6:9], s[44:45]
	v_add_u32_e32 v222, 0x2c10, v234
	global_store_dwordx4 v222, v[2:5], s[44:45]

.LBB0_2514:
	v_add_u32_e32 v149, s40, v147
	s_add_u32 s20, s8, s18
	ds_read_b128 v[150:153], v149
	ds_read_b128 v[154:157], v149 offset:1024
	ds_read_b128 v[158:161], v149 offset:2048
	ds_read_b128 v[162:165], v149 offset:3072
	s_addc_u32 s21, s9, s19
	s_add_u32 s20, s20, 0x100
	s_addc_u32 s21, s21, 0
	s_add_u32 s48, s45, s18
	s_addc_u32 s49, s46, s19
	s_cmpk_eq_i32 s18, 0x1500
	s_cselect_b32 s23, s17, s21
	s_cselect_b32 s22, s16, s20
	s_cselect_b32 s21, s1, s49
	s_cselect_b32 s20, s0, s48
	v_lshl_add_u64 v[202:203], v[142:143], 0, s[18:19]
	s_add_i32 m0, s31, 0xc000
	ds_read_b128 v[166:169], v148
	ds_read_b128 v[170:173], v148 offset:1024
	ds_read_b128 v[174:177], v148 offset:2048
	ds_read_b128 v[182:185], v148 offset:3072
	ds_read_b128 v[186:189], v148 offset:4096
	ds_read_b128 v[190:193], v148 offset:5120
	ds_read_b128 v[194:197], v148 offset:6144
	ds_read_b128 v[198:201], v148 offset:7168
	global_load_lds_dwordx4 v[202:203], off
	v_lshl_add_u64 v[202:203], v[144:145], 0, s[18:19]
	s_add_i32 m0, s31, 0xe000
	s_nop 0
	global_load_lds_dwordx4 v[202:203], off
	s_waitcnt lgkmcnt(8)
	s_barrier
	s_waitcnt lgkmcnt(0)
	s_waitcnt lgkmcnt(0)
	v_mfma_f32_16x16x32_bf16 v[126:129], v[150:153], v[166:169], v[126:129]
	v_mfma_f32_16x16x32_bf16 v[122:125], v[158:161], v[166:169], v[122:125]
	v_mfma_f32_16x16x32_bf16 v[110:113], v[150:153], v[174:177], v[110:113]
	v_mfma_f32_16x16x32_bf16 v[106:109], v[158:161], v[174:177], v[106:109]
	v_mfma_f32_16x16x32_bf16 v[94:97], v[150:153], v[186:189], v[94:97]
	v_mfma_f32_16x16x32_bf16 v[90:93], v[158:161], v[186:189], v[90:93]
	v_mfma_f32_16x16x32_bf16 v[78:81], v[150:153], v[194:197], v[78:81]
	v_mfma_f32_16x16x32_bf16 v[74:77], v[158:161], v[194:197], v[74:77]
	v_mfma_f32_16x16x32_bf16 v[126:129], v[154:157], v[170:173], v[126:129]
	v_mfma_f32_16x16x32_bf16 v[122:125], v[162:165], v[170:173], v[122:125]
	v_mfma_f32_16x16x32_bf16 v[110:113], v[154:157], v[182:185], v[110:113]
	v_mfma_f32_16x16x32_bf16 v[106:109], v[162:165], v[182:185], v[106:109]
	v_mfma_f32_16x16x32_bf16 v[94:97], v[154:157], v[190:193], v[94:97]
	v_mfma_f32_16x16x32_bf16 v[90:93], v[162:165], v[190:193], v[90:93]
	v_mfma_f32_16x16x32_bf16 v[78:81], v[154:157], v[198:201], v[78:81]
	v_mfma_f32_16x16x32_bf16 v[74:77], v[162:165], v[198:201], v[74:77]
	s_barrier
	s_add_i32 s48, s40, s30
	v_add_u32_e32 v149, s41, v147
	v_lshl_add_u64 v[218:219], s[20:21], 0, v[130:131]
	s_mov_b32 m0, s48
	ds_read_b128 v[202:205], v149
	ds_read_b128 v[206:209], v149 offset:1024
	ds_read_b128 v[210:213], v149 offset:2048
	ds_read_b128 v[214:217], v149 offset:3072
	global_load_lds_dwordx4 v[218:219], off
	v_lshl_add_u64 v[220:221], s[20:21], 0, v[132:133]
	s_add_i32 m0, s48, 0x2000
	s_nop 0
	global_load_lds_dwordx4 v[220:221], off
	s_barrier
	s_waitcnt lgkmcnt(0)
	s_waitcnt lgkmcnt(0)
	v_mfma_f32_16x16x32_bf16 v[118:121], v[202:205], v[166:169], v[118:121]
	v_mfma_f32_16x16x32_bf16 v[114:117], v[210:213], v[166:169], v[114:117]
	v_mfma_f32_16x16x32_bf16 v[102:105], v[202:205], v[174:177], v[102:105]
	v_mfma_f32_16x16x32_bf16 v[98:101], v[210:213], v[174:177], v[98:101]
	v_mfma_f32_16x16x32_bf16 v[86:89], v[202:205], v[186:189], v[86:89]
	v_mfma_f32_16x16x32_bf16 v[82:85], v[210:213], v[186:189], v[82:85]
	v_mfma_f32_16x16x32_bf16 v[70:73], v[202:205], v[194:197], v[70:73]
	v_mfma_f32_16x16x32_bf16 v[66:69], v[210:213], v[194:197], v[66:69]
	v_mfma_f32_16x16x32_bf16 v[118:121], v[206:209], v[170:173], v[118:121]
	v_mfma_f32_16x16x32_bf16 v[114:117], v[214:217], v[170:173], v[114:117]
	v_mfma_f32_16x16x32_bf16 v[102:105], v[206:209], v[182:185], v[102:105]
	v_mfma_f32_16x16x32_bf16 v[98:101], v[214:217], v[182:185], v[98:101]
	v_mfma_f32_16x16x32_bf16 v[86:89], v[206:209], v[190:193], v[86:89]
	v_mfma_f32_16x16x32_bf16 v[82:85], v[214:217], v[190:193], v[82:85]
	v_mfma_f32_16x16x32_bf16 v[70:73], v[206:209], v[198:201], v[70:73]
	v_mfma_f32_16x16x32_bf16 v[66:69], v[214:217], v[198:201], v[66:69]
	s_mov_b32 m0, s31
	v_lshl_add_u64 v[222:223], s[22:23], 0, v[130:131]
	s_barrier
	ds_read_b128 v[166:169], v148 offset:16384
	ds_read_b128 v[170:173], v148 offset:17408
	ds_read_b128 v[174:177], v148 offset:18432
	ds_read_b128 v[182:185], v148 offset:19456
	ds_read_b128 v[186:189], v148 offset:20480
	ds_read_b128 v[190:193], v148 offset:21504
	ds_read_b128 v[194:197], v148 offset:22528
	ds_read_b128 v[198:201], v148 offset:23552
	global_load_lds_dwordx4 v[222:223], off
	v_lshl_add_u64 v[224:225], s[22:23], 0, v[132:133]
	s_mov_b32 m0, s33
	s_nop 0
	global_load_lds_dwordx4 v[224:225], off
	s_barrier
	s_waitcnt lgkmcnt(0)
	s_waitcnt lgkmcnt(0)
	v_mfma_f32_16x16x32_bf16 v[62:65], v[150:153], v[166:169], v[62:65]
	v_mfma_f32_16x16x32_bf16 v[58:61], v[158:161], v[166:169], v[58:61]
	v_mfma_f32_16x16x32_bf16 v[46:49], v[150:153], v[174:177], v[46:49]
	v_mfma_f32_16x16x32_bf16 v[42:45], v[158:161], v[174:177], v[42:45]
	v_mfma_f32_16x16x32_bf16 v[30:33], v[150:153], v[186:189], v[30:33]
	v_mfma_f32_16x16x32_bf16 v[26:29], v[158:161], v[186:189], v[26:29]
	v_mfma_f32_16x16x32_bf16 v[14:17], v[150:153], v[194:197], v[14:17]
	v_mfma_f32_16x16x32_bf16 v[10:13], v[158:161], v[194:197], v[10:13]
	v_mfma_f32_16x16x32_bf16 v[62:65], v[154:157], v[170:173], v[62:65]
	v_mfma_f32_16x16x32_bf16 v[58:61], v[162:165], v[170:173], v[58:61]
	v_mfma_f32_16x16x32_bf16 v[46:49], v[154:157], v[182:185], v[46:49]
	v_mfma_f32_16x16x32_bf16 v[42:45], v[162:165], v[182:185], v[42:45]
	v_mfma_f32_16x16x32_bf16 v[30:33], v[154:157], v[190:193], v[30:33]
	v_mfma_f32_16x16x32_bf16 v[26:29], v[162:165], v[190:193], v[26:29]
	v_mfma_f32_16x16x32_bf16 v[14:17], v[154:157], v[198:201], v[14:17]
	v_mfma_f32_16x16x32_bf16 v[10:13], v[162:165], v[198:201], v[10:13]
	s_barrier
	s_add_u32 s48, s20, 0xb0000
	s_addc_u32 s49, s21, 0
	s_add_i32 s50, s41, s30
	v_lshl_add_u64 v[150:151], s[48:49], 0, v[130:131]
	s_mov_b32 m0, s50
	s_nop 0
	global_load_lds_dwordx4 v[150:151], off
	v_lshl_add_u64 v[150:151], s[48:49], 0, v[132:133]
	s_add_i32 m0, s50, 0x2000
	s_nop 0
	global_load_lds_dwordx4 v[150:151], off
	s_waitcnt vmcnt(6)
	s_barrier
	v_mfma_f32_16x16x32_bf16 v[54:57], v[202:205], v[166:169], v[54:57]
	v_mfma_f32_16x16x32_bf16 v[50:53], v[210:213], v[166:169], v[50:53]
	v_mfma_f32_16x16x32_bf16 v[38:41], v[202:205], v[174:177], v[38:41]
	v_mfma_f32_16x16x32_bf16 v[34:37], v[210:213], v[174:177], v[34:37]
	v_mfma_f32_16x16x32_bf16 v[22:25], v[202:205], v[186:189], v[22:25]
	v_mfma_f32_16x16x32_bf16 v[18:21], v[210:213], v[186:189], v[18:21]
	v_mfma_f32_16x16x32_bf16 v[6:9], v[202:205], v[194:197], v[6:9]
	v_mfma_f32_16x16x32_bf16 v[2:5], v[210:213], v[194:197], v[2:5]
	v_mfma_f32_16x16x32_bf16 v[54:57], v[206:209], v[170:173], v[54:57]
	v_mfma_f32_16x16x32_bf16 v[50:53], v[214:217], v[170:173], v[50:53]
	v_mfma_f32_16x16x32_bf16 v[38:41], v[206:209], v[182:185], v[38:41]
	v_mfma_f32_16x16x32_bf16 v[34:37], v[214:217], v[182:185], v[34:37]
	v_mfma_f32_16x16x32_bf16 v[22:25], v[206:209], v[190:193], v[22:25]
	v_mfma_f32_16x16x32_bf16 v[18:21], v[214:217], v[190:193], v[18:21]
	v_mfma_f32_16x16x32_bf16 v[6:9], v[206:209], v[198:201], v[6:9]
	v_mfma_f32_16x16x32_bf16 v[2:5], v[214:217], v[198:201], v[2:5]
	s_add_i32 s48, 0, 0x18000
	v_add_u32_e32 v149, s48, v147
	s_barrier
	ds_read_b128 v[150:153], v149
	ds_read_b128 v[154:157], v149 offset:1024
	ds_read_b128 v[158:161], v149 offset:2048
	ds_read_b128 v[162:165], v149 offset:3072
	s_add_u32 s22, s22, 0xb0000
	s_addc_u32 s23, s23, 0
	s_mov_b32 m0, s34
	v_lshl_add_u64 v[202:203], s[22:23], 0, v[130:131]
	ds_read_b128 v[166:169], v148 offset:32768
	ds_read_b128 v[170:173], v148 offset:33792
	ds_read_b128 v[174:177], v148 offset:34816
	ds_read_b128 v[182:185], v148 offset:35840
	ds_read_b128 v[186:189], v148 offset:36864
	ds_read_b128 v[190:193], v148 offset:37888
	ds_read_b128 v[194:197], v148 offset:38912
	ds_read_b128 v[198:201], v148 offset:39936
	global_load_lds_dwordx4 v[202:203], off
	v_lshl_add_u64 v[202:203], s[22:23], 0, v[132:133]
	s_mov_b32 m0, s35
	s_nop 0
	global_load_lds_dwordx4 v[202:203], off
	s_waitcnt lgkmcnt(8)
	s_barrier
	s_waitcnt lgkmcnt(0)
	s_waitcnt lgkmcnt(0)
	v_mfma_f32_16x16x32_bf16 v[126:129], v[150:153], v[166:169], v[126:129]
	v_mfma_f32_16x16x32_bf16 v[122:125], v[158:161], v[166:169], v[122:125]
	v_mfma_f32_16x16x32_bf16 v[110:113], v[150:153], v[174:177], v[110:113]
	v_mfma_f32_16x16x32_bf16 v[106:109], v[158:161], v[174:177], v[106:109]
	v_mfma_f32_16x16x32_bf16 v[94:97], v[150:153], v[186:189], v[94:97]
	v_mfma_f32_16x16x32_bf16 v[90:93], v[158:161], v[186:189], v[90:93]
	v_mfma_f32_16x16x32_bf16 v[78:81], v[150:153], v[194:197], v[78:81]
	v_mfma_f32_16x16x32_bf16 v[74:77], v[158:161], v[194:197], v[74:77]
	v_mfma_f32_16x16x32_bf16 v[126:129], v[154:157], v[170:173], v[126:129]
	v_mfma_f32_16x16x32_bf16 v[122:125], v[162:165], v[170:173], v[122:125]
	v_mfma_f32_16x16x32_bf16 v[110:113], v[154:157], v[182:185], v[110:113]
	v_mfma_f32_16x16x32_bf16 v[106:109], v[162:165], v[182:185], v[106:109]
	v_mfma_f32_16x16x32_bf16 v[94:97], v[154:157], v[190:193], v[94:97]
	v_mfma_f32_16x16x32_bf16 v[90:93], v[162:165], v[190:193], v[90:93]
	v_mfma_f32_16x16x32_bf16 v[78:81], v[154:157], v[198:201], v[78:81]
	v_mfma_f32_16x16x32_bf16 v[74:77], v[162:165], v[198:201], v[74:77]
	s_barrier
	s_add_i32 s22, 0, 0x1c000
	s_add_i32 s23, s48, s30
	v_add_u32_e32 v149, s22, v147
	v_lshl_add_u64 v[218:219], v[218:219], 0, s[10:11]
	s_mov_b32 m0, s23
	ds_read_b128 v[202:205], v149
	ds_read_b128 v[206:209], v149 offset:1024
	ds_read_b128 v[210:213], v149 offset:2048
	ds_read_b128 v[214:217], v149 offset:3072
	global_load_lds_dwordx4 v[218:219], off
	v_lshl_add_u64 v[218:219], v[220:221], 0, s[10:11]
	s_add_i32 m0, s23, 0x2000
	s_nop 0
	global_load_lds_dwordx4 v[218:219], off
	s_barrier
	s_waitcnt lgkmcnt(0)
	s_waitcnt lgkmcnt(0)
	v_mfma_f32_16x16x32_bf16 v[118:121], v[202:205], v[166:169], v[118:121]
	v_mfma_f32_16x16x32_bf16 v[114:117], v[210:213], v[166:169], v[114:117]
	v_mfma_f32_16x16x32_bf16 v[102:105], v[202:205], v[174:177], v[102:105]
	v_mfma_f32_16x16x32_bf16 v[98:101], v[210:213], v[174:177], v[98:101]
	v_mfma_f32_16x16x32_bf16 v[86:89], v[202:205], v[186:189], v[86:89]
	v_mfma_f32_16x16x32_bf16 v[82:85], v[210:213], v[186:189], v[82:85]
	v_mfma_f32_16x16x32_bf16 v[70:73], v[202:205], v[194:197], v[70:73]
	v_mfma_f32_16x16x32_bf16 v[66:69], v[210:213], v[194:197], v[66:69]
	v_mfma_f32_16x16x32_bf16 v[118:121], v[206:209], v[170:173], v[118:121]
	v_mfma_f32_16x16x32_bf16 v[114:117], v[214:217], v[170:173], v[114:117]
	v_mfma_f32_16x16x32_bf16 v[102:105], v[206:209], v[182:185], v[102:105]
	v_mfma_f32_16x16x32_bf16 v[98:101], v[214:217], v[182:185], v[98:101]
	v_mfma_f32_16x16x32_bf16 v[86:89], v[206:209], v[190:193], v[86:89]
	v_mfma_f32_16x16x32_bf16 v[82:85], v[214:217], v[190:193], v[82:85]
	v_mfma_f32_16x16x32_bf16 v[70:73], v[206:209], v[198:201], v[70:73]
	v_mfma_f32_16x16x32_bf16 v[66:69], v[214:217], v[198:201], v[66:69]
	s_mov_b32 m0, s38
	v_lshl_add_u64 v[218:219], v[222:223], 0, s[10:11]
	s_barrier
	ds_read_b128 v[166:169], v148 offset:49152
	ds_read_b128 v[170:173], v148 offset:50176
	ds_read_b128 v[174:177], v148 offset:51200
	ds_read_b128 v[182:185], v148 offset:52224
	ds_read_b128 v[186:189], v148 offset:53248
	ds_read_b128 v[190:193], v148 offset:54272
	ds_read_b128 v[194:197], v148 offset:55296
	ds_read_b128 v[198:201], v148 offset:56320
	global_load_lds_dwordx4 v[218:219], off
	v_lshl_add_u64 v[218:219], v[224:225], 0, s[10:11]
	s_mov_b32 m0, s39
	s_nop 0
	global_load_lds_dwordx4 v[218:219], off
	s_barrier
	s_waitcnt lgkmcnt(0)
	s_waitcnt lgkmcnt(0)
	v_mfma_f32_16x16x32_bf16 v[62:65], v[150:153], v[166:169], v[62:65]
	v_mfma_f32_16x16x32_bf16 v[58:61], v[158:161], v[166:169], v[58:61]
	v_mfma_f32_16x16x32_bf16 v[46:49], v[150:153], v[174:177], v[46:49]
	v_mfma_f32_16x16x32_bf16 v[42:45], v[158:161], v[174:177], v[42:45]
	v_mfma_f32_16x16x32_bf16 v[30:33], v[150:153], v[186:189], v[30:33]
	v_mfma_f32_16x16x32_bf16 v[26:29], v[158:161], v[186:189], v[26:29]
	v_mfma_f32_16x16x32_bf16 v[14:17], v[150:153], v[194:197], v[14:17]
	v_mfma_f32_16x16x32_bf16 v[10:13], v[158:161], v[194:197], v[10:13]
	v_mfma_f32_16x16x32_bf16 v[62:65], v[154:157], v[170:173], v[62:65]
	v_mfma_f32_16x16x32_bf16 v[58:61], v[162:165], v[170:173], v[58:61]
	v_mfma_f32_16x16x32_bf16 v[46:49], v[154:157], v[182:185], v[46:49]
	v_mfma_f32_16x16x32_bf16 v[42:45], v[162:165], v[182:185], v[42:45]
	v_mfma_f32_16x16x32_bf16 v[30:33], v[154:157], v[190:193], v[30:33]
	v_mfma_f32_16x16x32_bf16 v[26:29], v[162:165], v[190:193], v[26:29]
	v_mfma_f32_16x16x32_bf16 v[14:17], v[154:157], v[198:201], v[14:17]
	v_mfma_f32_16x16x32_bf16 v[10:13], v[162:165], v[198:201], v[10:13]
	s_barrier
	s_add_u32 s20, s20, 0xb0080
	s_addc_u32 s21, s21, 0
	s_add_i32 s22, s22, s30
	v_lshl_add_u64 v[150:151], s[20:21], 0, v[130:131]
	s_mov_b32 m0, s22
	s_nop 0
	global_load_lds_dwordx4 v[150:151], off
	v_lshl_add_u64 v[150:151], s[20:21], 0, v[132:133]
	s_add_i32 m0, s22, 0x2000
	s_nop 0
	global_load_lds_dwordx4 v[150:151], off
	s_waitcnt vmcnt(6)
	s_barrier
	v_mfma_f32_16x16x32_bf16 v[54:57], v[202:205], v[166:169], v[54:57]
	v_mfma_f32_16x16x32_bf16 v[50:53], v[210:213], v[166:169], v[50:53]
	v_mfma_f32_16x16x32_bf16 v[38:41], v[202:205], v[174:177], v[38:41]
	v_mfma_f32_16x16x32_bf16 v[34:37], v[210:213], v[174:177], v[34:37]
	v_mfma_f32_16x16x32_bf16 v[22:25], v[202:205], v[186:189], v[22:25]
	v_mfma_f32_16x16x32_bf16 v[18:21], v[210:213], v[186:189], v[18:21]
	v_mfma_f32_16x16x32_bf16 v[6:9], v[202:205], v[194:197], v[6:9]
	v_mfma_f32_16x16x32_bf16 v[2:5], v[210:213], v[194:197], v[2:5]
	v_mfma_f32_16x16x32_bf16 v[54:57], v[206:209], v[170:173], v[54:57]
	v_mfma_f32_16x16x32_bf16 v[50:53], v[214:217], v[170:173], v[50:53]
	v_mfma_f32_16x16x32_bf16 v[38:41], v[206:209], v[182:185], v[38:41]
	v_mfma_f32_16x16x32_bf16 v[34:37], v[214:217], v[182:185], v[34:37]
	v_mfma_f32_16x16x32_bf16 v[22:25], v[206:209], v[190:193], v[22:25]
	v_mfma_f32_16x16x32_bf16 v[18:21], v[214:217], v[190:193], v[18:21]
	v_mfma_f32_16x16x32_bf16 v[6:9], v[206:209], v[198:201], v[6:9]
	v_mfma_f32_16x16x32_bf16 v[2:5], v[214:217], v[198:201], v[2:5]
	s_add_i32 s47, s47, 2
	s_add_u32 s18, s18, 0x100
	s_addc_u32 s19, s19, 0
	s_cmp_gt_u32 s47, 41
	s_barrier
	s_cbranch_scc0 .LBB0_2514
	s_add_u32 s18, s45, 0xffffff00
	s_addc_u32 s19, s46, -1
	s_and_b64 vcc, exec, s[6:7]
	s_cbranch_vccnz .LBB0_2501
	v_mov_b32_e32 v2, 0
	s_mov_b32 s2, s42
	s_mov_b32 s26, s43
	s_mov_b64 s[8:9], s[16:17]
	s_mov_b32 s37, s44
	v_mov_b32_e32 v3, v2
	v_mov_b32_e32 v4, v2
	v_mov_b32_e32 v5, v2
	v_mov_b32_e32 v6, v2
	v_mov_b32_e32 v7, v2
	v_mov_b32_e32 v8, v2
	v_mov_b32_e32 v9, v2
	v_mov_b32_e32 v18, v2
	v_mov_b32_e32 v19, v2
	v_mov_b32_e32 v20, v2
	v_mov_b32_e32 v21, v2
	v_mov_b32_e32 v22, v2
	v_mov_b32_e32 v23, v2
	v_mov_b32_e32 v24, v2
	v_mov_b32_e32 v25, v2
	v_mov_b32_e32 v34, v2
	v_mov_b32_e32 v35, v2
	v_mov_b32_e32 v36, v2
	v_mov_b32_e32 v37, v2
	v_mov_b32_e32 v38, v2
	v_mov_b32_e32 v39, v2
	v_mov_b32_e32 v40, v2
	v_mov_b32_e32 v41, v2
	v_mov_b32_e32 v50, v2
	v_mov_b32_e32 v51, v2
	v_mov_b32_e32 v52, v2
	v_mov_b32_e32 v53, v2
	v_mov_b32_e32 v54, v2
	v_mov_b32_e32 v55, v2
	v_mov_b32_e32 v56, v2
	v_mov_b32_e32 v57, v2
	v_mov_b32_e32 v10, v2
	v_mov_b32_e32 v11, v2
	v_mov_b32_e32 v12, v2
	v_mov_b32_e32 v13, v2
	v_mov_b32_e32 v14, v2
	v_mov_b32_e32 v15, v2
	v_mov_b32_e32 v16, v2
	v_mov_b32_e32 v17, v2
	v_mov_b32_e32 v26, v2
	v_mov_b32_e32 v27, v2
	v_mov_b32_e32 v28, v2
	v_mov_b32_e32 v29, v2
	v_mov_b32_e32 v30, v2
	v_mov_b32_e32 v31, v2
	v_mov_b32_e32 v32, v2
	v_mov_b32_e32 v33, v2
	v_mov_b32_e32 v42, v2
	v_mov_b32_e32 v43, v2
	v_mov_b32_e32 v44, v2
	v_mov_b32_e32 v45, v2
	v_mov_b32_e32 v46, v2
	v_mov_b32_e32 v47, v2
	v_mov_b32_e32 v48, v2
	v_mov_b32_e32 v49, v2
	v_mov_b32_e32 v58, v2
	v_mov_b32_e32 v59, v2
	v_mov_b32_e32 v60, v2
	v_mov_b32_e32 v61, v2
	v_mov_b32_e32 v62, v2
	v_mov_b32_e32 v63, v2
	v_mov_b32_e32 v64, v2
	v_mov_b32_e32 v65, v2
	v_mov_b32_e32 v66, v2
	v_mov_b32_e32 v67, v2
	v_mov_b32_e32 v68, v2
	v_mov_b32_e32 v69, v2
	v_mov_b32_e32 v70, v2
	v_mov_b32_e32 v71, v2
	v_mov_b32_e32 v72, v2
	v_mov_b32_e32 v73, v2
	v_mov_b32_e32 v82, v2
	v_mov_b32_e32 v83, v2
	v_mov_b32_e32 v84, v2
	v_mov_b32_e32 v85, v2
	v_mov_b32_e32 v86, v2
	v_mov_b32_e32 v87, v2
	v_mov_b32_e32 v88, v2
	v_mov_b32_e32 v89, v2
	v_mov_b32_e32 v98, v2
	v_mov_b32_e32 v99, v2
	v_mov_b32_e32 v100, v2
	v_mov_b32_e32 v101, v2
	v_mov_b32_e32 v102, v2
	v_mov_b32_e32 v103, v2
	v_mov_b32_e32 v104, v2
	v_mov_b32_e32 v105, v2
	v_mov_b32_e32 v114, v2
	v_mov_b32_e32 v115, v2
	v_mov_b32_e32 v116, v2
	v_mov_b32_e32 v117, v2
	v_mov_b32_e32 v118, v2
	v_mov_b32_e32 v119, v2
	v_mov_b32_e32 v120, v2
	v_mov_b32_e32 v121, v2
	v_mov_b32_e32 v74, v2
	v_mov_b32_e32 v75, v2
	v_mov_b32_e32 v76, v2
	v_mov_b32_e32 v77, v2
	v_mov_b32_e32 v78, v2
	v_mov_b32_e32 v79, v2
	v_mov_b32_e32 v80, v2
	v_mov_b32_e32 v81, v2
	v_mov_b32_e32 v90, v2
	v_mov_b32_e32 v91, v2
	v_mov_b32_e32 v92, v2
	v_mov_b32_e32 v93, v2
	v_mov_b32_e32 v94, v2
	v_mov_b32_e32 v95, v2
	v_mov_b32_e32 v96, v2
	v_mov_b32_e32 v97, v2
	v_mov_b32_e32 v106, v2
	v_mov_b32_e32 v107, v2
	v_mov_b32_e32 v108, v2
	v_mov_b32_e32 v109, v2
	v_mov_b32_e32 v110, v2
	v_mov_b32_e32 v111, v2
	v_mov_b32_e32 v112, v2
	v_mov_b32_e32 v113, v2
	v_mov_b32_e32 v122, v2
	v_mov_b32_e32 v123, v2
	v_mov_b32_e32 v124, v2
	v_mov_b32_e32 v125, v2
	v_mov_b32_e32 v126, v2
	v_mov_b32_e32 v127, v2
	v_mov_b32_e32 v128, v2
	v_mov_b32_e32 v129, v2
	s_andn2_b64 vcc, exec, s[4:5]
	s_cbranch_vccnz .LBB0_2502

.LBB0_2768:
	ds_read_b128 v[148:151], v173
	ds_read_b128 v[152:155], v173 offset:1024
	ds_read_b128 v[156:159], v173 offset:2048
	ds_read_b128 v[160:163], v173 offset:3072
	s_add_u32 s8, s0, 0xfffc0080
	s_addc_u32 s9, s1, -1
	s_cmp_eq_u32 s24, 12
	s_cselect_b32 s11, s7, s9
	s_cselect_b32 s10, s12, s8
	s_cselect_b32 s9, s21, s19
	s_cselect_b32 s8, s20, s17
	v_lshl_add_u64 v[206:207], s[0:1], 0, v[140:141]
	s_add_i32 m0, s42, 0xc000
	ds_read_b128 v[164:167], v174
	ds_read_b128 v[168:171], v174 offset:1024
	ds_read_b128 v[182:185], v174 offset:2048
	ds_read_b128 v[186:189], v174 offset:3072
	ds_read_b128 v[190:193], v174 offset:4096
	ds_read_b128 v[194:197], v174 offset:5120
	ds_read_b128 v[198:201], v174 offset:6144
	ds_read_b128 v[202:205], v174 offset:7168
	global_load_lds_dwordx4 v[206:207], off
	v_lshl_add_u64 v[206:207], s[0:1], 0, v[142:143]
	s_add_i32 m0, s42, 0xe000
	s_nop 0
	global_load_lds_dwordx4 v[206:207], off
	s_waitcnt lgkmcnt(8)
	s_barrier
	s_waitcnt lgkmcnt(0)
	s_waitcnt lgkmcnt(0)
	v_mfma_f32_16x16x32_bf16 v[126:129], v[148:151], v[164:167], v[126:129]
	v_mfma_f32_16x16x32_bf16 v[122:125], v[156:159], v[164:167], v[122:125]
	v_mfma_f32_16x16x32_bf16 v[110:113], v[148:151], v[182:185], v[110:113]
	v_mfma_f32_16x16x32_bf16 v[106:109], v[156:159], v[182:185], v[106:109]
	v_mfma_f32_16x16x32_bf16 v[94:97], v[148:151], v[190:193], v[94:97]
	v_mfma_f32_16x16x32_bf16 v[90:93], v[156:159], v[190:193], v[90:93]
	v_mfma_f32_16x16x32_bf16 v[78:81], v[148:151], v[198:201], v[78:81]
	v_mfma_f32_16x16x32_bf16 v[74:77], v[156:159], v[198:201], v[74:77]
	v_mfma_f32_16x16x32_bf16 v[126:129], v[152:155], v[168:171], v[126:129]
	v_mfma_f32_16x16x32_bf16 v[122:125], v[160:163], v[168:171], v[122:125]
	v_mfma_f32_16x16x32_bf16 v[110:113], v[152:155], v[186:189], v[110:113]
	v_mfma_f32_16x16x32_bf16 v[106:109], v[160:163], v[186:189], v[106:109]
	v_mfma_f32_16x16x32_bf16 v[94:97], v[152:155], v[194:197], v[94:97]
	v_mfma_f32_16x16x32_bf16 v[90:93], v[160:163], v[194:197], v[90:93]
	v_mfma_f32_16x16x32_bf16 v[78:81], v[152:155], v[202:205], v[78:81]
	v_mfma_f32_16x16x32_bf16 v[74:77], v[160:163], v[202:205], v[74:77]
	s_barrier
	s_add_i32 s25, s52, s41
	v_lshl_add_u64 v[222:223], s[8:9], 0, v[130:131]
	s_mov_b32 m0, s25
	ds_read_b128 v[206:209], v175
	ds_read_b128 v[210:213], v175 offset:1024
	ds_read_b128 v[214:217], v175 offset:2048
	ds_read_b128 v[218:221], v175 offset:3072
	global_load_lds_dwordx4 v[222:223], off
	v_lshl_add_u64 v[224:225], s[8:9], 0, v[132:133]
	s_add_i32 m0, s25, 0x2000
	s_nop 0
	global_load_lds_dwordx4 v[224:225], off
	s_barrier
	s_waitcnt lgkmcnt(0)
	s_waitcnt lgkmcnt(0)
	v_mfma_f32_16x16x32_bf16 v[118:121], v[206:209], v[164:167], v[118:121]
	v_mfma_f32_16x16x32_bf16 v[114:117], v[214:217], v[164:167], v[114:117]
	v_mfma_f32_16x16x32_bf16 v[102:105], v[206:209], v[182:185], v[102:105]
	v_mfma_f32_16x16x32_bf16 v[98:101], v[214:217], v[182:185], v[98:101]
	v_mfma_f32_16x16x32_bf16 v[86:89], v[206:209], v[190:193], v[86:89]
	v_mfma_f32_16x16x32_bf16 v[82:85], v[214:217], v[190:193], v[82:85]
	v_mfma_f32_16x16x32_bf16 v[70:73], v[206:209], v[198:201], v[70:73]
	v_mfma_f32_16x16x32_bf16 v[66:69], v[214:217], v[198:201], v[66:69]
	v_mfma_f32_16x16x32_bf16 v[118:121], v[210:213], v[168:171], v[118:121]
	v_mfma_f32_16x16x32_bf16 v[114:117], v[218:221], v[168:171], v[114:117]
	v_mfma_f32_16x16x32_bf16 v[102:105], v[210:213], v[186:189], v[102:105]
	v_mfma_f32_16x16x32_bf16 v[98:101], v[218:221], v[186:189], v[98:101]
	v_mfma_f32_16x16x32_bf16 v[86:89], v[210:213], v[194:197], v[86:89]
	v_mfma_f32_16x16x32_bf16 v[82:85], v[218:221], v[194:197], v[82:85]
	v_mfma_f32_16x16x32_bf16 v[70:73], v[210:213], v[202:205], v[70:73]
	v_mfma_f32_16x16x32_bf16 v[66:69], v[218:221], v[202:205], v[66:69]
	s_mov_b32 m0, s42
	v_lshl_add_u64 v[228:229], s[10:11], 0, v[130:131]
	s_barrier
	ds_read_b128 v[164:167], v174 offset:16384
	ds_read_b128 v[168:171], v174 offset:17408
	ds_read_b128 v[182:185], v174 offset:18432
	ds_read_b128 v[186:189], v174 offset:19456
	ds_read_b128 v[190:193], v174 offset:20480
	ds_read_b128 v[194:197], v174 offset:21504
	ds_read_b128 v[198:201], v174 offset:22528
	ds_read_b128 v[202:205], v174 offset:23552
	global_load_lds_dwordx4 v[228:229], off
	v_lshl_add_u64 v[230:231], s[10:11], 0, v[132:133]
	s_mov_b32 m0, s43
	s_nop 0
	global_load_lds_dwordx4 v[230:231], off
	s_barrier
	s_waitcnt lgkmcnt(0)
	s_waitcnt lgkmcnt(0)
	v_mfma_f32_16x16x32_bf16 v[62:65], v[148:151], v[164:167], v[62:65]
	v_mfma_f32_16x16x32_bf16 v[58:61], v[156:159], v[164:167], v[58:61]
	v_mfma_f32_16x16x32_bf16 v[46:49], v[148:151], v[182:185], v[46:49]
	v_mfma_f32_16x16x32_bf16 v[42:45], v[156:159], v[182:185], v[42:45]
	v_mfma_f32_16x16x32_bf16 v[30:33], v[148:151], v[190:193], v[30:33]
	v_mfma_f32_16x16x32_bf16 v[26:29], v[156:159], v[190:193], v[26:29]
	v_mfma_f32_16x16x32_bf16 v[14:17], v[148:151], v[198:201], v[14:17]
	v_mfma_f32_16x16x32_bf16 v[10:13], v[156:159], v[198:201], v[10:13]
	v_mfma_f32_16x16x32_bf16 v[62:65], v[152:155], v[168:171], v[62:65]
	v_mfma_f32_16x16x32_bf16 v[58:61], v[160:163], v[168:171], v[58:61]
	v_mfma_f32_16x16x32_bf16 v[46:49], v[152:155], v[186:189], v[46:49]
	v_mfma_f32_16x16x32_bf16 v[42:45], v[160:163], v[186:189], v[42:45]
	v_mfma_f32_16x16x32_bf16 v[30:33], v[152:155], v[194:197], v[30:33]
	v_mfma_f32_16x16x32_bf16 v[26:29], v[160:163], v[194:197], v[26:29]
	v_mfma_f32_16x16x32_bf16 v[14:17], v[152:155], v[202:205], v[14:17]
	v_mfma_f32_16x16x32_bf16 v[10:13], v[160:163], v[202:205], v[10:13]
	s_barrier
	s_add_u32 s26, s8, 0x40000
	s_addc_u32 s27, s9, 0
	s_add_i32 s25, s53, s41
	v_lshl_add_u64 v[148:149], s[26:27], 0, v[130:131]
	s_mov_b32 m0, s25
	s_nop 0
	global_load_lds_dwordx4 v[148:149], off
	v_lshl_add_u64 v[148:149], s[26:27], 0, v[132:133]
	s_add_i32 m0, s25, 0x2000
	s_nop 0
	global_load_lds_dwordx4 v[148:149], off
	s_waitcnt vmcnt(6)
	s_barrier
	v_mfma_f32_16x16x32_bf16 v[54:57], v[206:209], v[164:167], v[54:57]
	v_mfma_f32_16x16x32_bf16 v[50:53], v[214:217], v[164:167], v[50:53]
	v_mfma_f32_16x16x32_bf16 v[38:41], v[206:209], v[182:185], v[38:41]
	v_mfma_f32_16x16x32_bf16 v[34:37], v[214:217], v[182:185], v[34:37]
	v_mfma_f32_16x16x32_bf16 v[22:25], v[206:209], v[190:193], v[22:25]
	v_mfma_f32_16x16x32_bf16 v[18:21], v[214:217], v[190:193], v[18:21]
	v_mfma_f32_16x16x32_bf16 v[6:9], v[206:209], v[198:201], v[6:9]
	v_mfma_f32_16x16x32_bf16 v[2:5], v[214:217], v[198:201], v[2:5]
	v_mfma_f32_16x16x32_bf16 v[54:57], v[210:213], v[168:171], v[54:57]
	v_mfma_f32_16x16x32_bf16 v[50:53], v[218:221], v[168:171], v[50:53]
	v_mfma_f32_16x16x32_bf16 v[38:41], v[210:213], v[186:189], v[38:41]
	v_mfma_f32_16x16x32_bf16 v[34:37], v[218:221], v[186:189], v[34:37]
	v_mfma_f32_16x16x32_bf16 v[22:25], v[210:213], v[194:197], v[22:25]
	v_mfma_f32_16x16x32_bf16 v[18:21], v[218:221], v[194:197], v[18:21]
	v_mfma_f32_16x16x32_bf16 v[6:9], v[210:213], v[202:205], v[6:9]
	v_mfma_f32_16x16x32_bf16 v[2:5], v[218:221], v[202:205], v[2:5]
	s_add_i32 s25, 0, 0x18000
	v_add_u32_e32 v134, s25, v172
	s_barrier
	ds_read_b128 v[148:151], v134
	ds_read_b128 v[152:155], v134 offset:1024
	ds_read_b128 v[156:159], v134 offset:2048
	ds_read_b128 v[160:163], v134 offset:3072
	s_add_u32 s10, s10, 0x40000
	s_addc_u32 s11, s11, 0
	s_mov_b32 m0, s44
	v_lshl_add_u64 v[206:207], s[10:11], 0, v[130:131]
	ds_read_b128 v[164:167], v174 offset:32768
	ds_read_b128 v[168:171], v174 offset:33792
	ds_read_b128 v[182:185], v174 offset:34816
	ds_read_b128 v[186:189], v174 offset:35840
	ds_read_b128 v[190:193], v174 offset:36864
	ds_read_b128 v[194:197], v174 offset:37888
	ds_read_b128 v[198:201], v174 offset:38912
	ds_read_b128 v[202:205], v174 offset:39936
	global_load_lds_dwordx4 v[206:207], off
	v_lshl_add_u64 v[206:207], s[10:11], 0, v[132:133]
	s_mov_b32 m0, s45
	s_nop 0
	global_load_lds_dwordx4 v[206:207], off
	s_waitcnt lgkmcnt(8)
	s_barrier
	s_waitcnt lgkmcnt(0)
	s_waitcnt lgkmcnt(0)
	v_mfma_f32_16x16x32_bf16 v[126:129], v[148:151], v[164:167], v[126:129]
	v_mfma_f32_16x16x32_bf16 v[122:125], v[156:159], v[164:167], v[122:125]
	v_mfma_f32_16x16x32_bf16 v[110:113], v[148:151], v[182:185], v[110:113]
	v_mfma_f32_16x16x32_bf16 v[106:109], v[156:159], v[182:185], v[106:109]
	v_mfma_f32_16x16x32_bf16 v[94:97], v[148:151], v[190:193], v[94:97]
	v_mfma_f32_16x16x32_bf16 v[90:93], v[156:159], v[190:193], v[90:93]
	v_mfma_f32_16x16x32_bf16 v[78:81], v[148:151], v[198:201], v[78:81]
	v_mfma_f32_16x16x32_bf16 v[74:77], v[156:159], v[198:201], v[74:77]
	v_mfma_f32_16x16x32_bf16 v[126:129], v[152:155], v[168:171], v[126:129]
	v_mfma_f32_16x16x32_bf16 v[122:125], v[160:163], v[168:171], v[122:125]
	v_mfma_f32_16x16x32_bf16 v[110:113], v[152:155], v[186:189], v[110:113]
	v_mfma_f32_16x16x32_bf16 v[106:109], v[160:163], v[186:189], v[106:109]
	v_mfma_f32_16x16x32_bf16 v[94:97], v[152:155], v[194:197], v[94:97]
	v_mfma_f32_16x16x32_bf16 v[90:93], v[160:163], v[194:197], v[90:93]
	v_mfma_f32_16x16x32_bf16 v[78:81], v[152:155], v[202:205], v[78:81]
	v_mfma_f32_16x16x32_bf16 v[74:77], v[160:163], v[202:205], v[74:77]
	s_barrier
	s_add_i32 s10, 0, 0x1c000
	s_add_i32 s11, s25, s41
	v_add_u32_e32 v134, s10, v172
	v_lshl_add_u64 v[222:223], v[222:223], 0, s[14:15]
	s_mov_b32 m0, s11
	ds_read_b128 v[206:209], v134
	ds_read_b128 v[210:213], v134 offset:1024
	ds_read_b128 v[214:217], v134 offset:2048
	ds_read_b128 v[218:221], v134 offset:3072
	global_load_lds_dwordx4 v[222:223], off
	v_lshl_add_u64 v[222:223], v[224:225], 0, s[14:15]
	s_add_i32 m0, s11, 0x2000
	s_nop 0
	global_load_lds_dwordx4 v[222:223], off
	s_barrier
	s_waitcnt lgkmcnt(0)
	s_waitcnt lgkmcnt(0)
	v_mfma_f32_16x16x32_bf16 v[118:121], v[206:209], v[164:167], v[118:121]
	v_mfma_f32_16x16x32_bf16 v[114:117], v[214:217], v[164:167], v[114:117]
	v_mfma_f32_16x16x32_bf16 v[102:105], v[206:209], v[182:185], v[102:105]
	v_mfma_f32_16x16x32_bf16 v[98:101], v[214:217], v[182:185], v[98:101]
	v_mfma_f32_16x16x32_bf16 v[86:89], v[206:209], v[190:193], v[86:89]
	v_mfma_f32_16x16x32_bf16 v[82:85], v[214:217], v[190:193], v[82:85]
	v_mfma_f32_16x16x32_bf16 v[70:73], v[206:209], v[198:201], v[70:73]
	v_mfma_f32_16x16x32_bf16 v[66:69], v[214:217], v[198:201], v[66:69]
	v_mfma_f32_16x16x32_bf16 v[118:121], v[210:213], v[168:171], v[118:121]
	v_mfma_f32_16x16x32_bf16 v[114:117], v[218:221], v[168:171], v[114:117]
	v_mfma_f32_16x16x32_bf16 v[102:105], v[210:213], v[186:189], v[102:105]
	v_mfma_f32_16x16x32_bf16 v[98:101], v[218:221], v[186:189], v[98:101]
	v_mfma_f32_16x16x32_bf16 v[86:89], v[210:213], v[194:197], v[86:89]
	v_mfma_f32_16x16x32_bf16 v[82:85], v[218:221], v[194:197], v[82:85]
	v_mfma_f32_16x16x32_bf16 v[70:73], v[210:213], v[202:205], v[70:73]
	v_mfma_f32_16x16x32_bf16 v[66:69], v[218:221], v[202:205], v[66:69]
	s_mov_b32 m0, s47
	v_lshl_add_u64 v[222:223], v[228:229], 0, s[14:15]
	s_barrier
	ds_read_b128 v[164:167], v174 offset:49152
	ds_read_b128 v[168:171], v174 offset:50176
	ds_read_b128 v[182:185], v174 offset:51200
	ds_read_b128 v[186:189], v174 offset:52224
	ds_read_b128 v[190:193], v174 offset:53248
	ds_read_b128 v[194:197], v174 offset:54272
	ds_read_b128 v[198:201], v174 offset:55296
	ds_read_b128 v[202:205], v174 offset:56320
	global_load_lds_dwordx4 v[222:223], off
	v_lshl_add_u64 v[222:223], v[230:231], 0, s[14:15]
	s_mov_b32 m0, s48
	s_nop 0
	global_load_lds_dwordx4 v[222:223], off
	s_barrier
	s_waitcnt lgkmcnt(0)
	s_waitcnt lgkmcnt(0)
	v_mfma_f32_16x16x32_bf16 v[62:65], v[148:151], v[164:167], v[62:65]
	v_mfma_f32_16x16x32_bf16 v[58:61], v[156:159], v[164:167], v[58:61]
	v_mfma_f32_16x16x32_bf16 v[46:49], v[148:151], v[182:185], v[46:49]
	v_mfma_f32_16x16x32_bf16 v[42:45], v[156:159], v[182:185], v[42:45]
	v_mfma_f32_16x16x32_bf16 v[30:33], v[148:151], v[190:193], v[30:33]
	v_mfma_f32_16x16x32_bf16 v[26:29], v[156:159], v[190:193], v[26:29]
	v_mfma_f32_16x16x32_bf16 v[14:17], v[148:151], v[198:201], v[14:17]
	v_mfma_f32_16x16x32_bf16 v[10:13], v[156:159], v[198:201], v[10:13]
	v_mfma_f32_16x16x32_bf16 v[62:65], v[152:155], v[168:171], v[62:65]
	v_mfma_f32_16x16x32_bf16 v[58:61], v[160:163], v[168:171], v[58:61]
	v_mfma_f32_16x16x32_bf16 v[46:49], v[152:155], v[186:189], v[46:49]
	v_mfma_f32_16x16x32_bf16 v[42:45], v[160:163], v[186:189], v[42:45]
	v_mfma_f32_16x16x32_bf16 v[30:33], v[152:155], v[194:197], v[30:33]
	v_mfma_f32_16x16x32_bf16 v[26:29], v[160:163], v[194:197], v[26:29]
	v_mfma_f32_16x16x32_bf16 v[14:17], v[152:155], v[202:205], v[14:17]
	v_mfma_f32_16x16x32_bf16 v[10:13], v[160:163], v[202:205], v[10:13]
	s_barrier
	s_add_u32 s8, s8, 0x40080
	s_addc_u32 s9, s9, 0
	s_add_i32 s10, s10, s41
	v_lshl_add_u64 v[148:149], s[8:9], 0, v[130:131]
	s_mov_b32 m0, s10
	s_nop 0
	global_load_lds_dwordx4 v[148:149], off
	v_lshl_add_u64 v[148:149], s[8:9], 0, v[132:133]
	s_add_i32 m0, s10, 0x2000
	s_nop 0
	global_load_lds_dwordx4 v[148:149], off
	s_waitcnt vmcnt(6)
	s_barrier
	v_mfma_f32_16x16x32_bf16 v[54:57], v[206:209], v[164:167], v[54:57]
	v_mfma_f32_16x16x32_bf16 v[50:53], v[214:217], v[164:167], v[50:53]
	v_mfma_f32_16x16x32_bf16 v[38:41], v[206:209], v[182:185], v[38:41]
	v_mfma_f32_16x16x32_bf16 v[34:37], v[214:217], v[182:185], v[34:37]
	v_mfma_f32_16x16x32_bf16 v[22:25], v[206:209], v[190:193], v[22:25]
	v_mfma_f32_16x16x32_bf16 v[18:21], v[214:217], v[190:193], v[18:21]
	v_mfma_f32_16x16x32_bf16 v[6:9], v[206:209], v[198:201], v[6:9]
	v_mfma_f32_16x16x32_bf16 v[2:5], v[214:217], v[198:201], v[2:5]
	v_mfma_f32_16x16x32_bf16 v[54:57], v[210:213], v[168:171], v[54:57]
	v_mfma_f32_16x16x32_bf16 v[50:53], v[218:221], v[168:171], v[50:53]
	v_mfma_f32_16x16x32_bf16 v[38:41], v[210:213], v[186:189], v[38:41]
	v_mfma_f32_16x16x32_bf16 v[34:37], v[218:221], v[186:189], v[34:37]
	v_mfma_f32_16x16x32_bf16 v[22:25], v[210:213], v[194:197], v[22:25]
	v_mfma_f32_16x16x32_bf16 v[18:21], v[218:221], v[194:197], v[18:21]
	v_mfma_f32_16x16x32_bf16 v[6:9], v[210:213], v[202:205], v[6:9]
	v_mfma_f32_16x16x32_bf16 v[2:5], v[218:221], v[202:205], v[2:5]
	s_add_i32 s24, s24, 2
	s_add_u32 s0, s0, 0x100
	s_addc_u32 s1, s1, 0
	s_add_u32 s17, s17, 0x100
	s_addc_u32 s19, s19, 0
	s_cmp_gt_u32 s24, 13
	s_barrier
	s_cbranch_scc0 .LBB0_2768
	s_mov_b64 s[30:31], exec
	s_load_dwordx8 s[80:87], s[78:79], 0x130
	s_load_dwordx4 s[88:91], s[78:79], 0x270
	s_load_dwordx2 s[92:93], s[78:79], 0x280
	s_load_dwordx2 s[94:95], s[78:79], 0x200
	s_load_dwordx2 s[64:65], s[78:79], 0x220
	s_load_dwordx2 s[66:67], s[78:79], 0x1e0
	v_and_b32_e32 v148, 15, v248
	v_bfe_u32 v149, v248, 8, 1
	v_bfe_u32 v150, v248, 6, 2
	v_bfe_u32 v151, v248, 4, 2
	v_lshlrev_b32_e32 v152, 5, v150
	v_lshl_or_b32 v152, v151, 2, v152
	v_lshl_add_u32 v153, v149, 6, v148
	s_lshl_b32 s0, s6, 8
	v_add_u32_e32 v154, s0, v153
	s_cmp_ge_u32 s28, 6
	s_cbranch_scc1 .Lmy_kn_nsa
	s_cmp_ge_u32 s6, 64
	s_cbranch_scc1 .Lmy_kn_smp
	s_cmp_ge_u32 s28, 4
	s_cbranch_scc1 .Lmy_kn_p_bf
	s_lshl_b32 s0, s28, 10
	v_lshlrev_b32_e32 v155, 12, v154
	v_lshl_add_u32 v155, v152, 2, v155
	v_add_u32_e32 v155, s0, v155
	s_waitcnt lgkmcnt(0)
	global_store_dwordx4 v155, v[126:129], s[80:81]
	global_store_dwordx4 v155, v[122:125], s[80:81] offset:64
	global_store_dwordx4 v155, v[118:121], s[80:81] offset:512
	global_store_dwordx4 v155, v[114:117], s[80:81] offset:576
	v_add_u32_e32 v134, 0x10000, v155
	global_store_dwordx4 v134, v[110:113], s[80:81]
	v_add_u32_e32 v134, 0x10040, v155
	global_store_dwordx4 v134, v[106:109], s[80:81]
	v_add_u32_e32 v134, 0x10200, v155
	global_store_dwordx4 v134, v[102:105], s[80:81]
	v_add_u32_e32 v134, 0x10240, v155
	global_store_dwordx4 v134, v[98:101], s[80:81]
	v_add_u32_e32 v134, 0x20000, v155
	global_store_dwordx4 v134, v[94:97], s[80:81]
	v_add_u32_e32 v134, 0x20040, v155
	global_store_dwordx4 v134, v[90:93], s[80:81]
	v_add_u32_e32 v134, 0x20200, v155
	global_store_dwordx4 v134, v[86:89], s[80:81]
	v_add_u32_e32 v134, 0x20240, v155
	global_store_dwordx4 v134, v[82:85], s[80:81]
	v_add_u32_e32 v134, 0x30000, v155
	global_store_dwordx4 v134, v[78:81], s[80:81]
	v_add_u32_e32 v134, 0x30040, v155
	global_store_dwordx4 v134, v[74:77], s[80:81]
	v_add_u32_e32 v134, 0x30200, v155
	global_store_dwordx4 v134, v[70:73], s[80:81]
	v_add_u32_e32 v134, 0x30240, v155
	global_store_dwordx4 v134, v[66:69], s[80:81]
	v_add_u32_e32 v134, 0x80000, v155
	global_store_dwordx4 v134, v[62:65], s[80:81]
	v_add_u32_e32 v134, 0x80040, v155
	global_store_dwordx4 v134, v[58:61], s[80:81]
	v_add_u32_e32 v134, 0x80200, v155
	global_store_dwordx4 v134, v[54:57], s[80:81]
	v_add_u32_e32 v134, 0x80240, v155
	global_store_dwordx4 v134, v[50:53], s[80:81]
	v_add_u32_e32 v134, 0x90000, v155
	global_store_dwordx4 v134, v[46:49], s[80:81]
	v_add_u32_e32 v134, 0x90040, v155
	global_store_dwordx4 v134, v[42:45], s[80:81]
	v_add_u32_e32 v134, 0x90200, v155
	global_store_dwordx4 v134, v[38:41], s[80:81]
	v_add_u32_e32 v134, 0x90240, v155
	global_store_dwordx4 v134, v[34:37], s[80:81]
	v_add_u32_e32 v134, 0xa0000, v155
	global_store_dwordx4 v134, v[30:33], s[80:81]
	v_add_u32_e32 v134, 0xa0040, v155
	global_store_dwordx4 v134, v[26:29], s[80:81]
	v_add_u32_e32 v134, 0xa0200, v155
	global_store_dwordx4 v134, v[22:25], s[80:81]
	v_add_u32_e32 v134, 0xa0240, v155
	global_store_dwordx4 v134, v[18:21], s[80:81]
	v_add_u32_e32 v134, 0xb0000, v155
	global_store_dwordx4 v134, v[14:17], s[80:81]
	v_add_u32_e32 v134, 0xb0040, v155
	global_store_dwordx4 v134, v[10:13], s[80:81]
	v_add_u32_e32 v134, 0xb0200, v155
	global_store_dwordx4 v134, v[6:9], s[80:81]
	v_add_u32_e32 v134, 0xb0240, v155
	global_store_dwordx4 v134, v[2:5], s[80:81]

.LBB0_3964:
	ds_read_b128 v[142:145], v155
	ds_read_b128 v[158:161], v155 offset:1024
	ds_read_b128 v[162:165], v155 offset:2048
	ds_read_b128 v[166:169], v155 offset:3072
	s_add_u32 s18, s16, 0xfffc0080
	s_addc_u32 s19, s17, -1
	s_cmp_eq_u32 s44, 12
	s_cselect_b32 s21, s9, s19
	s_cselect_b32 s20, s40, s18
	s_cselect_b32 s19, s7, s43
	s_cselect_b32 s18, s41, s42
	v_lshl_add_u64 v[206:207], s[16:17], 0, v[138:139]
	s_add_i32 m0, s27, 0xc000
	ds_read_b128 v[170:173], v156
	ds_read_b128 v[174:177], v156 offset:1024
	ds_read_b128 v[182:185], v156 offset:2048
	ds_read_b128 v[186:189], v156 offset:3072
	ds_read_b128 v[190:193], v156 offset:4096
	ds_read_b128 v[194:197], v156 offset:5120
	ds_read_b128 v[198:201], v156 offset:6144
	ds_read_b128 v[202:205], v156 offset:7168
	global_load_lds_dwordx4 v[206:207], off
	v_lshl_add_u64 v[206:207], s[16:17], 0, v[140:141]
	s_add_i32 m0, s27, 0xe000
	s_nop 0
	global_load_lds_dwordx4 v[206:207], off
	s_waitcnt lgkmcnt(8)
	s_barrier
	s_waitcnt lgkmcnt(0)
	s_waitcnt lgkmcnt(0)
	v_mfma_f32_16x16x32_bf16 v[126:129], v[142:145], v[170:173], v[126:129]
	v_mfma_f32_16x16x32_bf16 v[122:125], v[162:165], v[170:173], v[122:125]
	v_mfma_f32_16x16x32_bf16 v[114:117], v[142:145], v[182:185], v[114:117]
	v_mfma_f32_16x16x32_bf16 v[106:109], v[162:165], v[182:185], v[106:109]
	v_mfma_f32_16x16x32_bf16 v[98:101], v[142:145], v[190:193], v[98:101]
	v_mfma_f32_16x16x32_bf16 v[90:93], v[162:165], v[190:193], v[90:93]
	v_mfma_f32_16x16x32_bf16 v[82:85], v[142:145], v[198:201], v[82:85]
	v_mfma_f32_16x16x32_bf16 v[74:77], v[162:165], v[198:201], v[74:77]
	v_mfma_f32_16x16x32_bf16 v[126:129], v[158:161], v[174:177], v[126:129]
	v_mfma_f32_16x16x32_bf16 v[122:125], v[166:169], v[174:177], v[122:125]
	v_mfma_f32_16x16x32_bf16 v[114:117], v[158:161], v[186:189], v[114:117]
	v_mfma_f32_16x16x32_bf16 v[106:109], v[166:169], v[186:189], v[106:109]
	v_mfma_f32_16x16x32_bf16 v[98:101], v[158:161], v[194:197], v[98:101]
	v_mfma_f32_16x16x32_bf16 v[90:93], v[166:169], v[194:197], v[90:93]
	v_mfma_f32_16x16x32_bf16 v[82:85], v[158:161], v[202:205], v[82:85]
	v_mfma_f32_16x16x32_bf16 v[74:77], v[166:169], v[202:205], v[74:77]
	s_barrier
	s_add_i32 s45, s36, s25
	v_lshl_add_u64 v[222:223], s[18:19], 0, v[132:133]
	s_mov_b32 m0, s45
	ds_read_b128 v[206:209], v157
	ds_read_b128 v[210:213], v157 offset:1024
	ds_read_b128 v[214:217], v157 offset:2048
	ds_read_b128 v[218:221], v157 offset:3072
	global_load_lds_dwordx4 v[222:223], off
	v_lshl_add_u64 v[224:225], s[18:19], 0, v[136:137]
	s_add_i32 m0, s45, 0x2000
	s_nop 0
	global_load_lds_dwordx4 v[224:225], off
	s_barrier
	s_waitcnt lgkmcnt(0)
	s_waitcnt lgkmcnt(0)
	v_mfma_f32_16x16x32_bf16 v[118:121], v[206:209], v[170:173], v[118:121]
	v_mfma_f32_16x16x32_bf16 v[110:113], v[214:217], v[170:173], v[110:113]
	v_mfma_f32_16x16x32_bf16 v[102:105], v[206:209], v[182:185], v[102:105]
	v_mfma_f32_16x16x32_bf16 v[94:97], v[214:217], v[182:185], v[94:97]
	v_mfma_f32_16x16x32_bf16 v[86:89], v[206:209], v[190:193], v[86:89]
	v_mfma_f32_16x16x32_bf16 v[78:81], v[214:217], v[190:193], v[78:81]
	v_mfma_f32_16x16x32_bf16 v[70:73], v[206:209], v[198:201], v[70:73]
	v_mfma_f32_16x16x32_bf16 v[66:69], v[214:217], v[198:201], v[66:69]
	v_mfma_f32_16x16x32_bf16 v[118:121], v[210:213], v[174:177], v[118:121]
	v_mfma_f32_16x16x32_bf16 v[110:113], v[218:221], v[174:177], v[110:113]
	v_mfma_f32_16x16x32_bf16 v[102:105], v[210:213], v[186:189], v[102:105]
	v_mfma_f32_16x16x32_bf16 v[94:97], v[218:221], v[186:189], v[94:97]
	v_mfma_f32_16x16x32_bf16 v[86:89], v[210:213], v[194:197], v[86:89]
	v_mfma_f32_16x16x32_bf16 v[78:81], v[218:221], v[194:197], v[78:81]
	v_mfma_f32_16x16x32_bf16 v[70:73], v[210:213], v[202:205], v[70:73]
	v_mfma_f32_16x16x32_bf16 v[66:69], v[218:221], v[202:205], v[66:69]
	s_mov_b32 m0, s27
	v_lshl_add_u64 v[228:229], s[20:21], 0, v[130:131]
	s_barrier
	ds_read_b128 v[170:173], v156 offset:16384
	ds_read_b128 v[174:177], v156 offset:17408
	ds_read_b128 v[182:185], v156 offset:18432
	ds_read_b128 v[186:189], v156 offset:19456
	ds_read_b128 v[190:193], v156 offset:20480
	ds_read_b128 v[194:197], v156 offset:21504
	ds_read_b128 v[198:201], v156 offset:22528
	ds_read_b128 v[202:205], v156 offset:23552
	global_load_lds_dwordx4 v[228:229], off
	v_lshl_add_u64 v[230:231], s[20:21], 0, v[134:135]
	s_mov_b32 m0, s28
	s_nop 0
	global_load_lds_dwordx4 v[230:231], off
	s_barrier
	s_waitcnt lgkmcnt(0)
	s_waitcnt lgkmcnt(0)
	v_mfma_f32_16x16x32_bf16 v[62:65], v[142:145], v[170:173], v[62:65]
	v_mfma_f32_16x16x32_bf16 v[58:61], v[162:165], v[170:173], v[58:61]
	v_mfma_f32_16x16x32_bf16 v[50:53], v[142:145], v[182:185], v[50:53]
	v_mfma_f32_16x16x32_bf16 v[42:45], v[162:165], v[182:185], v[42:45]
	v_mfma_f32_16x16x32_bf16 v[34:37], v[142:145], v[190:193], v[34:37]
	v_mfma_f32_16x16x32_bf16 v[26:29], v[162:165], v[190:193], v[26:29]
	v_mfma_f32_16x16x32_bf16 v[18:21], v[142:145], v[198:201], v[18:21]
	v_mfma_f32_16x16x32_bf16 v[10:13], v[162:165], v[198:201], v[10:13]
	v_mfma_f32_16x16x32_bf16 v[62:65], v[158:161], v[174:177], v[62:65]
	v_mfma_f32_16x16x32_bf16 v[58:61], v[166:169], v[174:177], v[58:61]
	v_mfma_f32_16x16x32_bf16 v[50:53], v[158:161], v[186:189], v[50:53]
	v_mfma_f32_16x16x32_bf16 v[42:45], v[166:169], v[186:189], v[42:45]
	v_mfma_f32_16x16x32_bf16 v[34:37], v[158:161], v[194:197], v[34:37]
	v_mfma_f32_16x16x32_bf16 v[26:29], v[166:169], v[194:197], v[26:29]
	v_mfma_f32_16x16x32_bf16 v[18:21], v[158:161], v[202:205], v[18:21]
	v_mfma_f32_16x16x32_bf16 v[10:13], v[166:169], v[202:205], v[10:13]
	s_barrier
	s_add_u32 s46, s18, 0x40000
	s_addc_u32 s47, s19, 0
	s_add_i32 s45, s37, s25
	v_lshl_add_u64 v[142:143], s[46:47], 0, v[132:133]
	s_mov_b32 m0, s45
	s_nop 0
	global_load_lds_dwordx4 v[142:143], off
	v_lshl_add_u64 v[142:143], s[46:47], 0, v[136:137]
	s_add_i32 m0, s45, 0x2000
	s_nop 0
	global_load_lds_dwordx4 v[142:143], off
	s_waitcnt vmcnt(6)
	s_barrier
	v_mfma_f32_16x16x32_bf16 v[54:57], v[206:209], v[170:173], v[54:57]
	v_mfma_f32_16x16x32_bf16 v[46:49], v[214:217], v[170:173], v[46:49]
	v_mfma_f32_16x16x32_bf16 v[38:41], v[206:209], v[182:185], v[38:41]
	v_mfma_f32_16x16x32_bf16 v[30:33], v[214:217], v[182:185], v[30:33]
	v_mfma_f32_16x16x32_bf16 v[22:25], v[206:209], v[190:193], v[22:25]
	v_mfma_f32_16x16x32_bf16 v[14:17], v[214:217], v[190:193], v[14:17]
	v_mfma_f32_16x16x32_bf16 v[6:9], v[206:209], v[198:201], v[6:9]
	v_mfma_f32_16x16x32_bf16 v[2:5], v[214:217], v[198:201], v[2:5]
	v_mfma_f32_16x16x32_bf16 v[54:57], v[210:213], v[174:177], v[54:57]
	v_mfma_f32_16x16x32_bf16 v[46:49], v[218:221], v[174:177], v[46:49]
	v_mfma_f32_16x16x32_bf16 v[38:41], v[210:213], v[186:189], v[38:41]
	v_mfma_f32_16x16x32_bf16 v[30:33], v[218:221], v[186:189], v[30:33]
	v_mfma_f32_16x16x32_bf16 v[22:25], v[210:213], v[194:197], v[22:25]
	v_mfma_f32_16x16x32_bf16 v[14:17], v[218:221], v[194:197], v[14:17]
	v_mfma_f32_16x16x32_bf16 v[6:9], v[210:213], v[202:205], v[6:9]
	v_mfma_f32_16x16x32_bf16 v[2:5], v[218:221], v[202:205], v[2:5]
	s_add_i32 s45, 0, 0x18000
	v_add_u32_e32 v166, s45, v153
	s_barrier
	ds_read_b128 v[142:145], v166
	ds_read_b128 v[158:161], v166 offset:1024
	ds_read_b128 v[162:165], v166 offset:2048
	ds_read_b128 v[166:169], v166 offset:3072
	s_add_u32 s20, s20, 0x40000
	s_addc_u32 s21, s21, 0
	s_mov_b32 m0, s29
	v_lshl_add_u64 v[206:207], s[20:21], 0, v[130:131]
	ds_read_b128 v[170:173], v156 offset:32768
	ds_read_b128 v[174:177], v156 offset:33792
	ds_read_b128 v[182:185], v156 offset:34816
	ds_read_b128 v[186:189], v156 offset:35840
	ds_read_b128 v[190:193], v156 offset:36864
	ds_read_b128 v[194:197], v156 offset:37888
	ds_read_b128 v[198:201], v156 offset:38912
	ds_read_b128 v[202:205], v156 offset:39936
	global_load_lds_dwordx4 v[206:207], off
	v_lshl_add_u64 v[206:207], s[20:21], 0, v[134:135]
	s_mov_b32 m0, s30
	s_nop 0
	global_load_lds_dwordx4 v[206:207], off
	s_waitcnt lgkmcnt(8)
	s_barrier
	s_waitcnt lgkmcnt(0)
	s_waitcnt lgkmcnt(0)
	v_mfma_f32_16x16x32_bf16 v[126:129], v[142:145], v[170:173], v[126:129]
	v_mfma_f32_16x16x32_bf16 v[122:125], v[162:165], v[170:173], v[122:125]
	v_mfma_f32_16x16x32_bf16 v[114:117], v[142:145], v[182:185], v[114:117]
	v_mfma_f32_16x16x32_bf16 v[106:109], v[162:165], v[182:185], v[106:109]
	v_mfma_f32_16x16x32_bf16 v[98:101], v[142:145], v[190:193], v[98:101]
	v_mfma_f32_16x16x32_bf16 v[90:93], v[162:165], v[190:193], v[90:93]
	v_mfma_f32_16x16x32_bf16 v[82:85], v[142:145], v[198:201], v[82:85]
	v_mfma_f32_16x16x32_bf16 v[74:77], v[162:165], v[198:201], v[74:77]
	v_mfma_f32_16x16x32_bf16 v[126:129], v[158:161], v[174:177], v[126:129]
	v_mfma_f32_16x16x32_bf16 v[122:125], v[166:169], v[174:177], v[122:125]
	v_mfma_f32_16x16x32_bf16 v[114:117], v[158:161], v[186:189], v[114:117]
	v_mfma_f32_16x16x32_bf16 v[106:109], v[166:169], v[186:189], v[106:109]
	v_mfma_f32_16x16x32_bf16 v[98:101], v[158:161], v[194:197], v[98:101]
	v_mfma_f32_16x16x32_bf16 v[90:93], v[166:169], v[194:197], v[90:93]
	v_mfma_f32_16x16x32_bf16 v[82:85], v[158:161], v[202:205], v[82:85]
	v_mfma_f32_16x16x32_bf16 v[74:77], v[166:169], v[202:205], v[74:77]
	s_barrier
	s_add_i32 s20, 0, 0x1c000
	s_add_i32 s21, s45, s25
	v_add_u32_e32 v181, s20, v153
	v_lshl_add_u64 v[222:223], v[222:223], 0, s[2:3]
	s_mov_b32 m0, s21
	ds_read_b128 v[206:209], v181
	ds_read_b128 v[210:213], v181 offset:1024
	ds_read_b128 v[214:217], v181 offset:2048
	ds_read_b128 v[218:221], v181 offset:3072
	global_load_lds_dwordx4 v[222:223], off
	v_lshl_add_u64 v[222:223], v[224:225], 0, s[2:3]
	s_add_i32 m0, s21, 0x2000
	s_nop 0
	global_load_lds_dwordx4 v[222:223], off
	s_barrier
	s_waitcnt lgkmcnt(0)
	s_waitcnt lgkmcnt(0)
	v_mfma_f32_16x16x32_bf16 v[118:121], v[206:209], v[170:173], v[118:121]
	v_mfma_f32_16x16x32_bf16 v[110:113], v[214:217], v[170:173], v[110:113]
	v_mfma_f32_16x16x32_bf16 v[102:105], v[206:209], v[182:185], v[102:105]
	v_mfma_f32_16x16x32_bf16 v[94:97], v[214:217], v[182:185], v[94:97]
	v_mfma_f32_16x16x32_bf16 v[86:89], v[206:209], v[190:193], v[86:89]
	v_mfma_f32_16x16x32_bf16 v[78:81], v[214:217], v[190:193], v[78:81]
	v_mfma_f32_16x16x32_bf16 v[70:73], v[206:209], v[198:201], v[70:73]
	v_mfma_f32_16x16x32_bf16 v[66:69], v[214:217], v[198:201], v[66:69]
	v_mfma_f32_16x16x32_bf16 v[118:121], v[210:213], v[174:177], v[118:121]
	v_mfma_f32_16x16x32_bf16 v[110:113], v[218:221], v[174:177], v[110:113]
	v_mfma_f32_16x16x32_bf16 v[102:105], v[210:213], v[186:189], v[102:105]
	v_mfma_f32_16x16x32_bf16 v[94:97], v[218:221], v[186:189], v[94:97]
	v_mfma_f32_16x16x32_bf16 v[86:89], v[210:213], v[194:197], v[86:89]
	v_mfma_f32_16x16x32_bf16 v[78:81], v[218:221], v[194:197], v[78:81]
	v_mfma_f32_16x16x32_bf16 v[70:73], v[210:213], v[202:205], v[70:73]
	v_mfma_f32_16x16x32_bf16 v[66:69], v[218:221], v[202:205], v[66:69]
	s_mov_b32 m0, s31
	v_lshl_add_u64 v[222:223], v[228:229], 0, s[2:3]
	s_barrier
	ds_read_b128 v[170:173], v156 offset:49152
	ds_read_b128 v[174:177], v156 offset:50176
	ds_read_b128 v[182:185], v156 offset:51200
	ds_read_b128 v[186:189], v156 offset:52224
	ds_read_b128 v[190:193], v156 offset:53248
	ds_read_b128 v[194:197], v156 offset:54272
	ds_read_b128 v[198:201], v156 offset:55296
	ds_read_b128 v[202:205], v156 offset:56320
	global_load_lds_dwordx4 v[222:223], off
	v_lshl_add_u64 v[222:223], v[230:231], 0, s[2:3]
	s_mov_b32 m0, s33
	s_nop 0
	global_load_lds_dwordx4 v[222:223], off
	s_barrier
	s_waitcnt lgkmcnt(0)
	s_waitcnt lgkmcnt(0)
	v_mfma_f32_16x16x32_bf16 v[62:65], v[142:145], v[170:173], v[62:65]
	v_mfma_f32_16x16x32_bf16 v[58:61], v[162:165], v[170:173], v[58:61]
	v_mfma_f32_16x16x32_bf16 v[50:53], v[142:145], v[182:185], v[50:53]
	v_mfma_f32_16x16x32_bf16 v[42:45], v[162:165], v[182:185], v[42:45]
	v_mfma_f32_16x16x32_bf16 v[34:37], v[142:145], v[190:193], v[34:37]
	v_mfma_f32_16x16x32_bf16 v[26:29], v[162:165], v[190:193], v[26:29]
	v_mfma_f32_16x16x32_bf16 v[18:21], v[142:145], v[198:201], v[18:21]
	v_mfma_f32_16x16x32_bf16 v[10:13], v[162:165], v[198:201], v[10:13]
	v_mfma_f32_16x16x32_bf16 v[62:65], v[158:161], v[174:177], v[62:65]
	v_mfma_f32_16x16x32_bf16 v[58:61], v[166:169], v[174:177], v[58:61]
	v_mfma_f32_16x16x32_bf16 v[50:53], v[158:161], v[186:189], v[50:53]
	v_mfma_f32_16x16x32_bf16 v[42:45], v[166:169], v[186:189], v[42:45]
	v_mfma_f32_16x16x32_bf16 v[34:37], v[158:161], v[194:197], v[34:37]
	v_mfma_f32_16x16x32_bf16 v[26:29], v[166:169], v[194:197], v[26:29]
	v_mfma_f32_16x16x32_bf16 v[18:21], v[158:161], v[202:205], v[18:21]
	v_mfma_f32_16x16x32_bf16 v[10:13], v[166:169], v[202:205], v[10:13]
	s_barrier
	s_add_u32 s18, s18, 0x40080
	s_addc_u32 s19, s19, 0
	s_add_i32 s20, s20, s25
	v_lshl_add_u64 v[142:143], s[18:19], 0, v[132:133]
	s_mov_b32 m0, s20
	s_nop 0
	global_load_lds_dwordx4 v[142:143], off
	v_lshl_add_u64 v[142:143], s[18:19], 0, v[136:137]
	s_add_i32 m0, s20, 0x2000
	s_nop 0
	global_load_lds_dwordx4 v[142:143], off
	s_waitcnt vmcnt(6)
	s_barrier
	v_mfma_f32_16x16x32_bf16 v[54:57], v[206:209], v[170:173], v[54:57]
	v_mfma_f32_16x16x32_bf16 v[46:49], v[214:217], v[170:173], v[46:49]
	v_mfma_f32_16x16x32_bf16 v[38:41], v[206:209], v[182:185], v[38:41]
	v_mfma_f32_16x16x32_bf16 v[30:33], v[214:217], v[182:185], v[30:33]
	v_mfma_f32_16x16x32_bf16 v[22:25], v[206:209], v[190:193], v[22:25]
	v_mfma_f32_16x16x32_bf16 v[14:17], v[214:217], v[190:193], v[14:17]
	v_mfma_f32_16x16x32_bf16 v[6:9], v[206:209], v[198:201], v[6:9]
	v_mfma_f32_16x16x32_bf16 v[2:5], v[214:217], v[198:201], v[2:5]
	v_mfma_f32_16x16x32_bf16 v[54:57], v[210:213], v[174:177], v[54:57]
	v_mfma_f32_16x16x32_bf16 v[46:49], v[218:221], v[174:177], v[46:49]
	v_mfma_f32_16x16x32_bf16 v[38:41], v[210:213], v[186:189], v[38:41]
	v_mfma_f32_16x16x32_bf16 v[30:33], v[218:221], v[186:189], v[30:33]
	v_mfma_f32_16x16x32_bf16 v[22:25], v[210:213], v[194:197], v[22:25]
	v_mfma_f32_16x16x32_bf16 v[14:17], v[218:221], v[194:197], v[14:17]
	v_mfma_f32_16x16x32_bf16 v[6:9], v[210:213], v[202:205], v[6:9]
	v_mfma_f32_16x16x32_bf16 v[2:5], v[218:221], v[202:205], v[2:5]
	s_add_i32 s44, s44, 2
	s_add_u32 s16, s16, 0x100
	s_addc_u32 s17, s17, 0
	s_add_u32 s42, s42, 0x100
	s_addc_u32 s43, s43, 0
	s_cmp_gt_u32 s44, 13
	s_barrier
	s_cbranch_scc0 .LBB0_3964
	v_lshl_add_u32 v144, s14, 8, v152
	v_lshl_or_b32 v142, s15, 8, v154
	v_cmp_gt_i32_e32 vcc, s38, v144
	v_ashrrev_i32_e32 v143, 31, v142
	s_and_saveexec_b64 s[14:15], vcc
	s_cbranch_execz .LBB0_3967
	s_load_dwordx16 s[40:55], s[78:79], 0x1e0
	v_ashrrev_i32_e32 v145, 31, v144
	v_lshlrev_b64 v[158:159], 9, v[144:145]
	v_cvt_pk_bf16_f32 v126, v126, v127
	v_cvt_pk_bf16_f32 v127, v128, v129
	v_cvt_pk_bf16_f32 v128, v122, v123
	s_waitcnt lgkmcnt(0)
	v_lshl_add_u64 v[122:123], s[44:45], 0, v[158:159]
	v_lshl_add_u64 v[122:123], v[142:143], 1, v[122:123]
	v_cvt_pk_bf16_f32 v129, v124, v125
	global_store_dwordx4 v[122:123], v[126:129], off
	v_cvt_pk_bf16_f32 v118, v118, v119
	v_cvt_pk_bf16_f32 v119, v120, v121
	v_cvt_pk_bf16_f32 v120, v110, v111
	v_cvt_pk_bf16_f32 v121, v112, v113
	global_store_dwordx4 v[122:123], v[118:121], off offset:256

.LBB0_4002:
	ds_read_b128 v[142:145], v1
	ds_read_b128 v[154:157], v1 offset:1024
	ds_read_b128 v[160:163], v1 offset:2048
	ds_read_b128 v[164:167], v1 offset:3072
	s_add_u32 s22, s20, 0xfffc0080
	s_addc_u32 s23, s21, -1
	s_cmp_eq_u32 s49, 12
	s_cselect_b32 s25, s13, s23
	s_cselect_b32 s24, s45, s22
	s_cselect_b32 s23, s11, s48
	s_cselect_b32 s22, s46, s47
	v_lshl_add_u64 v[176:177], s[20:21], 0, v[138:139]
	s_add_i32 m0, s33, 0xc000
	ds_read_b128 v[168:171], v146
	ds_read_b128 v[172:175], v146 offset:1024
	ds_read_b128 v[182:185], v146 offset:2048
	ds_read_b128 v[186:189], v146 offset:3072
	ds_read_b128 v[190:193], v146 offset:4096
	ds_read_b128 v[194:197], v146 offset:5120
	ds_read_b128 v[198:201], v146 offset:6144
	ds_read_b128 v[202:205], v146 offset:7168
	global_load_lds_dwordx4 v[176:177], off
	v_lshl_add_u64 v[176:177], s[20:21], 0, v[140:141]
	s_add_i32 m0, s33, 0xe000
	s_nop 0
	global_load_lds_dwordx4 v[176:177], off
	s_waitcnt lgkmcnt(8)
	s_barrier
	s_waitcnt lgkmcnt(0)
	s_waitcnt lgkmcnt(0)
	v_mfma_f32_16x16x32_bf16 v[126:129], v[142:145], v[168:171], v[126:129]
	v_mfma_f32_16x16x32_bf16 v[122:125], v[160:163], v[168:171], v[122:125]
	v_mfma_f32_16x16x32_bf16 v[114:117], v[142:145], v[182:185], v[114:117]
	v_mfma_f32_16x16x32_bf16 v[106:109], v[160:163], v[182:185], v[106:109]
	v_mfma_f32_16x16x32_bf16 v[98:101], v[142:145], v[190:193], v[98:101]
	v_mfma_f32_16x16x32_bf16 v[90:93], v[160:163], v[190:193], v[90:93]
	v_mfma_f32_16x16x32_bf16 v[82:85], v[142:145], v[198:201], v[82:85]
	v_mfma_f32_16x16x32_bf16 v[74:77], v[160:163], v[198:201], v[74:77]
	v_mfma_f32_16x16x32_bf16 v[126:129], v[154:157], v[172:175], v[126:129]
	v_mfma_f32_16x16x32_bf16 v[122:125], v[164:167], v[172:175], v[122:125]
	v_mfma_f32_16x16x32_bf16 v[114:117], v[154:157], v[186:189], v[114:117]
	v_mfma_f32_16x16x32_bf16 v[106:109], v[164:167], v[186:189], v[106:109]
	v_mfma_f32_16x16x32_bf16 v[98:101], v[154:157], v[194:197], v[98:101]
	v_mfma_f32_16x16x32_bf16 v[90:93], v[164:167], v[194:197], v[90:93]
	v_mfma_f32_16x16x32_bf16 v[82:85], v[154:157], v[202:205], v[82:85]
	v_mfma_f32_16x16x32_bf16 v[74:77], v[164:167], v[202:205], v[74:77]
	s_barrier
	s_add_i32 s50, s41, s31
	v_lshl_add_u64 v[176:177], s[22:23], 0, v[132:133]
	s_mov_b32 m0, s50
	ds_read_b128 v[206:209], v147
	ds_read_b128 v[210:213], v147 offset:1024
	ds_read_b128 v[214:217], v147 offset:2048
	ds_read_b128 v[218:221], v147 offset:3072
	global_load_lds_dwordx4 v[176:177], off
	v_lshl_add_u64 v[222:223], s[22:23], 0, v[136:137]
	s_add_i32 m0, s50, 0x2000
	s_nop 0
	global_load_lds_dwordx4 v[222:223], off
	s_barrier
	s_waitcnt lgkmcnt(0)
	s_waitcnt lgkmcnt(0)
	v_mfma_f32_16x16x32_bf16 v[118:121], v[206:209], v[168:171], v[118:121]
	v_mfma_f32_16x16x32_bf16 v[110:113], v[214:217], v[168:171], v[110:113]
	v_mfma_f32_16x16x32_bf16 v[102:105], v[206:209], v[182:185], v[102:105]
	v_mfma_f32_16x16x32_bf16 v[94:97], v[214:217], v[182:185], v[94:97]
	v_mfma_f32_16x16x32_bf16 v[86:89], v[206:209], v[190:193], v[86:89]
	v_mfma_f32_16x16x32_bf16 v[78:81], v[214:217], v[190:193], v[78:81]
	v_mfma_f32_16x16x32_bf16 v[70:73], v[206:209], v[198:201], v[70:73]
	v_mfma_f32_16x16x32_bf16 v[66:69], v[214:217], v[198:201], v[66:69]
	v_mfma_f32_16x16x32_bf16 v[118:121], v[210:213], v[172:175], v[118:121]
	v_mfma_f32_16x16x32_bf16 v[110:113], v[218:221], v[172:175], v[110:113]
	v_mfma_f32_16x16x32_bf16 v[102:105], v[210:213], v[186:189], v[102:105]
	v_mfma_f32_16x16x32_bf16 v[94:97], v[218:221], v[186:189], v[94:97]
	v_mfma_f32_16x16x32_bf16 v[86:89], v[210:213], v[194:197], v[86:89]
	v_mfma_f32_16x16x32_bf16 v[78:81], v[218:221], v[194:197], v[78:81]
	v_mfma_f32_16x16x32_bf16 v[70:73], v[210:213], v[202:205], v[70:73]
	v_mfma_f32_16x16x32_bf16 v[66:69], v[218:221], v[202:205], v[66:69]
	s_mov_b32 m0, s33
	v_lshl_add_u64 v[224:225], s[24:25], 0, v[130:131]
	s_barrier
	ds_read_b128 v[168:171], v146 offset:16384
	ds_read_b128 v[172:175], v146 offset:17408
	ds_read_b128 v[182:185], v146 offset:18432
	ds_read_b128 v[186:189], v146 offset:19456
	ds_read_b128 v[190:193], v146 offset:20480
	ds_read_b128 v[194:197], v146 offset:21504
	ds_read_b128 v[198:201], v146 offset:22528
	ds_read_b128 v[202:205], v146 offset:23552
	global_load_lds_dwordx4 v[224:225], off
	v_lshl_add_u64 v[228:229], s[24:25], 0, v[134:135]
	s_mov_b32 m0, s34
	s_nop 0
	global_load_lds_dwordx4 v[228:229], off
	s_barrier
	s_waitcnt lgkmcnt(0)
	s_waitcnt lgkmcnt(0)
	v_mfma_f32_16x16x32_bf16 v[62:65], v[142:145], v[168:171], v[62:65]
	v_mfma_f32_16x16x32_bf16 v[58:61], v[160:163], v[168:171], v[58:61]
	v_mfma_f32_16x16x32_bf16 v[50:53], v[142:145], v[182:185], v[50:53]
	v_mfma_f32_16x16x32_bf16 v[42:45], v[160:163], v[182:185], v[42:45]
	v_mfma_f32_16x16x32_bf16 v[34:37], v[142:145], v[190:193], v[34:37]
	v_mfma_f32_16x16x32_bf16 v[26:29], v[160:163], v[190:193], v[26:29]
	v_mfma_f32_16x16x32_bf16 v[18:21], v[142:145], v[198:201], v[18:21]
	v_mfma_f32_16x16x32_bf16 v[10:13], v[160:163], v[198:201], v[10:13]
	v_mfma_f32_16x16x32_bf16 v[62:65], v[154:157], v[172:175], v[62:65]
	v_mfma_f32_16x16x32_bf16 v[58:61], v[164:167], v[172:175], v[58:61]
	v_mfma_f32_16x16x32_bf16 v[50:53], v[154:157], v[186:189], v[50:53]
	v_mfma_f32_16x16x32_bf16 v[42:45], v[164:167], v[186:189], v[42:45]
	v_mfma_f32_16x16x32_bf16 v[34:37], v[154:157], v[194:197], v[34:37]
	v_mfma_f32_16x16x32_bf16 v[26:29], v[164:167], v[194:197], v[26:29]
	v_mfma_f32_16x16x32_bf16 v[18:21], v[154:157], v[202:205], v[18:21]
	v_mfma_f32_16x16x32_bf16 v[10:13], v[164:167], v[202:205], v[10:13]
	s_barrier
	s_add_u32 s50, s22, 0x40000
	s_addc_u32 s51, s23, 0
	s_add_i32 s52, s42, s31
	v_lshl_add_u64 v[142:143], s[50:51], 0, v[132:133]
	s_mov_b32 m0, s52
	s_nop 0
	global_load_lds_dwordx4 v[142:143], off
	v_lshl_add_u64 v[142:143], s[50:51], 0, v[136:137]
	s_add_i32 m0, s52, 0x2000
	s_nop 0
	global_load_lds_dwordx4 v[142:143], off
	s_waitcnt vmcnt(6)
	s_barrier
	v_mfma_f32_16x16x32_bf16 v[54:57], v[206:209], v[168:171], v[54:57]
	v_mfma_f32_16x16x32_bf16 v[46:49], v[214:217], v[168:171], v[46:49]
	v_mfma_f32_16x16x32_bf16 v[38:41], v[206:209], v[182:185], v[38:41]
	v_mfma_f32_16x16x32_bf16 v[30:33], v[214:217], v[182:185], v[30:33]
	v_mfma_f32_16x16x32_bf16 v[22:25], v[206:209], v[190:193], v[22:25]
	v_mfma_f32_16x16x32_bf16 v[14:17], v[214:217], v[190:193], v[14:17]
	v_mfma_f32_16x16x32_bf16 v[6:9], v[206:209], v[198:201], v[6:9]
	v_mfma_f32_16x16x32_bf16 v[2:5], v[214:217], v[198:201], v[2:5]
	v_mfma_f32_16x16x32_bf16 v[54:57], v[210:213], v[172:175], v[54:57]
	v_mfma_f32_16x16x32_bf16 v[46:49], v[218:221], v[172:175], v[46:49]
	v_mfma_f32_16x16x32_bf16 v[38:41], v[210:213], v[186:189], v[38:41]
	v_mfma_f32_16x16x32_bf16 v[30:33], v[218:221], v[186:189], v[30:33]
	v_mfma_f32_16x16x32_bf16 v[22:25], v[210:213], v[194:197], v[22:25]
	v_mfma_f32_16x16x32_bf16 v[14:17], v[218:221], v[194:197], v[14:17]
	v_mfma_f32_16x16x32_bf16 v[6:9], v[210:213], v[202:205], v[6:9]
	v_mfma_f32_16x16x32_bf16 v[2:5], v[218:221], v[202:205], v[2:5]
	s_add_i32 s50, 0, 0x18000
	v_add_u32_e32 v148, s50, v150
	s_barrier
	ds_read_b128 v[142:145], v148
	ds_read_b128 v[154:157], v148 offset:1024
	ds_read_b128 v[160:163], v148 offset:2048
	ds_read_b128 v[164:167], v148 offset:3072
	s_add_u32 s24, s24, 0x40000
	s_addc_u32 s25, s25, 0
	s_mov_b32 m0, s35
	v_lshl_add_u64 v[206:207], s[24:25], 0, v[130:131]
	ds_read_b128 v[168:171], v146 offset:32768
	ds_read_b128 v[172:175], v146 offset:33792
	ds_read_b128 v[182:185], v146 offset:34816
	ds_read_b128 v[186:189], v146 offset:35840
	ds_read_b128 v[190:193], v146 offset:36864
	ds_read_b128 v[194:197], v146 offset:37888
	ds_read_b128 v[198:201], v146 offset:38912
	ds_read_b128 v[202:205], v146 offset:39936
	global_load_lds_dwordx4 v[206:207], off
	v_lshl_add_u64 v[206:207], s[24:25], 0, v[134:135]
	s_mov_b32 m0, s36
	s_nop 0
	global_load_lds_dwordx4 v[206:207], off
	s_waitcnt lgkmcnt(8)
	s_barrier
	s_waitcnt lgkmcnt(0)
	s_waitcnt lgkmcnt(0)
	v_mfma_f32_16x16x32_bf16 v[126:129], v[142:145], v[168:171], v[126:129]
	v_mfma_f32_16x16x32_bf16 v[122:125], v[160:163], v[168:171], v[122:125]
	v_mfma_f32_16x16x32_bf16 v[114:117], v[142:145], v[182:185], v[114:117]
	v_mfma_f32_16x16x32_bf16 v[106:109], v[160:163], v[182:185], v[106:109]
	v_mfma_f32_16x16x32_bf16 v[98:101], v[142:145], v[190:193], v[98:101]
	v_mfma_f32_16x16x32_bf16 v[90:93], v[160:163], v[190:193], v[90:93]
	v_mfma_f32_16x16x32_bf16 v[82:85], v[142:145], v[198:201], v[82:85]
	v_mfma_f32_16x16x32_bf16 v[74:77], v[160:163], v[198:201], v[74:77]
	v_mfma_f32_16x16x32_bf16 v[126:129], v[154:157], v[172:175], v[126:129]
	v_mfma_f32_16x16x32_bf16 v[122:125], v[164:167], v[172:175], v[122:125]
	v_mfma_f32_16x16x32_bf16 v[114:117], v[154:157], v[186:189], v[114:117]
	v_mfma_f32_16x16x32_bf16 v[106:109], v[164:167], v[186:189], v[106:109]
	v_mfma_f32_16x16x32_bf16 v[98:101], v[154:157], v[194:197], v[98:101]
	v_mfma_f32_16x16x32_bf16 v[90:93], v[164:167], v[194:197], v[90:93]
	v_mfma_f32_16x16x32_bf16 v[82:85], v[154:157], v[202:205], v[82:85]
	v_mfma_f32_16x16x32_bf16 v[74:77], v[164:167], v[202:205], v[74:77]
	s_barrier
	s_add_i32 s24, 0, 0x1c000
	s_add_i32 s25, s50, s31
	v_add_u32_e32 v148, s24, v150
	v_lshl_add_u64 v[176:177], v[176:177], 0, s[6:7]
	s_mov_b32 m0, s25
	ds_read_b128 v[206:209], v148
	ds_read_b128 v[210:213], v148 offset:1024
	ds_read_b128 v[214:217], v148 offset:2048
	ds_read_b128 v[218:221], v148 offset:3072
	global_load_lds_dwordx4 v[176:177], off
	v_lshl_add_u64 v[176:177], v[222:223], 0, s[6:7]
	s_add_i32 m0, s25, 0x2000
	s_nop 0
	global_load_lds_dwordx4 v[176:177], off
	s_barrier
	s_waitcnt lgkmcnt(0)
	s_waitcnt lgkmcnt(0)
	v_mfma_f32_16x16x32_bf16 v[118:121], v[206:209], v[168:171], v[118:121]
	v_mfma_f32_16x16x32_bf16 v[110:113], v[214:217], v[168:171], v[110:113]
	v_mfma_f32_16x16x32_bf16 v[102:105], v[206:209], v[182:185], v[102:105]
	v_mfma_f32_16x16x32_bf16 v[94:97], v[214:217], v[182:185], v[94:97]
	v_mfma_f32_16x16x32_bf16 v[86:89], v[206:209], v[190:193], v[86:89]
	v_mfma_f32_16x16x32_bf16 v[78:81], v[214:217], v[190:193], v[78:81]
	v_mfma_f32_16x16x32_bf16 v[70:73], v[206:209], v[198:201], v[70:73]
	v_mfma_f32_16x16x32_bf16 v[66:69], v[214:217], v[198:201], v[66:69]
	v_mfma_f32_16x16x32_bf16 v[118:121], v[210:213], v[172:175], v[118:121]
	v_mfma_f32_16x16x32_bf16 v[110:113], v[218:221], v[172:175], v[110:113]
	v_mfma_f32_16x16x32_bf16 v[102:105], v[210:213], v[186:189], v[102:105]
	v_mfma_f32_16x16x32_bf16 v[94:97], v[218:221], v[186:189], v[94:97]
	v_mfma_f32_16x16x32_bf16 v[86:89], v[210:213], v[194:197], v[86:89]
	v_mfma_f32_16x16x32_bf16 v[78:81], v[218:221], v[194:197], v[78:81]
	v_mfma_f32_16x16x32_bf16 v[70:73], v[210:213], v[202:205], v[70:73]
	v_mfma_f32_16x16x32_bf16 v[66:69], v[218:221], v[202:205], v[66:69]
	s_mov_b32 m0, s37
	v_lshl_add_u64 v[176:177], v[224:225], 0, s[6:7]
	s_barrier
	ds_read_b128 v[168:171], v146 offset:49152
	ds_read_b128 v[172:175], v146 offset:50176
	ds_read_b128 v[182:185], v146 offset:51200
	ds_read_b128 v[186:189], v146 offset:52224
	ds_read_b128 v[190:193], v146 offset:53248
	ds_read_b128 v[194:197], v146 offset:54272
	ds_read_b128 v[198:201], v146 offset:55296
	ds_read_b128 v[202:205], v146 offset:56320
	global_load_lds_dwordx4 v[176:177], off
	v_lshl_add_u64 v[176:177], v[228:229], 0, s[6:7]
	s_mov_b32 m0, s38
	s_nop 0
	global_load_lds_dwordx4 v[176:177], off
	s_barrier
	s_waitcnt lgkmcnt(0)
	s_waitcnt lgkmcnt(0)
	v_mfma_f32_16x16x32_bf16 v[62:65], v[142:145], v[168:171], v[62:65]
	v_mfma_f32_16x16x32_bf16 v[58:61], v[160:163], v[168:171], v[58:61]
	v_mfma_f32_16x16x32_bf16 v[50:53], v[142:145], v[182:185], v[50:53]
	v_mfma_f32_16x16x32_bf16 v[42:45], v[160:163], v[182:185], v[42:45]
	v_mfma_f32_16x16x32_bf16 v[34:37], v[142:145], v[190:193], v[34:37]
	v_mfma_f32_16x16x32_bf16 v[26:29], v[160:163], v[190:193], v[26:29]
	v_mfma_f32_16x16x32_bf16 v[18:21], v[142:145], v[198:201], v[18:21]
	v_mfma_f32_16x16x32_bf16 v[10:13], v[160:163], v[198:201], v[10:13]
	v_mfma_f32_16x16x32_bf16 v[62:65], v[154:157], v[172:175], v[62:65]
	v_mfma_f32_16x16x32_bf16 v[58:61], v[164:167], v[172:175], v[58:61]
	v_mfma_f32_16x16x32_bf16 v[50:53], v[154:157], v[186:189], v[50:53]
	v_mfma_f32_16x16x32_bf16 v[42:45], v[164:167], v[186:189], v[42:45]
	v_mfma_f32_16x16x32_bf16 v[34:37], v[154:157], v[194:197], v[34:37]
	v_mfma_f32_16x16x32_bf16 v[26:29], v[164:167], v[194:197], v[26:29]
	v_mfma_f32_16x16x32_bf16 v[18:21], v[154:157], v[202:205], v[18:21]
	v_mfma_f32_16x16x32_bf16 v[10:13], v[164:167], v[202:205], v[10:13]
	s_barrier
	s_add_u32 s22, s22, 0x40080
	s_addc_u32 s23, s23, 0
	s_add_i32 s24, s24, s31
	v_lshl_add_u64 v[142:143], s[22:23], 0, v[132:133]
	s_mov_b32 m0, s24
	s_nop 0
	global_load_lds_dwordx4 v[142:143], off
	v_lshl_add_u64 v[142:143], s[22:23], 0, v[136:137]
	s_add_i32 m0, s24, 0x2000
	s_nop 0
	global_load_lds_dwordx4 v[142:143], off
	s_waitcnt vmcnt(6)
	s_barrier
	v_mfma_f32_16x16x32_bf16 v[54:57], v[206:209], v[168:171], v[54:57]
	v_mfma_f32_16x16x32_bf16 v[46:49], v[214:217], v[168:171], v[46:49]
	v_mfma_f32_16x16x32_bf16 v[38:41], v[206:209], v[182:185], v[38:41]
	v_mfma_f32_16x16x32_bf16 v[30:33], v[214:217], v[182:185], v[30:33]
	v_mfma_f32_16x16x32_bf16 v[22:25], v[206:209], v[190:193], v[22:25]
	v_mfma_f32_16x16x32_bf16 v[14:17], v[214:217], v[190:193], v[14:17]
	v_mfma_f32_16x16x32_bf16 v[6:9], v[206:209], v[198:201], v[6:9]
	v_mfma_f32_16x16x32_bf16 v[2:5], v[214:217], v[198:201], v[2:5]
	v_mfma_f32_16x16x32_bf16 v[54:57], v[210:213], v[172:175], v[54:57]
	v_mfma_f32_16x16x32_bf16 v[46:49], v[218:221], v[172:175], v[46:49]
	v_mfma_f32_16x16x32_bf16 v[38:41], v[210:213], v[186:189], v[38:41]
	v_mfma_f32_16x16x32_bf16 v[30:33], v[218:221], v[186:189], v[30:33]
	v_mfma_f32_16x16x32_bf16 v[22:25], v[210:213], v[194:197], v[22:25]
	v_mfma_f32_16x16x32_bf16 v[14:17], v[218:221], v[194:197], v[14:17]
	v_mfma_f32_16x16x32_bf16 v[6:9], v[210:213], v[202:205], v[6:9]
	v_mfma_f32_16x16x32_bf16 v[2:5], v[218:221], v[202:205], v[2:5]
	s_add_i32 s49, s49, 2
	s_add_u32 s20, s20, 0x100
	s_addc_u32 s21, s21, 0
	s_add_u32 s47, s47, 0x100
	s_addc_u32 s48, s48, 0
	s_cmp_gt_u32 s49, 13
	s_barrier
	s_cbranch_scc0 .LBB0_4002
	v_lshl_add_u32 v144, s18, 8, v152
	v_lshl_or_b32 v142, s19, 8, v149
	v_cmp_gt_i32_e32 vcc, s43, v144
	v_ashrrev_i32_e32 v143, 31, v142
	s_and_saveexec_b64 s[18:19], vcc
	s_cbranch_execz .LBB0_4005
	v_ashrrev_i32_e32 v145, 31, v144
	v_lshlrev_b64 v[154:155], 9, v[144:145]
	v_cvt_pk_bf16_f32 v126, v126, v127
	v_cvt_pk_bf16_f32 v127, v128, v129
	v_cvt_pk_bf16_f32 v128, v122, v123
	v_lshl_add_u64 v[122:123], s[4:5], 0, v[154:155]
	v_lshl_add_u64 v[122:123], v[142:143], 1, v[122:123]
	v_cvt_pk_bf16_f32 v129, v124, v125
	global_store_dwordx4 v[122:123], v[126:129], off
	v_cvt_pk_bf16_f32 v118, v118, v119
	v_cvt_pk_bf16_f32 v119, v120, v121
	v_cvt_pk_bf16_f32 v120, v110, v111
	v_cvt_pk_bf16_f32 v121, v112, v113
	global_store_dwordx4 v[122:123], v[118:121], off offset:256

.LBB0_4568:
	v_add_u32_e32 v149, s44, v147
	s_add_u32 s26, s0, s24
	ds_read_b128 v[150:153], v149
	ds_read_b128 v[154:157], v149 offset:1024
	ds_read_b128 v[158:161], v149 offset:2048
	ds_read_b128 v[162:165], v149 offset:3072
	s_addc_u32 s27, s1, s25
	s_add_u32 s26, s26, 0x100
	s_addc_u32 s27, s27, 0
	s_add_u32 s52, s47, s24
	s_addc_u32 s53, s48, s25
	s_cmpk_eq_i32 s24, 0x700
	s_cselect_b32 s29, s19, s27
	s_cselect_b32 s28, s49, s26
	s_cselect_b32 s27, s17, s53
	s_cselect_b32 s26, s50, s52
	v_lshl_add_u64 v[202:203], v[142:143], 0, s[24:25]
	s_add_i32 m0, s36, 0xc000
	ds_read_b128 v[166:169], v148
	ds_read_b128 v[170:173], v148 offset:1024
	ds_read_b128 v[174:177], v148 offset:2048
	ds_read_b128 v[182:185], v148 offset:3072
	ds_read_b128 v[186:189], v148 offset:4096
	ds_read_b128 v[190:193], v148 offset:5120
	ds_read_b128 v[194:197], v148 offset:6144
	ds_read_b128 v[198:201], v148 offset:7168
	global_load_lds_dwordx4 v[202:203], off
	v_lshl_add_u64 v[202:203], v[144:145], 0, s[24:25]
	s_add_i32 m0, s36, 0xe000
	s_nop 0
	global_load_lds_dwordx4 v[202:203], off
	s_waitcnt lgkmcnt(8)
	s_barrier
	s_waitcnt lgkmcnt(0)
	s_waitcnt lgkmcnt(0)
	v_mfma_f32_16x16x32_bf16 v[126:129], v[150:153], v[166:169], v[126:129]
	v_mfma_f32_16x16x32_bf16 v[122:125], v[158:161], v[166:169], v[122:125]
	v_mfma_f32_16x16x32_bf16 v[110:113], v[150:153], v[174:177], v[110:113]
	v_mfma_f32_16x16x32_bf16 v[106:109], v[158:161], v[174:177], v[106:109]
	v_mfma_f32_16x16x32_bf16 v[94:97], v[150:153], v[186:189], v[94:97]
	v_mfma_f32_16x16x32_bf16 v[90:93], v[158:161], v[186:189], v[90:93]
	v_mfma_f32_16x16x32_bf16 v[78:81], v[150:153], v[194:197], v[78:81]
	v_mfma_f32_16x16x32_bf16 v[74:77], v[158:161], v[194:197], v[74:77]
	v_mfma_f32_16x16x32_bf16 v[126:129], v[154:157], v[170:173], v[126:129]
	v_mfma_f32_16x16x32_bf16 v[122:125], v[162:165], v[170:173], v[122:125]
	v_mfma_f32_16x16x32_bf16 v[110:113], v[154:157], v[182:185], v[110:113]
	v_mfma_f32_16x16x32_bf16 v[106:109], v[162:165], v[182:185], v[106:109]
	v_mfma_f32_16x16x32_bf16 v[94:97], v[154:157], v[190:193], v[94:97]
	v_mfma_f32_16x16x32_bf16 v[90:93], v[162:165], v[190:193], v[90:93]
	v_mfma_f32_16x16x32_bf16 v[78:81], v[154:157], v[198:201], v[78:81]
	v_mfma_f32_16x16x32_bf16 v[74:77], v[162:165], v[198:201], v[74:77]
	s_barrier
	s_add_i32 s52, s44, s35
	v_add_u32_e32 v149, s45, v147
	v_lshl_add_u64 v[218:219], s[26:27], 0, v[130:131]
	s_mov_b32 m0, s52
	ds_read_b128 v[202:205], v149
	ds_read_b128 v[206:209], v149 offset:1024
	ds_read_b128 v[210:213], v149 offset:2048
	ds_read_b128 v[214:217], v149 offset:3072
	global_load_lds_dwordx4 v[218:219], off
	v_lshl_add_u64 v[220:221], s[26:27], 0, v[132:133]
	s_add_i32 m0, s52, 0x2000
	s_nop 0
	global_load_lds_dwordx4 v[220:221], off
	s_barrier
	s_waitcnt lgkmcnt(0)
	s_waitcnt lgkmcnt(0)
	v_mfma_f32_16x16x32_bf16 v[118:121], v[202:205], v[166:169], v[118:121]
	v_mfma_f32_16x16x32_bf16 v[114:117], v[210:213], v[166:169], v[114:117]
	v_mfma_f32_16x16x32_bf16 v[102:105], v[202:205], v[174:177], v[102:105]
	v_mfma_f32_16x16x32_bf16 v[98:101], v[210:213], v[174:177], v[98:101]
	v_mfma_f32_16x16x32_bf16 v[86:89], v[202:205], v[186:189], v[86:89]
	v_mfma_f32_16x16x32_bf16 v[82:85], v[210:213], v[186:189], v[82:85]
	v_mfma_f32_16x16x32_bf16 v[70:73], v[202:205], v[194:197], v[70:73]
	v_mfma_f32_16x16x32_bf16 v[66:69], v[210:213], v[194:197], v[66:69]
	v_mfma_f32_16x16x32_bf16 v[118:121], v[206:209], v[170:173], v[118:121]
	v_mfma_f32_16x16x32_bf16 v[114:117], v[214:217], v[170:173], v[114:117]
	v_mfma_f32_16x16x32_bf16 v[102:105], v[206:209], v[182:185], v[102:105]
	v_mfma_f32_16x16x32_bf16 v[98:101], v[214:217], v[182:185], v[98:101]
	v_mfma_f32_16x16x32_bf16 v[86:89], v[206:209], v[190:193], v[86:89]
	v_mfma_f32_16x16x32_bf16 v[82:85], v[214:217], v[190:193], v[82:85]
	v_mfma_f32_16x16x32_bf16 v[70:73], v[206:209], v[198:201], v[70:73]
	v_mfma_f32_16x16x32_bf16 v[66:69], v[214:217], v[198:201], v[66:69]
	s_mov_b32 m0, s36
	v_lshl_add_u64 v[222:223], s[28:29], 0, v[130:131]
	s_barrier
	ds_read_b128 v[166:169], v148 offset:16384
	ds_read_b128 v[170:173], v148 offset:17408
	ds_read_b128 v[174:177], v148 offset:18432
	ds_read_b128 v[182:185], v148 offset:19456
	ds_read_b128 v[186:189], v148 offset:20480
	ds_read_b128 v[190:193], v148 offset:21504
	ds_read_b128 v[194:197], v148 offset:22528
	ds_read_b128 v[198:201], v148 offset:23552
	global_load_lds_dwordx4 v[222:223], off
	v_lshl_add_u64 v[224:225], s[28:29], 0, v[132:133]
	s_mov_b32 m0, s37
	s_nop 0
	global_load_lds_dwordx4 v[224:225], off
	s_barrier
	s_waitcnt lgkmcnt(0)
	s_waitcnt lgkmcnt(0)
	v_mfma_f32_16x16x32_bf16 v[62:65], v[150:153], v[166:169], v[62:65]
	v_mfma_f32_16x16x32_bf16 v[58:61], v[158:161], v[166:169], v[58:61]
	v_mfma_f32_16x16x32_bf16 v[46:49], v[150:153], v[174:177], v[46:49]
	v_mfma_f32_16x16x32_bf16 v[42:45], v[158:161], v[174:177], v[42:45]
	v_mfma_f32_16x16x32_bf16 v[30:33], v[150:153], v[186:189], v[30:33]
	v_mfma_f32_16x16x32_bf16 v[26:29], v[158:161], v[186:189], v[26:29]
	v_mfma_f32_16x16x32_bf16 v[14:17], v[150:153], v[194:197], v[14:17]
	v_mfma_f32_16x16x32_bf16 v[10:13], v[158:161], v[194:197], v[10:13]
	v_mfma_f32_16x16x32_bf16 v[62:65], v[154:157], v[170:173], v[62:65]
	v_mfma_f32_16x16x32_bf16 v[58:61], v[162:165], v[170:173], v[58:61]
	v_mfma_f32_16x16x32_bf16 v[46:49], v[154:157], v[182:185], v[46:49]
	v_mfma_f32_16x16x32_bf16 v[42:45], v[162:165], v[182:185], v[42:45]
	v_mfma_f32_16x16x32_bf16 v[30:33], v[154:157], v[190:193], v[30:33]
	v_mfma_f32_16x16x32_bf16 v[26:29], v[162:165], v[190:193], v[26:29]
	v_mfma_f32_16x16x32_bf16 v[14:17], v[154:157], v[198:201], v[14:17]
	v_mfma_f32_16x16x32_bf16 v[10:13], v[162:165], v[198:201], v[10:13]
	s_barrier
	s_add_u32 s52, s26, 0x40000
	s_addc_u32 s53, s27, 0
	s_add_i32 s54, s45, s35
	v_lshl_add_u64 v[150:151], s[52:53], 0, v[130:131]
	s_mov_b32 m0, s54
	s_nop 0
	global_load_lds_dwordx4 v[150:151], off
	v_lshl_add_u64 v[150:151], s[52:53], 0, v[132:133]
	s_add_i32 m0, s54, 0x2000
	s_nop 0
	global_load_lds_dwordx4 v[150:151], off
	s_waitcnt vmcnt(6)
	s_barrier
	v_mfma_f32_16x16x32_bf16 v[54:57], v[202:205], v[166:169], v[54:57]
	v_mfma_f32_16x16x32_bf16 v[50:53], v[210:213], v[166:169], v[50:53]
	v_mfma_f32_16x16x32_bf16 v[38:41], v[202:205], v[174:177], v[38:41]
	v_mfma_f32_16x16x32_bf16 v[34:37], v[210:213], v[174:177], v[34:37]
	v_mfma_f32_16x16x32_bf16 v[22:25], v[202:205], v[186:189], v[22:25]
	v_mfma_f32_16x16x32_bf16 v[18:21], v[210:213], v[186:189], v[18:21]
	v_mfma_f32_16x16x32_bf16 v[6:9], v[202:205], v[194:197], v[6:9]
	v_mfma_f32_16x16x32_bf16 v[2:5], v[210:213], v[194:197], v[2:5]
	v_mfma_f32_16x16x32_bf16 v[54:57], v[206:209], v[170:173], v[54:57]
	v_mfma_f32_16x16x32_bf16 v[50:53], v[214:217], v[170:173], v[50:53]
	v_mfma_f32_16x16x32_bf16 v[38:41], v[206:209], v[182:185], v[38:41]
	v_mfma_f32_16x16x32_bf16 v[34:37], v[214:217], v[182:185], v[34:37]
	v_mfma_f32_16x16x32_bf16 v[22:25], v[206:209], v[190:193], v[22:25]
	v_mfma_f32_16x16x32_bf16 v[18:21], v[214:217], v[190:193], v[18:21]
	v_mfma_f32_16x16x32_bf16 v[6:9], v[206:209], v[198:201], v[6:9]
	v_mfma_f32_16x16x32_bf16 v[2:5], v[214:217], v[198:201], v[2:5]
	s_add_i32 s52, 0, 0x18000
	v_add_u32_e32 v149, s52, v147
	s_barrier
	ds_read_b128 v[150:153], v149
	ds_read_b128 v[154:157], v149 offset:1024
	ds_read_b128 v[158:161], v149 offset:2048
	ds_read_b128 v[162:165], v149 offset:3072
	s_add_u32 s28, s28, 0x40000
	s_addc_u32 s29, s29, 0
	s_mov_b32 m0, s38
	v_lshl_add_u64 v[202:203], s[28:29], 0, v[130:131]
	ds_read_b128 v[166:169], v148 offset:32768
	ds_read_b128 v[170:173], v148 offset:33792
	ds_read_b128 v[174:177], v148 offset:34816
	ds_read_b128 v[182:185], v148 offset:35840
	ds_read_b128 v[186:189], v148 offset:36864
	ds_read_b128 v[190:193], v148 offset:37888
	ds_read_b128 v[194:197], v148 offset:38912
	ds_read_b128 v[198:201], v148 offset:39936
	global_load_lds_dwordx4 v[202:203], off
	v_lshl_add_u64 v[202:203], s[28:29], 0, v[132:133]
	s_mov_b32 m0, s39
	s_nop 0
	global_load_lds_dwordx4 v[202:203], off
	s_waitcnt lgkmcnt(8)
	s_barrier
	s_waitcnt lgkmcnt(0)
	s_waitcnt lgkmcnt(0)
	v_mfma_f32_16x16x32_bf16 v[126:129], v[150:153], v[166:169], v[126:129]
	v_mfma_f32_16x16x32_bf16 v[122:125], v[158:161], v[166:169], v[122:125]
	v_mfma_f32_16x16x32_bf16 v[110:113], v[150:153], v[174:177], v[110:113]
	v_mfma_f32_16x16x32_bf16 v[106:109], v[158:161], v[174:177], v[106:109]
	v_mfma_f32_16x16x32_bf16 v[94:97], v[150:153], v[186:189], v[94:97]
	v_mfma_f32_16x16x32_bf16 v[90:93], v[158:161], v[186:189], v[90:93]
	v_mfma_f32_16x16x32_bf16 v[78:81], v[150:153], v[194:197], v[78:81]
	v_mfma_f32_16x16x32_bf16 v[74:77], v[158:161], v[194:197], v[74:77]
	v_mfma_f32_16x16x32_bf16 v[126:129], v[154:157], v[170:173], v[126:129]
	v_mfma_f32_16x16x32_bf16 v[122:125], v[162:165], v[170:173], v[122:125]
	v_mfma_f32_16x16x32_bf16 v[110:113], v[154:157], v[182:185], v[110:113]
	v_mfma_f32_16x16x32_bf16 v[106:109], v[162:165], v[182:185], v[106:109]
	v_mfma_f32_16x16x32_bf16 v[94:97], v[154:157], v[190:193], v[94:97]
	v_mfma_f32_16x16x32_bf16 v[90:93], v[162:165], v[190:193], v[90:93]
	v_mfma_f32_16x16x32_bf16 v[78:81], v[154:157], v[198:201], v[78:81]
	v_mfma_f32_16x16x32_bf16 v[74:77], v[162:165], v[198:201], v[74:77]
	s_barrier
	s_add_i32 s28, 0, 0x1c000
	s_add_i32 s29, s52, s35
	v_add_u32_e32 v149, s28, v147
	v_lshl_add_u64 v[218:219], v[218:219], 0, s[14:15]
	s_mov_b32 m0, s29
	ds_read_b128 v[202:205], v149
	ds_read_b128 v[206:209], v149 offset:1024
	ds_read_b128 v[210:213], v149 offset:2048
	ds_read_b128 v[214:217], v149 offset:3072
	global_load_lds_dwordx4 v[218:219], off
	v_lshl_add_u64 v[218:219], v[220:221], 0, s[14:15]
	s_add_i32 m0, s29, 0x2000
	s_nop 0
	global_load_lds_dwordx4 v[218:219], off
	s_barrier
	s_waitcnt lgkmcnt(0)
	s_waitcnt lgkmcnt(0)
	v_mfma_f32_16x16x32_bf16 v[118:121], v[202:205], v[166:169], v[118:121]
	v_mfma_f32_16x16x32_bf16 v[114:117], v[210:213], v[166:169], v[114:117]
	v_mfma_f32_16x16x32_bf16 v[102:105], v[202:205], v[174:177], v[102:105]
	v_mfma_f32_16x16x32_bf16 v[98:101], v[210:213], v[174:177], v[98:101]
	v_mfma_f32_16x16x32_bf16 v[86:89], v[202:205], v[186:189], v[86:89]
	v_mfma_f32_16x16x32_bf16 v[82:85], v[210:213], v[186:189], v[82:85]
	v_mfma_f32_16x16x32_bf16 v[70:73], v[202:205], v[194:197], v[70:73]
	v_mfma_f32_16x16x32_bf16 v[66:69], v[210:213], v[194:197], v[66:69]
	v_mfma_f32_16x16x32_bf16 v[118:121], v[206:209], v[170:173], v[118:121]
	v_mfma_f32_16x16x32_bf16 v[114:117], v[214:217], v[170:173], v[114:117]
	v_mfma_f32_16x16x32_bf16 v[102:105], v[206:209], v[182:185], v[102:105]
	v_mfma_f32_16x16x32_bf16 v[98:101], v[214:217], v[182:185], v[98:101]
	v_mfma_f32_16x16x32_bf16 v[86:89], v[206:209], v[190:193], v[86:89]
	v_mfma_f32_16x16x32_bf16 v[82:85], v[214:217], v[190:193], v[82:85]
	v_mfma_f32_16x16x32_bf16 v[70:73], v[206:209], v[198:201], v[70:73]
	v_mfma_f32_16x16x32_bf16 v[66:69], v[214:217], v[198:201], v[66:69]
	s_mov_b32 m0, s42
	v_lshl_add_u64 v[218:219], v[222:223], 0, s[14:15]
	s_barrier
	ds_read_b128 v[166:169], v148 offset:49152
	ds_read_b128 v[170:173], v148 offset:50176
	ds_read_b128 v[174:177], v148 offset:51200
	ds_read_b128 v[182:185], v148 offset:52224
	ds_read_b128 v[186:189], v148 offset:53248
	ds_read_b128 v[190:193], v148 offset:54272
	ds_read_b128 v[194:197], v148 offset:55296
	ds_read_b128 v[198:201], v148 offset:56320
	global_load_lds_dwordx4 v[218:219], off
	v_lshl_add_u64 v[218:219], v[224:225], 0, s[14:15]
	s_mov_b32 m0, s43
	s_nop 0
	global_load_lds_dwordx4 v[218:219], off
	s_barrier
	s_waitcnt lgkmcnt(0)
	s_waitcnt lgkmcnt(0)
	v_mfma_f32_16x16x32_bf16 v[62:65], v[150:153], v[166:169], v[62:65]
	v_mfma_f32_16x16x32_bf16 v[58:61], v[158:161], v[166:169], v[58:61]
	v_mfma_f32_16x16x32_bf16 v[46:49], v[150:153], v[174:177], v[46:49]
	v_mfma_f32_16x16x32_bf16 v[42:45], v[158:161], v[174:177], v[42:45]
	v_mfma_f32_16x16x32_bf16 v[30:33], v[150:153], v[186:189], v[30:33]
	v_mfma_f32_16x16x32_bf16 v[26:29], v[158:161], v[186:189], v[26:29]
	v_mfma_f32_16x16x32_bf16 v[14:17], v[150:153], v[194:197], v[14:17]
	v_mfma_f32_16x16x32_bf16 v[10:13], v[158:161], v[194:197], v[10:13]
	v_mfma_f32_16x16x32_bf16 v[62:65], v[154:157], v[170:173], v[62:65]
	v_mfma_f32_16x16x32_bf16 v[58:61], v[162:165], v[170:173], v[58:61]
	v_mfma_f32_16x16x32_bf16 v[46:49], v[154:157], v[182:185], v[46:49]
	v_mfma_f32_16x16x32_bf16 v[42:45], v[162:165], v[182:185], v[42:45]
	v_mfma_f32_16x16x32_bf16 v[30:33], v[154:157], v[190:193], v[30:33]
	v_mfma_f32_16x16x32_bf16 v[26:29], v[162:165], v[190:193], v[26:29]
	v_mfma_f32_16x16x32_bf16 v[14:17], v[154:157], v[198:201], v[14:17]
	v_mfma_f32_16x16x32_bf16 v[10:13], v[162:165], v[198:201], v[10:13]
	s_barrier
	s_add_u32 s26, s26, 0x40080
	s_addc_u32 s27, s27, 0
	s_add_i32 s28, s28, s35
	v_lshl_add_u64 v[150:151], s[26:27], 0, v[130:131]
	s_mov_b32 m0, s28
	s_nop 0
	global_load_lds_dwordx4 v[150:151], off
	v_lshl_add_u64 v[150:151], s[26:27], 0, v[132:133]
	s_add_i32 m0, s28, 0x2000
	s_nop 0
	global_load_lds_dwordx4 v[150:151], off
	s_waitcnt vmcnt(6)
	s_barrier
	v_mfma_f32_16x16x32_bf16 v[54:57], v[202:205], v[166:169], v[54:57]
	v_mfma_f32_16x16x32_bf16 v[50:53], v[210:213], v[166:169], v[50:53]
	v_mfma_f32_16x16x32_bf16 v[38:41], v[202:205], v[174:177], v[38:41]
	v_mfma_f32_16x16x32_bf16 v[34:37], v[210:213], v[174:177], v[34:37]
	v_mfma_f32_16x16x32_bf16 v[22:25], v[202:205], v[186:189], v[22:25]
	v_mfma_f32_16x16x32_bf16 v[18:21], v[210:213], v[186:189], v[18:21]
	v_mfma_f32_16x16x32_bf16 v[6:9], v[202:205], v[194:197], v[6:9]
	v_mfma_f32_16x16x32_bf16 v[2:5], v[210:213], v[194:197], v[2:5]
	v_mfma_f32_16x16x32_bf16 v[54:57], v[206:209], v[170:173], v[54:57]
	v_mfma_f32_16x16x32_bf16 v[50:53], v[214:217], v[170:173], v[50:53]
	v_mfma_f32_16x16x32_bf16 v[38:41], v[206:209], v[182:185], v[38:41]
	v_mfma_f32_16x16x32_bf16 v[34:37], v[214:217], v[182:185], v[34:37]
	v_mfma_f32_16x16x32_bf16 v[22:25], v[206:209], v[190:193], v[22:25]
	v_mfma_f32_16x16x32_bf16 v[18:21], v[214:217], v[190:193], v[18:21]
	v_mfma_f32_16x16x32_bf16 v[6:9], v[206:209], v[198:201], v[6:9]
	v_mfma_f32_16x16x32_bf16 v[2:5], v[214:217], v[198:201], v[2:5]
	s_add_i32 s51, s51, 2
	s_add_u32 s24, s24, 0x100
	s_addc_u32 s25, s25, 0
	s_cmp_gt_u32 s51, 13
	s_barrier
	s_cbranch_scc0 .LBB0_4568
	s_add_u32 s24, s47, 0xffffff00
	s_addc_u32 s25, s48, -1
	s_andn2_b64 vcc, exec, s[6:7]
	s_cbranch_vccnz .LBB0_4559
	v_mov_b32_e32 v2, 0
	s_mov_b32 s2, s16
	s_mov_b32 s12, s18
	s_mov_b64 s[0:1], s[22:23]
	s_mov_b32 s41, s46
	v_mov_b32_e32 v3, v2
	v_mov_b32_e32 v4, v2
	v_mov_b32_e32 v5, v2
	v_mov_b32_e32 v6, v2
	v_mov_b32_e32 v7, v2
	v_mov_b32_e32 v8, v2
	v_mov_b32_e32 v9, v2
	v_mov_b32_e32 v18, v2
	v_mov_b32_e32 v19, v2
	v_mov_b32_e32 v20, v2
	v_mov_b32_e32 v21, v2
	v_mov_b32_e32 v22, v2
	v_mov_b32_e32 v23, v2
	v_mov_b32_e32 v24, v2
	v_mov_b32_e32 v25, v2
	v_mov_b32_e32 v34, v2
	v_mov_b32_e32 v35, v2
	v_mov_b32_e32 v36, v2
	v_mov_b32_e32 v37, v2
	v_mov_b32_e32 v38, v2
	v_mov_b32_e32 v39, v2
	v_mov_b32_e32 v40, v2
	v_mov_b32_e32 v41, v2
	v_mov_b32_e32 v50, v2
	v_mov_b32_e32 v51, v2
	v_mov_b32_e32 v52, v2
	v_mov_b32_e32 v53, v2
	v_mov_b32_e32 v54, v2
	v_mov_b32_e32 v55, v2
	v_mov_b32_e32 v56, v2
	v_mov_b32_e32 v57, v2
	v_mov_b32_e32 v10, v2
	v_mov_b32_e32 v11, v2
	v_mov_b32_e32 v12, v2
	v_mov_b32_e32 v13, v2
	v_mov_b32_e32 v14, v2
	v_mov_b32_e32 v15, v2
	v_mov_b32_e32 v16, v2
	v_mov_b32_e32 v17, v2
	v_mov_b32_e32 v26, v2
	v_mov_b32_e32 v27, v2
	v_mov_b32_e32 v28, v2
	v_mov_b32_e32 v29, v2
	v_mov_b32_e32 v30, v2
	v_mov_b32_e32 v31, v2
	v_mov_b32_e32 v32, v2
	v_mov_b32_e32 v33, v2
	v_mov_b32_e32 v42, v2
	v_mov_b32_e32 v43, v2
	v_mov_b32_e32 v44, v2
	v_mov_b32_e32 v45, v2
	v_mov_b32_e32 v46, v2
	v_mov_b32_e32 v47, v2
	v_mov_b32_e32 v48, v2
	v_mov_b32_e32 v49, v2
	v_mov_b32_e32 v58, v2
	v_mov_b32_e32 v59, v2
	v_mov_b32_e32 v60, v2
	v_mov_b32_e32 v61, v2
	v_mov_b32_e32 v62, v2
	v_mov_b32_e32 v63, v2
	v_mov_b32_e32 v64, v2
	v_mov_b32_e32 v65, v2
	v_mov_b32_e32 v66, v2
	v_mov_b32_e32 v67, v2
	v_mov_b32_e32 v68, v2
	v_mov_b32_e32 v69, v2
	v_mov_b32_e32 v70, v2
	v_mov_b32_e32 v71, v2
	v_mov_b32_e32 v72, v2
	v_mov_b32_e32 v73, v2
	v_mov_b32_e32 v82, v2
	v_mov_b32_e32 v83, v2
	v_mov_b32_e32 v84, v2
	v_mov_b32_e32 v85, v2
	v_mov_b32_e32 v86, v2
	v_mov_b32_e32 v87, v2
	v_mov_b32_e32 v88, v2
	v_mov_b32_e32 v89, v2
	v_mov_b32_e32 v98, v2
	v_mov_b32_e32 v99, v2
	v_mov_b32_e32 v100, v2
	v_mov_b32_e32 v101, v2
	v_mov_b32_e32 v102, v2
	v_mov_b32_e32 v103, v2
	v_mov_b32_e32 v104, v2
	v_mov_b32_e32 v105, v2
	v_mov_b32_e32 v114, v2
	v_mov_b32_e32 v115, v2
	v_mov_b32_e32 v116, v2
	v_mov_b32_e32 v117, v2
	v_mov_b32_e32 v118, v2
	v_mov_b32_e32 v119, v2
	v_mov_b32_e32 v120, v2
	v_mov_b32_e32 v121, v2
	v_mov_b32_e32 v74, v2
	v_mov_b32_e32 v75, v2
	v_mov_b32_e32 v76, v2
	v_mov_b32_e32 v77, v2
	v_mov_b32_e32 v78, v2
	v_mov_b32_e32 v79, v2
	v_mov_b32_e32 v80, v2
	v_mov_b32_e32 v81, v2
	v_mov_b32_e32 v90, v2
	v_mov_b32_e32 v91, v2
	v_mov_b32_e32 v92, v2
	v_mov_b32_e32 v93, v2
	v_mov_b32_e32 v94, v2
	v_mov_b32_e32 v95, v2
	v_mov_b32_e32 v96, v2
	v_mov_b32_e32 v97, v2
	v_mov_b32_e32 v106, v2
	v_mov_b32_e32 v107, v2
	v_mov_b32_e32 v108, v2
	v_mov_b32_e32 v109, v2
	v_mov_b32_e32 v110, v2
	v_mov_b32_e32 v111, v2
	v_mov_b32_e32 v112, v2
	v_mov_b32_e32 v113, v2
	v_mov_b32_e32 v122, v2
	v_mov_b32_e32 v123, v2
	v_mov_b32_e32 v124, v2
	v_mov_b32_e32 v125, v2
	v_mov_b32_e32 v126, v2
	v_mov_b32_e32 v127, v2
	v_mov_b32_e32 v128, v2
	v_mov_b32_e32 v129, v2
	s_andn2_b64 vcc, exec, s[4:5]
	s_cbranch_vccnz .LBB0_4560

.LBB0_4743:
	ds_read_b128 v[130:133], v228
	ds_read_b128 v[134:137], v228 offset:1024
	ds_read_b128 v[138:141], v228 offset:2048
	ds_read_b128 v[142:145], v228 offset:3072
	s_add_u32 s18, s16, 0xfffc0080
	s_addc_u32 s19, s17, -1
	s_cmp_eq_u32 s26, 12
	s_cselect_b32 s21, s13, s19
	s_cselect_b32 s20, s15, s18
	s_cselect_b32 s19, s22, s25
	s_cselect_b32 s18, s23, s24
	v_lshl_add_u64 v[204:205], s[16:17], 0, v[196:197]
	s_add_i32 m0, s62, 0xc000
	ds_read_b128 v[146:149], v229
	ds_read_b128 v[150:153], v229 offset:1024
	ds_read_b128 v[154:157], v229 offset:2048
	ds_read_b128 v[158:161], v229 offset:3072
	ds_read_b128 v[162:165], v229 offset:4096
	ds_read_b128 v[166:169], v229 offset:5120
	ds_read_b128 v[170:173], v229 offset:6144
	ds_read_b128 v[174:177], v229 offset:7168
	global_load_lds_dwordx4 v[204:205], off
	v_lshl_add_u64 v[204:205], s[16:17], 0, v[198:199]
	s_add_i32 m0, s62, 0xe000
	s_nop 0
	global_load_lds_dwordx4 v[204:205], off
	s_waitcnt lgkmcnt(8)
	s_barrier
	s_waitcnt lgkmcnt(0)
	s_waitcnt lgkmcnt(0)
	v_mfma_f32_16x16x32_bf16 v[126:129], v[130:133], v[146:149], v[126:129]
	v_mfma_f32_16x16x32_bf16 v[62:65], v[138:141], v[146:149], v[62:65]
	v_mfma_f32_16x16x32_bf16 v[118:121], v[130:133], v[154:157], v[118:121]
	v_mfma_f32_16x16x32_bf16 v[54:57], v[138:141], v[154:157], v[54:57]
	v_mfma_f32_16x16x32_bf16 v[110:113], v[130:133], v[162:165], v[110:113]
	v_mfma_f32_16x16x32_bf16 v[46:49], v[138:141], v[162:165], v[46:49]
	v_mfma_f32_16x16x32_bf16 v[102:105], v[130:133], v[170:173], v[102:105]
	v_mfma_f32_16x16x32_bf16 v[38:41], v[138:141], v[170:173], v[38:41]
	v_mfma_f32_16x16x32_bf16 v[126:129], v[134:137], v[150:153], v[126:129]
	v_mfma_f32_16x16x32_bf16 v[62:65], v[142:145], v[150:153], v[62:65]
	v_mfma_f32_16x16x32_bf16 v[118:121], v[134:137], v[158:161], v[118:121]
	v_mfma_f32_16x16x32_bf16 v[54:57], v[142:145], v[158:161], v[54:57]
	v_mfma_f32_16x16x32_bf16 v[110:113], v[134:137], v[166:169], v[110:113]
	v_mfma_f32_16x16x32_bf16 v[46:49], v[142:145], v[166:169], v[46:49]
	v_mfma_f32_16x16x32_bf16 v[102:105], v[134:137], v[174:177], v[102:105]
	v_mfma_f32_16x16x32_bf16 v[38:41], v[142:145], v[174:177], v[38:41]
	s_barrier
	s_add_i32 s27, s33, s1
	v_lshl_add_u64 v[220:221], s[18:19], 0, v[184:185]
	s_mov_b32 m0, s27
	ds_read_b128 v[204:207], v230
	ds_read_b128 v[208:211], v230 offset:1024
	ds_read_b128 v[212:215], v230 offset:2048
	ds_read_b128 v[216:219], v230 offset:3072
	global_load_lds_dwordx4 v[220:221], off
	v_lshl_add_u64 v[222:223], s[18:19], 0, v[188:189]
	s_add_i32 m0, s27, 0x2000
	s_nop 0
	global_load_lds_dwordx4 v[222:223], off
	s_barrier
	s_waitcnt lgkmcnt(0)
	s_waitcnt lgkmcnt(0)
	v_mfma_f32_16x16x32_bf16 v[122:125], v[204:207], v[146:149], v[122:125]
	v_mfma_f32_16x16x32_bf16 v[58:61], v[212:215], v[146:149], v[58:61]
	v_mfma_f32_16x16x32_bf16 v[114:117], v[204:207], v[154:157], v[114:117]
	v_mfma_f32_16x16x32_bf16 v[50:53], v[212:215], v[154:157], v[50:53]
	v_mfma_f32_16x16x32_bf16 v[106:109], v[204:207], v[162:165], v[106:109]
	v_mfma_f32_16x16x32_bf16 v[42:45], v[212:215], v[162:165], v[42:45]
	v_mfma_f32_16x16x32_bf16 v[98:101], v[204:207], v[170:173], v[98:101]
	v_mfma_f32_16x16x32_bf16 v[34:37], v[212:215], v[170:173], v[34:37]
	v_mfma_f32_16x16x32_bf16 v[122:125], v[208:211], v[150:153], v[122:125]
	v_mfma_f32_16x16x32_bf16 v[58:61], v[216:219], v[150:153], v[58:61]
	v_mfma_f32_16x16x32_bf16 v[114:117], v[208:211], v[158:161], v[114:117]
	v_mfma_f32_16x16x32_bf16 v[50:53], v[216:219], v[158:161], v[50:53]
	v_mfma_f32_16x16x32_bf16 v[106:109], v[208:211], v[166:169], v[106:109]
	v_mfma_f32_16x16x32_bf16 v[42:45], v[216:219], v[166:169], v[42:45]
	v_mfma_f32_16x16x32_bf16 v[98:101], v[208:211], v[174:177], v[98:101]
	v_mfma_f32_16x16x32_bf16 v[34:37], v[216:219], v[174:177], v[34:37]
	s_mov_b32 m0, s62
	v_lshl_add_u64 v[224:225], s[20:21], 0, v[182:183]
	s_barrier
	ds_read_b128 v[146:149], v229 offset:16384
	ds_read_b128 v[150:153], v229 offset:17408
	ds_read_b128 v[154:157], v229 offset:18432
	ds_read_b128 v[158:161], v229 offset:19456
	ds_read_b128 v[162:165], v229 offset:20480
	ds_read_b128 v[166:169], v229 offset:21504
	ds_read_b128 v[170:173], v229 offset:22528
	ds_read_b128 v[174:177], v229 offset:23552
	global_load_lds_dwordx4 v[224:225], off
	v_lshl_add_u64 v[232:233], s[20:21], 0, v[186:187]
	s_mov_b32 m0, s63
	s_nop 0
	global_load_lds_dwordx4 v[232:233], off
	s_barrier
	s_waitcnt lgkmcnt(0)
	s_waitcnt lgkmcnt(0)
	v_mfma_f32_16x16x32_bf16 v[94:97], v[130:133], v[146:149], v[94:97]
	v_mfma_f32_16x16x32_bf16 v[30:33], v[138:141], v[146:149], v[30:33]
	v_mfma_f32_16x16x32_bf16 v[86:89], v[130:133], v[154:157], v[86:89]
	v_mfma_f32_16x16x32_bf16 v[22:25], v[138:141], v[154:157], v[22:25]
	v_mfma_f32_16x16x32_bf16 v[78:81], v[130:133], v[162:165], v[78:81]
	v_mfma_f32_16x16x32_bf16 v[14:17], v[138:141], v[162:165], v[14:17]
	v_mfma_f32_16x16x32_bf16 v[70:73], v[130:133], v[170:173], v[70:73]
	v_mfma_f32_16x16x32_bf16 v[6:9], v[138:141], v[170:173], v[6:9]
	v_mfma_f32_16x16x32_bf16 v[94:97], v[134:137], v[150:153], v[94:97]
	v_mfma_f32_16x16x32_bf16 v[30:33], v[142:145], v[150:153], v[30:33]
	v_mfma_f32_16x16x32_bf16 v[86:89], v[134:137], v[158:161], v[86:89]
	v_mfma_f32_16x16x32_bf16 v[22:25], v[142:145], v[158:161], v[22:25]
	v_mfma_f32_16x16x32_bf16 v[78:81], v[134:137], v[166:169], v[78:81]
	v_mfma_f32_16x16x32_bf16 v[14:17], v[142:145], v[166:169], v[14:17]
	v_mfma_f32_16x16x32_bf16 v[70:73], v[134:137], v[174:177], v[70:73]
	v_mfma_f32_16x16x32_bf16 v[6:9], v[142:145], v[174:177], v[6:9]
	s_barrier
	s_add_u32 s28, s18, 0x40000
	s_addc_u32 s29, s19, 0
	s_add_i32 s27, s83, s1
	v_lshl_add_u64 v[130:131], s[28:29], 0, v[184:185]
	s_mov_b32 m0, s27
	s_nop 0
	global_load_lds_dwordx4 v[130:131], off
	v_lshl_add_u64 v[130:131], s[28:29], 0, v[188:189]
	s_add_i32 m0, s27, 0x2000
	s_nop 0
	global_load_lds_dwordx4 v[130:131], off
	s_waitcnt vmcnt(6)
	s_barrier
	v_mfma_f32_16x16x32_bf16 v[90:93], v[204:207], v[146:149], v[90:93]
	v_mfma_f32_16x16x32_bf16 v[26:29], v[212:215], v[146:149], v[26:29]
	v_mfma_f32_16x16x32_bf16 v[82:85], v[204:207], v[154:157], v[82:85]
	v_mfma_f32_16x16x32_bf16 v[18:21], v[212:215], v[154:157], v[18:21]
	v_mfma_f32_16x16x32_bf16 v[74:77], v[204:207], v[162:165], v[74:77]
	v_mfma_f32_16x16x32_bf16 v[10:13], v[212:215], v[162:165], v[10:13]
	v_mfma_f32_16x16x32_bf16 v[66:69], v[204:207], v[170:173], v[66:69]
	v_mfma_f32_16x16x32_bf16 v[2:5], v[212:215], v[170:173], v[2:5]
	v_mfma_f32_16x16x32_bf16 v[90:93], v[208:211], v[150:153], v[90:93]
	v_mfma_f32_16x16x32_bf16 v[26:29], v[216:219], v[150:153], v[26:29]
	v_mfma_f32_16x16x32_bf16 v[82:85], v[208:211], v[158:161], v[82:85]
	v_mfma_f32_16x16x32_bf16 v[18:21], v[216:219], v[158:161], v[18:21]
	v_mfma_f32_16x16x32_bf16 v[74:77], v[208:211], v[166:169], v[74:77]
	v_mfma_f32_16x16x32_bf16 v[10:13], v[216:219], v[166:169], v[10:13]
	v_mfma_f32_16x16x32_bf16 v[66:69], v[208:211], v[174:177], v[66:69]
	v_mfma_f32_16x16x32_bf16 v[2:5], v[216:219], v[174:177], v[2:5]
	s_add_i32 s27, 0, 0x18000
	v_add_u32_e32 v142, s27, v1
	s_barrier
	ds_read_b128 v[130:133], v142
	ds_read_b128 v[134:137], v142 offset:1024
	ds_read_b128 v[138:141], v142 offset:2048
	ds_read_b128 v[142:145], v142 offset:3072
	s_add_u32 s20, s20, 0x40000
	s_addc_u32 s21, s21, 0
	s_mov_b32 m0, s6
	v_lshl_add_u64 v[204:205], s[20:21], 0, v[182:183]
	ds_read_b128 v[146:149], v229 offset:32768
	ds_read_b128 v[150:153], v229 offset:33792
	ds_read_b128 v[154:157], v229 offset:34816
	ds_read_b128 v[158:161], v229 offset:35840
	ds_read_b128 v[162:165], v229 offset:36864
	ds_read_b128 v[166:169], v229 offset:37888
	ds_read_b128 v[170:173], v229 offset:38912
	ds_read_b128 v[174:177], v229 offset:39936
	global_load_lds_dwordx4 v[204:205], off
	v_lshl_add_u64 v[204:205], s[20:21], 0, v[186:187]
	s_mov_b32 m0, s7
	s_nop 0
	global_load_lds_dwordx4 v[204:205], off
	s_waitcnt lgkmcnt(8)
	s_barrier
	s_waitcnt lgkmcnt(0)
	s_waitcnt lgkmcnt(0)
	v_mfma_f32_16x16x32_bf16 v[126:129], v[130:133], v[146:149], v[126:129]
	v_mfma_f32_16x16x32_bf16 v[62:65], v[138:141], v[146:149], v[62:65]
	v_mfma_f32_16x16x32_bf16 v[118:121], v[130:133], v[154:157], v[118:121]
	v_mfma_f32_16x16x32_bf16 v[54:57], v[138:141], v[154:157], v[54:57]
	v_mfma_f32_16x16x32_bf16 v[110:113], v[130:133], v[162:165], v[110:113]
	v_mfma_f32_16x16x32_bf16 v[46:49], v[138:141], v[162:165], v[46:49]
	v_mfma_f32_16x16x32_bf16 v[102:105], v[130:133], v[170:173], v[102:105]
	v_mfma_f32_16x16x32_bf16 v[38:41], v[138:141], v[170:173], v[38:41]
	v_mfma_f32_16x16x32_bf16 v[126:129], v[134:137], v[150:153], v[126:129]
	v_mfma_f32_16x16x32_bf16 v[62:65], v[142:145], v[150:153], v[62:65]
	v_mfma_f32_16x16x32_bf16 v[118:121], v[134:137], v[158:161], v[118:121]
	v_mfma_f32_16x16x32_bf16 v[54:57], v[142:145], v[158:161], v[54:57]
	v_mfma_f32_16x16x32_bf16 v[110:113], v[134:137], v[166:169], v[110:113]
	v_mfma_f32_16x16x32_bf16 v[46:49], v[142:145], v[166:169], v[46:49]
	v_mfma_f32_16x16x32_bf16 v[102:105], v[134:137], v[174:177], v[102:105]
	v_mfma_f32_16x16x32_bf16 v[38:41], v[142:145], v[174:177], v[38:41]
	s_barrier
	s_add_i32 s20, 0, 0x1c000
	s_add_i32 s21, s27, s1
	v_add_u32_e32 v190, s20, v1
	v_lshl_add_u64 v[220:221], v[220:221], 0, s[2:3]
	s_mov_b32 m0, s21
	ds_read_b128 v[204:207], v190
	ds_read_b128 v[208:211], v190 offset:1024
	ds_read_b128 v[212:215], v190 offset:2048
	ds_read_b128 v[216:219], v190 offset:3072
	global_load_lds_dwordx4 v[220:221], off
	v_lshl_add_u64 v[220:221], v[222:223], 0, s[2:3]
	s_add_i32 m0, s21, 0x2000
	s_nop 0
	global_load_lds_dwordx4 v[220:221], off
	s_barrier
	s_waitcnt lgkmcnt(0)
	s_waitcnt lgkmcnt(0)
	v_mfma_f32_16x16x32_bf16 v[122:125], v[204:207], v[146:149], v[122:125]
	v_mfma_f32_16x16x32_bf16 v[58:61], v[212:215], v[146:149], v[58:61]
	v_mfma_f32_16x16x32_bf16 v[114:117], v[204:207], v[154:157], v[114:117]
	v_mfma_f32_16x16x32_bf16 v[50:53], v[212:215], v[154:157], v[50:53]
	v_mfma_f32_16x16x32_bf16 v[106:109], v[204:207], v[162:165], v[106:109]
	v_mfma_f32_16x16x32_bf16 v[42:45], v[212:215], v[162:165], v[42:45]
	v_mfma_f32_16x16x32_bf16 v[98:101], v[204:207], v[170:173], v[98:101]
	v_mfma_f32_16x16x32_bf16 v[34:37], v[212:215], v[170:173], v[34:37]
	v_mfma_f32_16x16x32_bf16 v[122:125], v[208:211], v[150:153], v[122:125]
	v_mfma_f32_16x16x32_bf16 v[58:61], v[216:219], v[150:153], v[58:61]
	v_mfma_f32_16x16x32_bf16 v[114:117], v[208:211], v[158:161], v[114:117]
	v_mfma_f32_16x16x32_bf16 v[50:53], v[216:219], v[158:161], v[50:53]
	v_mfma_f32_16x16x32_bf16 v[106:109], v[208:211], v[166:169], v[106:109]
	v_mfma_f32_16x16x32_bf16 v[42:45], v[216:219], v[166:169], v[42:45]
	v_mfma_f32_16x16x32_bf16 v[98:101], v[208:211], v[174:177], v[98:101]
	v_mfma_f32_16x16x32_bf16 v[34:37], v[216:219], v[174:177], v[34:37]
	s_mov_b32 m0, s80
	v_lshl_add_u64 v[220:221], v[224:225], 0, s[2:3]
	s_barrier
	ds_read_b128 v[146:149], v229 offset:49152
	ds_read_b128 v[150:153], v229 offset:50176
	ds_read_b128 v[154:157], v229 offset:51200
	ds_read_b128 v[158:161], v229 offset:52224
	ds_read_b128 v[162:165], v229 offset:53248
	ds_read_b128 v[166:169], v229 offset:54272
	ds_read_b128 v[170:173], v229 offset:55296
	ds_read_b128 v[174:177], v229 offset:56320
	global_load_lds_dwordx4 v[220:221], off
	v_lshl_add_u64 v[220:221], v[232:233], 0, s[2:3]
	s_mov_b32 m0, s81
	s_nop 0
	global_load_lds_dwordx4 v[220:221], off
	s_barrier
	s_waitcnt lgkmcnt(0)
	s_waitcnt lgkmcnt(0)
	v_mfma_f32_16x16x32_bf16 v[94:97], v[130:133], v[146:149], v[94:97]
	v_mfma_f32_16x16x32_bf16 v[30:33], v[138:141], v[146:149], v[30:33]
	v_mfma_f32_16x16x32_bf16 v[86:89], v[130:133], v[154:157], v[86:89]
	v_mfma_f32_16x16x32_bf16 v[22:25], v[138:141], v[154:157], v[22:25]
	v_mfma_f32_16x16x32_bf16 v[78:81], v[130:133], v[162:165], v[78:81]
	v_mfma_f32_16x16x32_bf16 v[14:17], v[138:141], v[162:165], v[14:17]
	v_mfma_f32_16x16x32_bf16 v[70:73], v[130:133], v[170:173], v[70:73]
	v_mfma_f32_16x16x32_bf16 v[6:9], v[138:141], v[170:173], v[6:9]
	v_mfma_f32_16x16x32_bf16 v[94:97], v[134:137], v[150:153], v[94:97]
	v_mfma_f32_16x16x32_bf16 v[30:33], v[142:145], v[150:153], v[30:33]
	v_mfma_f32_16x16x32_bf16 v[86:89], v[134:137], v[158:161], v[86:89]
	v_mfma_f32_16x16x32_bf16 v[22:25], v[142:145], v[158:161], v[22:25]
	v_mfma_f32_16x16x32_bf16 v[78:81], v[134:137], v[166:169], v[78:81]
	v_mfma_f32_16x16x32_bf16 v[14:17], v[142:145], v[166:169], v[14:17]
	v_mfma_f32_16x16x32_bf16 v[70:73], v[134:137], v[174:177], v[70:73]
	v_mfma_f32_16x16x32_bf16 v[6:9], v[142:145], v[174:177], v[6:9]
	s_barrier
	s_add_u32 s18, s18, 0x40080
	s_addc_u32 s19, s19, 0
	s_add_i32 s20, s20, s1
	v_lshl_add_u64 v[130:131], s[18:19], 0, v[184:185]
	s_mov_b32 m0, s20
	s_nop 0
	global_load_lds_dwordx4 v[130:131], off
	v_lshl_add_u64 v[130:131], s[18:19], 0, v[188:189]
	s_add_i32 m0, s20, 0x2000
	s_nop 0
	global_load_lds_dwordx4 v[130:131], off
	s_waitcnt vmcnt(6)
	s_barrier
	v_mfma_f32_16x16x32_bf16 v[90:93], v[204:207], v[146:149], v[90:93]
	v_mfma_f32_16x16x32_bf16 v[26:29], v[212:215], v[146:149], v[26:29]
	v_mfma_f32_16x16x32_bf16 v[82:85], v[204:207], v[154:157], v[82:85]
	v_mfma_f32_16x16x32_bf16 v[18:21], v[212:215], v[154:157], v[18:21]
	v_mfma_f32_16x16x32_bf16 v[74:77], v[204:207], v[162:165], v[74:77]
	v_mfma_f32_16x16x32_bf16 v[10:13], v[212:215], v[162:165], v[10:13]
	v_mfma_f32_16x16x32_bf16 v[66:69], v[204:207], v[170:173], v[66:69]
	v_mfma_f32_16x16x32_bf16 v[2:5], v[212:215], v[170:173], v[2:5]
	v_mfma_f32_16x16x32_bf16 v[90:93], v[208:211], v[150:153], v[90:93]
	v_mfma_f32_16x16x32_bf16 v[26:29], v[216:219], v[150:153], v[26:29]
	v_mfma_f32_16x16x32_bf16 v[82:85], v[208:211], v[158:161], v[82:85]
	v_mfma_f32_16x16x32_bf16 v[18:21], v[216:219], v[158:161], v[18:21]
	v_mfma_f32_16x16x32_bf16 v[74:77], v[208:211], v[166:169], v[74:77]
	v_mfma_f32_16x16x32_bf16 v[10:13], v[216:219], v[166:169], v[10:13]
	v_mfma_f32_16x16x32_bf16 v[66:69], v[208:211], v[174:177], v[66:69]
	v_mfma_f32_16x16x32_bf16 v[2:5], v[216:219], v[174:177], v[2:5]
	s_add_i32 s26, s26, 2
	s_add_u32 s16, s16, 0x100
	s_addc_u32 s17, s17, 0
	s_add_u32 s24, s24, 0x100
	s_addc_u32 s25, s25, 0
	s_cmp_gt_u32 s26, 13
	s_barrier
	s_cbranch_scc0 .LBB0_4743
	s_mov_b64 s[16:17], -1
	s_cmp_lt_i32 s12, 64
	v_lshl_or_b32 v204, s14, 7, v181
	s_cbranch_scc0 .Lmy_ffnB_sample
	s_load_dwordx2 s[36:37], s[78:79], 0x268
	s_load_dwordx2 s[38:39], s[78:79], 0x2a0
	s_load_dwordx4 s[40:43], s[78:79], 0x70
	s_load_dwordx2 s[44:45], s[78:79], 0x120
	v_and_b32_e32 v204, 15, v248
	v_bfe_u32 v205, v248, 8, 1
	v_bfe_u32 v206, v248, 6, 2
	v_bfe_u32 v207, v248, 4, 2
	v_lshlrev_b32_e32 v206, 5, v206
	v_lshl_or_b32 v206, v207, 3, v206
	s_lshl_b32 s13, s14, 7
	v_add_u32_e32 v206, s13, v206
	s_lshl_b32 s13, s12, 8
	v_lshl_add_u32 v207, v205, 6, v204
	v_add_u32_e32 v207, s13, v207
	v_mul_u32_u24_e32 v231, 0x1600, v207
	v_lshl_add_u32 v231, v206, 1, v231
	v_lshlrev_b32_e32 v232, 2, v206
	s_lshl_b32 s13, s12, 4
	v_lshl_add_u32 v233, v205, 2, s13
	v_add_u32_e32 v208, -12, v204
	v_cmp_gt_u32_e32 vcc, 2, v204
	s_nop 1
	v_cndmask_b32_e32 v208, v208, v204, vcc
	v_add_u32_e32 v233, v233, v208
	v_mul_u32_u24_e32 v233, 0x2c00, v233
	v_lshl_add_u32 v233, v206, 1, v233
	s_lshr_b32 s13, s12, 3
	s_lshl_b32 s13, s13, 1
	s_add_i32 s13, s13, 2
	v_add_u32_e32 v234, s13, v204
	v_mul_u32_u24_e32 v234, 0x5800, v234
	v_lshl_add_u32 v234, v206, 2, v234
	v_readfirstlane_b32 s4, v248
	s_lshr_b32 s4, s4, 8
	s_and_b32 s5, s12, 7
	s_cmp_eq_u32 s5, 7
	s_cselect_b32 s5, 1, 0
	s_and_b32 s5, s5, s4
	s_waitcnt lgkmcnt(0)
	s_add_u32 s40, s40, 0x10800
	s_addc_u32 s41, s41, 0
	s_add_u32 s42, s42, 0x5800
	s_addc_u32 s43, s43, 0
	global_load_dwordx4 v[130:133], v232, s[40:41]
	v_add_u32_e32 v213, 0x5800, v232
	global_load_dwordx4 v[134:137], v213, s[40:41]
	v_add_u32_e32 v214, 0xb000, v232
	global_load_dwordx4 v[138:141], v214, s[40:41]
	global_load_dwordx4 v[142:145], v232, s[42:43]
	v_add_u32_e32 v215, 0x2c00, v232
	global_load_dwordx4 v[146:149], v215, s[40:41]
	v_add_u32_e32 v216, 0x8400, v232
	global_load_dwordx4 v[150:153], v216, s[40:41]
	v_add_u32_e32 v217, 0xdc00, v232
	global_load_dwordx4 v[154:157], v217, s[40:41]
	v_add_u32_e32 v218, 0x2c00, v232
	global_load_dwordx4 v[158:161], v218, s[42:43]
	s_mov_b32 exec_lo, 0x30003
	s_mov_b32 exec_hi, 0x30003
	v_cvt_pk_bf16_f32 v162, v126, v127
	v_cvt_pk_bf16_f32 v163, v128, v129
	global_store_dwordx2 v233, v[162:163], s[38:39]
	v_cvt_pk_bf16_f32 v164, v122, v123
	v_cvt_pk_bf16_f32 v165, v124, v125
	v_add_u32_e32 v220, 0x1600, v233
	global_store_dwordx2 v220, v[164:165], s[38:39]
	v_cvt_pk_bf16_f32 v166, v94, v95
	v_cvt_pk_bf16_f32 v167, v96, v97
	v_add_u32_e32 v221, 0x16000, v233
	global_store_dwordx2 v221, v[166:167], s[38:39]
	v_cvt_pk_bf16_f32 v168, v90, v91
	v_cvt_pk_bf16_f32 v169, v92, v93
	v_add_u32_e32 v222, 0x17600, v233
	global_store_dwordx2 v222, v[168:169], s[38:39]
	v_cvt_pk_bf16_f32 v170, v62, v63
	v_cvt_pk_bf16_f32 v171, v64, v65
	v_add_u32_e32 v223, 0x8, v233
	global_store_dwordx2 v223, v[170:171], s[38:39]
	v_cvt_pk_bf16_f32 v172, v58, v59
	v_cvt_pk_bf16_f32 v173, v60, v61
	v_add_u32_e32 v224, 0x1608, v233
	global_store_dwordx2 v224, v[172:173], s[38:39]
	v_cvt_pk_bf16_f32 v174, v30, v31
	v_cvt_pk_bf16_f32 v175, v32, v33
	v_add_u32_e32 v225, 0x16008, v233
	global_store_dwordx2 v225, v[174:175], s[38:39]
	v_cvt_pk_bf16_f32 v176, v26, v27
	v_cvt_pk_bf16_f32 v177, v28, v29
	v_add_u32_e32 v226, 0x17608, v233
	global_store_dwordx2 v226, v[176:177], s[38:39]
	s_mov_b32 exec_lo, 0xc000c000
	s_mov_b32 exec_hi, 0xc000c000
	v_cvt_pk_bf16_f32 v162, v102, v103
	v_cvt_pk_bf16_f32 v163, v104, v105
	global_store_dwordx2 v233, v[162:163], s[38:39]
	v_cvt_pk_bf16_f32 v164, v98, v99
	v_cvt_pk_bf16_f32 v165, v100, v101
	v_add_u32_e32 v220, 0x1600, v233
	global_store_dwordx2 v220, v[164:165], s[38:39]
	v_cvt_pk_bf16_f32 v166, v70, v71
	v_cvt_pk_bf16_f32 v167, v72, v73
	v_add_u32_e32 v221, 0x16000, v233
	global_store_dwordx2 v221, v[166:167], s[38:39]
	v_cvt_pk_bf16_f32 v168, v66, v67
	v_cvt_pk_bf16_f32 v169, v68, v69
	v_add_u32_e32 v222, 0x17600, v233
	global_store_dwordx2 v222, v[168:169], s[38:39]
	v_cvt_pk_bf16_f32 v170, v38, v39
	v_cvt_pk_bf16_f32 v171, v40, v41
	v_add_u32_e32 v223, 0x8, v233
	global_store_dwordx2 v223, v[170:171], s[38:39]
	v_cvt_pk_bf16_f32 v172, v34, v35
	v_cvt_pk_bf16_f32 v173, v36, v37
	v_add_u32_e32 v224, 0x1608, v233
	global_store_dwordx2 v224, v[172:173], s[38:39]
	v_cvt_pk_bf16_f32 v174, v6, v7
	v_cvt_pk_bf16_f32 v175, v8, v9
	v_add_u32_e32 v225, 0x16008, v233
	global_store_dwordx2 v225, v[174:175], s[38:39]
	v_cvt_pk_bf16_f32 v176, v2, v3
	v_cvt_pk_bf16_f32 v177, v4, v5
	v_add_u32_e32 v226, 0x17608, v233
	global_store_dwordx2 v226, v[176:177], s[38:39]
	s_cmp_lg_u32 s5, 0
	s_cbranch_scc0 .Lmy_ffnB_ncp
	global_store_dwordx4 v234, v[70:73], s[44:45]
	v_add_u32_e32 v220, 0x2c00, v234
	global_store_dwordx4 v220, v[66:69], s[44:45]
	v_add_u32_e32 v221, 0x10, v234
	global_store_dwordx4 v221, v[6:9], s[44:45]
	v_add_u32_e32 v222, 0x2c10, v234
	global_store_dwordx4 v222, v[2:5], s[44:45]

.LBB0_5227:
	v_add_u32_e32 v0, s38, v147
	s_add_u32 s16, s8, s14
	ds_read_b128 v[150:153], v0
	ds_read_b128 v[154:157], v0 offset:1024
	ds_read_b128 v[158:161], v0 offset:2048
	ds_read_b128 v[162:165], v0 offset:3072
	s_addc_u32 s17, s9, s15
	s_add_u32 s16, s16, 0x100
	s_addc_u32 s17, s17, 0
	s_add_u32 s46, s43, s14
	s_addc_u32 s47, s44, s15
	s_cmpk_eq_i32 s14, 0x1500
	s_cselect_b32 s19, s13, s17
	s_cselect_b32 s18, s12, s16
	s_cselect_b32 s17, s3, s47
	s_cselect_b32 s16, s2, s46
	v_lshl_add_u64 v[202:203], v[142:143], 0, s[14:15]
	s_add_i32 m0, s29, 0xc000
	ds_read_b128 v[166:169], v148
	ds_read_b128 v[170:173], v148 offset:1024
	ds_read_b128 v[174:177], v148 offset:2048
	ds_read_b128 v[182:185], v148 offset:3072
	ds_read_b128 v[186:189], v148 offset:4096
	ds_read_b128 v[190:193], v148 offset:5120
	ds_read_b128 v[194:197], v148 offset:6144
	ds_read_b128 v[198:201], v148 offset:7168
	global_load_lds_dwordx4 v[202:203], off
	v_lshl_add_u64 v[202:203], v[144:145], 0, s[14:15]
	s_add_i32 m0, s29, 0xe000
	s_nop 0
	global_load_lds_dwordx4 v[202:203], off
	s_waitcnt lgkmcnt(8)
	s_barrier
	s_waitcnt lgkmcnt(0)
	s_waitcnt lgkmcnt(0)
	v_mfma_f32_16x16x32_bf16 v[126:129], v[150:153], v[166:169], v[126:129]
	v_mfma_f32_16x16x32_bf16 v[122:125], v[158:161], v[166:169], v[122:125]
	v_mfma_f32_16x16x32_bf16 v[110:113], v[150:153], v[174:177], v[110:113]
	v_mfma_f32_16x16x32_bf16 v[106:109], v[158:161], v[174:177], v[106:109]
	v_mfma_f32_16x16x32_bf16 v[94:97], v[150:153], v[186:189], v[94:97]
	v_mfma_f32_16x16x32_bf16 v[90:93], v[158:161], v[186:189], v[90:93]
	v_mfma_f32_16x16x32_bf16 v[78:81], v[150:153], v[194:197], v[78:81]
	v_mfma_f32_16x16x32_bf16 v[74:77], v[158:161], v[194:197], v[74:77]
	v_mfma_f32_16x16x32_bf16 v[126:129], v[154:157], v[170:173], v[126:129]
	v_mfma_f32_16x16x32_bf16 v[122:125], v[162:165], v[170:173], v[122:125]
	v_mfma_f32_16x16x32_bf16 v[110:113], v[154:157], v[182:185], v[110:113]
	v_mfma_f32_16x16x32_bf16 v[106:109], v[162:165], v[182:185], v[106:109]
	v_mfma_f32_16x16x32_bf16 v[94:97], v[154:157], v[190:193], v[94:97]
	v_mfma_f32_16x16x32_bf16 v[90:93], v[162:165], v[190:193], v[90:93]
	v_mfma_f32_16x16x32_bf16 v[78:81], v[154:157], v[198:201], v[78:81]
	v_mfma_f32_16x16x32_bf16 v[74:77], v[162:165], v[198:201], v[74:77]
	s_barrier
	s_add_i32 s46, s38, s28
	v_add_u32_e32 v0, s39, v147
	v_lshl_add_u64 v[218:219], s[16:17], 0, v[130:131]
	s_mov_b32 m0, s46
	ds_read_b128 v[202:205], v0
	ds_read_b128 v[206:209], v0 offset:1024
	ds_read_b128 v[210:213], v0 offset:2048
	ds_read_b128 v[214:217], v0 offset:3072
	global_load_lds_dwordx4 v[218:219], off
	v_lshl_add_u64 v[220:221], s[16:17], 0, v[132:133]
	s_add_i32 m0, s46, 0x2000
	s_nop 0
	global_load_lds_dwordx4 v[220:221], off
	s_barrier
	s_waitcnt lgkmcnt(0)
	s_waitcnt lgkmcnt(0)
	v_mfma_f32_16x16x32_bf16 v[118:121], v[202:205], v[166:169], v[118:121]
	v_mfma_f32_16x16x32_bf16 v[114:117], v[210:213], v[166:169], v[114:117]
	v_mfma_f32_16x16x32_bf16 v[102:105], v[202:205], v[174:177], v[102:105]
	v_mfma_f32_16x16x32_bf16 v[98:101], v[210:213], v[174:177], v[98:101]
	v_mfma_f32_16x16x32_bf16 v[86:89], v[202:205], v[186:189], v[86:89]
	v_mfma_f32_16x16x32_bf16 v[82:85], v[210:213], v[186:189], v[82:85]
	v_mfma_f32_16x16x32_bf16 v[70:73], v[202:205], v[194:197], v[70:73]
	v_mfma_f32_16x16x32_bf16 v[66:69], v[210:213], v[194:197], v[66:69]
	v_mfma_f32_16x16x32_bf16 v[118:121], v[206:209], v[170:173], v[118:121]
	v_mfma_f32_16x16x32_bf16 v[114:117], v[214:217], v[170:173], v[114:117]
	v_mfma_f32_16x16x32_bf16 v[102:105], v[206:209], v[182:185], v[102:105]
	v_mfma_f32_16x16x32_bf16 v[98:101], v[214:217], v[182:185], v[98:101]
	v_mfma_f32_16x16x32_bf16 v[86:89], v[206:209], v[190:193], v[86:89]
	v_mfma_f32_16x16x32_bf16 v[82:85], v[214:217], v[190:193], v[82:85]
	v_mfma_f32_16x16x32_bf16 v[70:73], v[206:209], v[198:201], v[70:73]
	v_mfma_f32_16x16x32_bf16 v[66:69], v[214:217], v[198:201], v[66:69]
	s_mov_b32 m0, s29
	v_lshl_add_u64 v[222:223], s[18:19], 0, v[130:131]
	s_barrier
	ds_read_b128 v[166:169], v148 offset:16384
	ds_read_b128 v[170:173], v148 offset:17408
	ds_read_b128 v[174:177], v148 offset:18432
	ds_read_b128 v[182:185], v148 offset:19456
	ds_read_b128 v[186:189], v148 offset:20480
	ds_read_b128 v[190:193], v148 offset:21504
	ds_read_b128 v[194:197], v148 offset:22528
	ds_read_b128 v[198:201], v148 offset:23552
	global_load_lds_dwordx4 v[222:223], off
	v_lshl_add_u64 v[224:225], s[18:19], 0, v[132:133]
	s_mov_b32 m0, s30
	s_nop 0
	global_load_lds_dwordx4 v[224:225], off
	s_barrier
	s_waitcnt lgkmcnt(0)
	s_waitcnt lgkmcnt(0)
	v_mfma_f32_16x16x32_bf16 v[62:65], v[150:153], v[166:169], v[62:65]
	v_mfma_f32_16x16x32_bf16 v[58:61], v[158:161], v[166:169], v[58:61]
	v_mfma_f32_16x16x32_bf16 v[46:49], v[150:153], v[174:177], v[46:49]
	v_mfma_f32_16x16x32_bf16 v[42:45], v[158:161], v[174:177], v[42:45]
	v_mfma_f32_16x16x32_bf16 v[30:33], v[150:153], v[186:189], v[30:33]
	v_mfma_f32_16x16x32_bf16 v[26:29], v[158:161], v[186:189], v[26:29]
	v_mfma_f32_16x16x32_bf16 v[14:17], v[150:153], v[194:197], v[14:17]
	v_mfma_f32_16x16x32_bf16 v[10:13], v[158:161], v[194:197], v[10:13]
	v_mfma_f32_16x16x32_bf16 v[62:65], v[154:157], v[170:173], v[62:65]
	v_mfma_f32_16x16x32_bf16 v[58:61], v[162:165], v[170:173], v[58:61]
	v_mfma_f32_16x16x32_bf16 v[46:49], v[154:157], v[182:185], v[46:49]
	v_mfma_f32_16x16x32_bf16 v[42:45], v[162:165], v[182:185], v[42:45]
	v_mfma_f32_16x16x32_bf16 v[30:33], v[154:157], v[190:193], v[30:33]
	v_mfma_f32_16x16x32_bf16 v[26:29], v[162:165], v[190:193], v[26:29]
	v_mfma_f32_16x16x32_bf16 v[14:17], v[154:157], v[198:201], v[14:17]
	v_mfma_f32_16x16x32_bf16 v[10:13], v[162:165], v[198:201], v[10:13]
	s_barrier
	s_add_u32 s46, s16, 0xb0000
	s_addc_u32 s47, s17, 0
	s_add_i32 s48, s39, s28
	v_lshl_add_u64 v[150:151], s[46:47], 0, v[130:131]
	s_mov_b32 m0, s48
	s_nop 0
	global_load_lds_dwordx4 v[150:151], off
	v_lshl_add_u64 v[150:151], s[46:47], 0, v[132:133]
	s_add_i32 m0, s48, 0x2000
	s_nop 0
	global_load_lds_dwordx4 v[150:151], off
	s_waitcnt vmcnt(6)
	s_barrier
	v_mfma_f32_16x16x32_bf16 v[54:57], v[202:205], v[166:169], v[54:57]
	v_mfma_f32_16x16x32_bf16 v[50:53], v[210:213], v[166:169], v[50:53]
	v_mfma_f32_16x16x32_bf16 v[38:41], v[202:205], v[174:177], v[38:41]
	v_mfma_f32_16x16x32_bf16 v[34:37], v[210:213], v[174:177], v[34:37]
	v_mfma_f32_16x16x32_bf16 v[22:25], v[202:205], v[186:189], v[22:25]
	v_mfma_f32_16x16x32_bf16 v[18:21], v[210:213], v[186:189], v[18:21]
	v_mfma_f32_16x16x32_bf16 v[6:9], v[202:205], v[194:197], v[6:9]
	v_mfma_f32_16x16x32_bf16 v[2:5], v[210:213], v[194:197], v[2:5]
	v_mfma_f32_16x16x32_bf16 v[54:57], v[206:209], v[170:173], v[54:57]
	v_mfma_f32_16x16x32_bf16 v[50:53], v[214:217], v[170:173], v[50:53]
	v_mfma_f32_16x16x32_bf16 v[38:41], v[206:209], v[182:185], v[38:41]
	v_mfma_f32_16x16x32_bf16 v[34:37], v[214:217], v[182:185], v[34:37]
	v_mfma_f32_16x16x32_bf16 v[22:25], v[206:209], v[190:193], v[22:25]
	v_mfma_f32_16x16x32_bf16 v[18:21], v[214:217], v[190:193], v[18:21]
	v_mfma_f32_16x16x32_bf16 v[6:9], v[206:209], v[198:201], v[6:9]
	v_mfma_f32_16x16x32_bf16 v[2:5], v[214:217], v[198:201], v[2:5]
	s_add_i32 s46, 0, 0x18000
	v_add_u32_e32 v0, s46, v147
	s_barrier
	ds_read_b128 v[150:153], v0
	ds_read_b128 v[154:157], v0 offset:1024
	ds_read_b128 v[158:161], v0 offset:2048
	ds_read_b128 v[162:165], v0 offset:3072
	s_add_u32 s18, s18, 0xb0000
	s_addc_u32 s19, s19, 0
	s_mov_b32 m0, s31
	v_lshl_add_u64 v[202:203], s[18:19], 0, v[130:131]
	ds_read_b128 v[166:169], v148 offset:32768
	ds_read_b128 v[170:173], v148 offset:33792
	ds_read_b128 v[174:177], v148 offset:34816
	ds_read_b128 v[182:185], v148 offset:35840
	ds_read_b128 v[186:189], v148 offset:36864
	ds_read_b128 v[190:193], v148 offset:37888
	ds_read_b128 v[194:197], v148 offset:38912
	ds_read_b128 v[198:201], v148 offset:39936
	global_load_lds_dwordx4 v[202:203], off
	v_lshl_add_u64 v[202:203], s[18:19], 0, v[132:133]
	s_mov_b32 m0, s33
	s_nop 0
	global_load_lds_dwordx4 v[202:203], off
	s_waitcnt lgkmcnt(8)
	s_barrier
	s_waitcnt lgkmcnt(0)
	s_waitcnt lgkmcnt(0)
	v_mfma_f32_16x16x32_bf16 v[126:129], v[150:153], v[166:169], v[126:129]
	v_mfma_f32_16x16x32_bf16 v[122:125], v[158:161], v[166:169], v[122:125]
	v_mfma_f32_16x16x32_bf16 v[110:113], v[150:153], v[174:177], v[110:113]
	v_mfma_f32_16x16x32_bf16 v[106:109], v[158:161], v[174:177], v[106:109]
	v_mfma_f32_16x16x32_bf16 v[94:97], v[150:153], v[186:189], v[94:97]
	v_mfma_f32_16x16x32_bf16 v[90:93], v[158:161], v[186:189], v[90:93]
	v_mfma_f32_16x16x32_bf16 v[78:81], v[150:153], v[194:197], v[78:81]
	v_mfma_f32_16x16x32_bf16 v[74:77], v[158:161], v[194:197], v[74:77]
	v_mfma_f32_16x16x32_bf16 v[126:129], v[154:157], v[170:173], v[126:129]
	v_mfma_f32_16x16x32_bf16 v[122:125], v[162:165], v[170:173], v[122:125]
	v_mfma_f32_16x16x32_bf16 v[110:113], v[154:157], v[182:185], v[110:113]
	v_mfma_f32_16x16x32_bf16 v[106:109], v[162:165], v[182:185], v[106:109]
	v_mfma_f32_16x16x32_bf16 v[94:97], v[154:157], v[190:193], v[94:97]
	v_mfma_f32_16x16x32_bf16 v[90:93], v[162:165], v[190:193], v[90:93]
	v_mfma_f32_16x16x32_bf16 v[78:81], v[154:157], v[198:201], v[78:81]
	v_mfma_f32_16x16x32_bf16 v[74:77], v[162:165], v[198:201], v[74:77]
	s_barrier
	s_add_i32 s18, 0, 0x1c000
	s_add_i32 s19, s46, s28
	v_add_u32_e32 v0, s18, v147
	v_lshl_add_u64 v[218:219], v[218:219], 0, s[10:11]
	s_mov_b32 m0, s19
	ds_read_b128 v[202:205], v0
	ds_read_b128 v[206:209], v0 offset:1024
	ds_read_b128 v[210:213], v0 offset:2048
	ds_read_b128 v[214:217], v0 offset:3072
	global_load_lds_dwordx4 v[218:219], off
	v_lshl_add_u64 v[218:219], v[220:221], 0, s[10:11]
	s_add_i32 m0, s19, 0x2000
	s_nop 0
	global_load_lds_dwordx4 v[218:219], off
	s_barrier
	s_waitcnt lgkmcnt(0)
	s_waitcnt lgkmcnt(0)
	v_mfma_f32_16x16x32_bf16 v[118:121], v[202:205], v[166:169], v[118:121]
	v_mfma_f32_16x16x32_bf16 v[114:117], v[210:213], v[166:169], v[114:117]
	v_mfma_f32_16x16x32_bf16 v[102:105], v[202:205], v[174:177], v[102:105]
	v_mfma_f32_16x16x32_bf16 v[98:101], v[210:213], v[174:177], v[98:101]
	v_mfma_f32_16x16x32_bf16 v[86:89], v[202:205], v[186:189], v[86:89]
	v_mfma_f32_16x16x32_bf16 v[82:85], v[210:213], v[186:189], v[82:85]
	v_mfma_f32_16x16x32_bf16 v[70:73], v[202:205], v[194:197], v[70:73]
	v_mfma_f32_16x16x32_bf16 v[66:69], v[210:213], v[194:197], v[66:69]
	v_mfma_f32_16x16x32_bf16 v[118:121], v[206:209], v[170:173], v[118:121]
	v_mfma_f32_16x16x32_bf16 v[114:117], v[214:217], v[170:173], v[114:117]
	v_mfma_f32_16x16x32_bf16 v[102:105], v[206:209], v[182:185], v[102:105]
	v_mfma_f32_16x16x32_bf16 v[98:101], v[214:217], v[182:185], v[98:101]
	v_mfma_f32_16x16x32_bf16 v[86:89], v[206:209], v[190:193], v[86:89]
	v_mfma_f32_16x16x32_bf16 v[82:85], v[214:217], v[190:193], v[82:85]
	v_mfma_f32_16x16x32_bf16 v[70:73], v[206:209], v[198:201], v[70:73]
	v_mfma_f32_16x16x32_bf16 v[66:69], v[214:217], v[198:201], v[66:69]
	s_mov_b32 m0, s36
	v_lshl_add_u64 v[218:219], v[222:223], 0, s[10:11]
	s_barrier
	ds_read_b128 v[166:169], v148 offset:49152
	ds_read_b128 v[170:173], v148 offset:50176
	ds_read_b128 v[174:177], v148 offset:51200
	ds_read_b128 v[182:185], v148 offset:52224
	ds_read_b128 v[186:189], v148 offset:53248
	ds_read_b128 v[190:193], v148 offset:54272
	ds_read_b128 v[194:197], v148 offset:55296
	ds_read_b128 v[198:201], v148 offset:56320
	global_load_lds_dwordx4 v[218:219], off
	v_lshl_add_u64 v[218:219], v[224:225], 0, s[10:11]
	s_mov_b32 m0, s37
	s_nop 0
	global_load_lds_dwordx4 v[218:219], off
	s_barrier
	s_waitcnt lgkmcnt(0)
	s_waitcnt lgkmcnt(0)
	v_mfma_f32_16x16x32_bf16 v[62:65], v[150:153], v[166:169], v[62:65]
	v_mfma_f32_16x16x32_bf16 v[58:61], v[158:161], v[166:169], v[58:61]
	v_mfma_f32_16x16x32_bf16 v[46:49], v[150:153], v[174:177], v[46:49]
	v_mfma_f32_16x16x32_bf16 v[42:45], v[158:161], v[174:177], v[42:45]
	v_mfma_f32_16x16x32_bf16 v[30:33], v[150:153], v[186:189], v[30:33]
	v_mfma_f32_16x16x32_bf16 v[26:29], v[158:161], v[186:189], v[26:29]
	v_mfma_f32_16x16x32_bf16 v[14:17], v[150:153], v[194:197], v[14:17]
	v_mfma_f32_16x16x32_bf16 v[10:13], v[158:161], v[194:197], v[10:13]
	v_mfma_f32_16x16x32_bf16 v[62:65], v[154:157], v[170:173], v[62:65]
	v_mfma_f32_16x16x32_bf16 v[58:61], v[162:165], v[170:173], v[58:61]
	v_mfma_f32_16x16x32_bf16 v[46:49], v[154:157], v[182:185], v[46:49]
	v_mfma_f32_16x16x32_bf16 v[42:45], v[162:165], v[182:185], v[42:45]
	v_mfma_f32_16x16x32_bf16 v[30:33], v[154:157], v[190:193], v[30:33]
	v_mfma_f32_16x16x32_bf16 v[26:29], v[162:165], v[190:193], v[26:29]
	v_mfma_f32_16x16x32_bf16 v[14:17], v[154:157], v[198:201], v[14:17]
	v_mfma_f32_16x16x32_bf16 v[10:13], v[162:165], v[198:201], v[10:13]
	s_barrier
	s_add_u32 s16, s16, 0xb0080
	s_addc_u32 s17, s17, 0
	s_add_i32 s18, s18, s28
	v_lshl_add_u64 v[150:151], s[16:17], 0, v[130:131]
	s_mov_b32 m0, s18
	s_nop 0
	global_load_lds_dwordx4 v[150:151], off
	v_lshl_add_u64 v[150:151], s[16:17], 0, v[132:133]
	s_add_i32 m0, s18, 0x2000
	s_nop 0
	global_load_lds_dwordx4 v[150:151], off
	s_waitcnt vmcnt(6)
	s_barrier
	v_mfma_f32_16x16x32_bf16 v[54:57], v[202:205], v[166:169], v[54:57]
	v_mfma_f32_16x16x32_bf16 v[50:53], v[210:213], v[166:169], v[50:53]
	v_mfma_f32_16x16x32_bf16 v[38:41], v[202:205], v[174:177], v[38:41]
	v_mfma_f32_16x16x32_bf16 v[34:37], v[210:213], v[174:177], v[34:37]
	v_mfma_f32_16x16x32_bf16 v[22:25], v[202:205], v[186:189], v[22:25]
	v_mfma_f32_16x16x32_bf16 v[18:21], v[210:213], v[186:189], v[18:21]
	v_mfma_f32_16x16x32_bf16 v[6:9], v[202:205], v[194:197], v[6:9]
	v_mfma_f32_16x16x32_bf16 v[2:5], v[210:213], v[194:197], v[2:5]
	v_mfma_f32_16x16x32_bf16 v[54:57], v[206:209], v[170:173], v[54:57]
	v_mfma_f32_16x16x32_bf16 v[50:53], v[214:217], v[170:173], v[50:53]
	v_mfma_f32_16x16x32_bf16 v[38:41], v[206:209], v[182:185], v[38:41]
	v_mfma_f32_16x16x32_bf16 v[34:37], v[214:217], v[182:185], v[34:37]
	v_mfma_f32_16x16x32_bf16 v[22:25], v[206:209], v[190:193], v[22:25]
	v_mfma_f32_16x16x32_bf16 v[18:21], v[214:217], v[190:193], v[18:21]
	v_mfma_f32_16x16x32_bf16 v[6:9], v[206:209], v[198:201], v[6:9]
	v_mfma_f32_16x16x32_bf16 v[2:5], v[214:217], v[198:201], v[2:5]
	s_add_i32 s45, s45, 2
	s_add_u32 s14, s14, 0x100
	s_addc_u32 s15, s15, 0
	s_cmp_gt_u32 s45, 41
	s_barrier
	s_cbranch_scc0 .LBB0_5227
	s_add_u32 s14, s43, 0xffffff00
	s_addc_u32 s15, s44, -1
	s_and_b64 vcc, exec, s[4:5]
	s_cbranch_vccnz .LBB0_5214
	v_mov_b32_e32 v2, 0
	s_mov_b32 s6, s40
	s_mov_b32 s24, s41
	s_mov_b64 s[8:9], s[12:13]
	s_mov_b32 s35, s42
	v_mov_b32_e32 v3, v2
	v_mov_b32_e32 v4, v2
	v_mov_b32_e32 v5, v2
	v_mov_b32_e32 v6, v2
	v_mov_b32_e32 v7, v2
	v_mov_b32_e32 v8, v2
	v_mov_b32_e32 v9, v2
	v_mov_b32_e32 v18, v2
	v_mov_b32_e32 v19, v2
	v_mov_b32_e32 v20, v2
	v_mov_b32_e32 v21, v2
	v_mov_b32_e32 v22, v2
	v_mov_b32_e32 v23, v2
	v_mov_b32_e32 v24, v2
	v_mov_b32_e32 v25, v2
	v_mov_b32_e32 v34, v2
	v_mov_b32_e32 v35, v2
	v_mov_b32_e32 v36, v2
	v_mov_b32_e32 v37, v2
	v_mov_b32_e32 v38, v2
	v_mov_b32_e32 v39, v2
	v_mov_b32_e32 v40, v2
	v_mov_b32_e32 v41, v2
	v_mov_b32_e32 v50, v2
	v_mov_b32_e32 v51, v2
	v_mov_b32_e32 v52, v2
	v_mov_b32_e32 v53, v2
	v_mov_b32_e32 v54, v2
	v_mov_b32_e32 v55, v2
	v_mov_b32_e32 v56, v2
	v_mov_b32_e32 v57, v2
	v_mov_b32_e32 v10, v2
	v_mov_b32_e32 v11, v2
	v_mov_b32_e32 v12, v2
	v_mov_b32_e32 v13, v2
	v_mov_b32_e32 v14, v2
	v_mov_b32_e32 v15, v2
	v_mov_b32_e32 v16, v2
	v_mov_b32_e32 v17, v2
	v_mov_b32_e32 v26, v2
	v_mov_b32_e32 v27, v2
	v_mov_b32_e32 v28, v2
	v_mov_b32_e32 v29, v2
	v_mov_b32_e32 v30, v2
	v_mov_b32_e32 v31, v2
	v_mov_b32_e32 v32, v2
	v_mov_b32_e32 v33, v2
	v_mov_b32_e32 v42, v2
	v_mov_b32_e32 v43, v2
	v_mov_b32_e32 v44, v2
	v_mov_b32_e32 v45, v2
	v_mov_b32_e32 v46, v2
	v_mov_b32_e32 v47, v2
	v_mov_b32_e32 v48, v2
	v_mov_b32_e32 v49, v2
	v_mov_b32_e32 v58, v2
	v_mov_b32_e32 v59, v2
	v_mov_b32_e32 v60, v2
	v_mov_b32_e32 v61, v2
	v_mov_b32_e32 v62, v2
	v_mov_b32_e32 v63, v2
	v_mov_b32_e32 v64, v2
	v_mov_b32_e32 v65, v2
	v_mov_b32_e32 v66, v2
	v_mov_b32_e32 v67, v2
	v_mov_b32_e32 v68, v2
	v_mov_b32_e32 v69, v2
	v_mov_b32_e32 v70, v2
	v_mov_b32_e32 v71, v2
	v_mov_b32_e32 v72, v2
	v_mov_b32_e32 v73, v2
	v_mov_b32_e32 v82, v2
	v_mov_b32_e32 v83, v2
	v_mov_b32_e32 v84, v2
	v_mov_b32_e32 v85, v2
	v_mov_b32_e32 v86, v2
	v_mov_b32_e32 v87, v2
	v_mov_b32_e32 v88, v2
	v_mov_b32_e32 v89, v2
	v_mov_b32_e32 v98, v2
	v_mov_b32_e32 v99, v2
	v_mov_b32_e32 v100, v2
	v_mov_b32_e32 v101, v2
	v_mov_b32_e32 v102, v2
	v_mov_b32_e32 v103, v2
	v_mov_b32_e32 v104, v2
	v_mov_b32_e32 v105, v2
	v_mov_b32_e32 v114, v2
	v_mov_b32_e32 v115, v2
	v_mov_b32_e32 v116, v2
	v_mov_b32_e32 v117, v2
	v_mov_b32_e32 v118, v2
	v_mov_b32_e32 v119, v2
	v_mov_b32_e32 v120, v2
	v_mov_b32_e32 v121, v2
	v_mov_b32_e32 v74, v2
	v_mov_b32_e32 v75, v2
	v_mov_b32_e32 v76, v2
	v_mov_b32_e32 v77, v2
	v_mov_b32_e32 v78, v2
	v_mov_b32_e32 v79, v2
	v_mov_b32_e32 v80, v2
	v_mov_b32_e32 v81, v2
	v_mov_b32_e32 v90, v2
	v_mov_b32_e32 v91, v2
	v_mov_b32_e32 v92, v2
	v_mov_b32_e32 v93, v2
	v_mov_b32_e32 v94, v2
	v_mov_b32_e32 v95, v2
	v_mov_b32_e32 v96, v2
	v_mov_b32_e32 v97, v2
	v_mov_b32_e32 v106, v2
	v_mov_b32_e32 v107, v2
	v_mov_b32_e32 v108, v2
	v_mov_b32_e32 v109, v2
	v_mov_b32_e32 v110, v2
	v_mov_b32_e32 v111, v2
	v_mov_b32_e32 v112, v2
	v_mov_b32_e32 v113, v2
	v_mov_b32_e32 v122, v2
	v_mov_b32_e32 v123, v2
	v_mov_b32_e32 v124, v2
	v_mov_b32_e32 v125, v2
	v_mov_b32_e32 v126, v2
	v_mov_b32_e32 v127, v2
	v_mov_b32_e32 v128, v2
	v_mov_b32_e32 v129, v2
	s_andn2_b64 vcc, exec, s[0:1]
	s_cbranch_vccnz .LBB0_5215
